# P3 S5 scans: the 16 y stores of each chunk use one base address + immediate offsets, direction by one uniform branch (was 5 SALU + 1 VALU per store)
# speedup vs baseline: 1.0104x; 1.0003x over previous
.LBB0_828:
	s_lshl_b32 s30, s20, 7
	v_or_b32_e32 v118, s30, v153
	s_nop 1
	v_lshlrev_b32_e32 v0, 10, v118
	v_xor_b32_e32 v1, 0x3fc00, v0
	v_cndmask_b32_e64 v0, v1, v0, s[4:5]
	v_lshlrev_b32_e32 v142, 1, v0
	v_lshl_add_u64 v[0:1], v[172:173], 0, v[142:143]
	global_load_dwordx4 v[48:51], v[0:1], off
	v_bitop3_b32 v0, s30, v145, v153 bitop3:0x36
	v_or_b32_e32 v1, 16, v118
	v_cndmask_b32_e64 v0, v0, v1, s[4:5]
	v_lshlrev_b32_e32 v142, 11, v0
	v_lshl_add_u64 v[0:1], v[172:173], 0, v[142:143]
	global_load_dwordx4 v[136:139], v[0:1], off
	v_add_u32_e32 v181, 0xa000, v167
	v_add_u32_e32 v182, 0xa800, v167
	v_add_u32_e32 v183, 0xb000, v167
	v_add_u32_e32 v184, 0xb800, v167
	s_waitcnt vmcnt(1)
	v_mfma_f32_32x32x16_bf16 v[32:47], v[48:51], v[64:67], 0
	s_nop 11
	v_mov_b32_e32 v114, v32
	v_mfma_f32_32x32x16_bf16 v[0:15], v[48:51], v[72:75], 0
	v_mfma_f32_32x32x16_bf16 v[16:31], v[48:51], v[68:71], 0
	s_nop 10
	v_mov_b32_e32 v115, v0
	v_fma_f32 v114, -v170, v112, v114
	v_fma_f32 v115, -v171, v113, v115
	v_mov_b32_e32 v0, v33
	v_fma_f32 v114, v168, v206, v114
	v_fma_f32 v115, v169, v207, v115
	v_mfma_f32_32x32x16_bf16 v[48:63], v[48:51], v[76:79], 0
	v_mov_b32_e32 v116, v16
	v_mov_b32_e32 v16, v34
	v_mov_b32_e32 v32, v18
	v_mov_b32_e32 v18, v36
	v_mov_b32_e32 v34, v20
	v_mov_b32_e32 v20, v38
	v_mov_b32_e32 v36, v22
	s_nop 4
	v_mov_b32_e32 v117, v48
	v_pk_fma_f32 v[116:117], v[170:171], v[206:207], v[116:117]
	v_mov_b32_e32 v48, v17
	v_pk_fma_f32 v[112:113], v[168:169], v[112:113], v[116:117]
	v_pk_fma_f32 v[48:49], v[170:171], v[114:115], v[48:49]
	v_pk_fma_f32 v[0:1], v[170:171], v[112:113], v[0:1] neg_lo:[1,0,0] neg_hi:[1,0,0]
	v_mov_b32_e32 v17, v2
	v_mov_b32_e32 v33, v50
	v_pk_fma_f32 v[0:1], v[168:169], v[114:115], v[0:1]
	v_pk_fma_f32 v[48:49], v[168:169], v[112:113], v[48:49]
	v_pk_fma_f32 v[32:33], v[170:171], v[0:1], v[32:33]
	v_pk_fma_f32 v[16:17], v[170:171], v[48:49], v[16:17] neg_lo:[1,0,0] neg_hi:[1,0,0]
	v_mov_b32_e32 v2, v35
	v_mov_b32_e32 v50, v19
	v_cvt_pk_bf16_f32 v117, v112, v113
	v_cvt_pk_bf16_f32 v112, v0, v1
	v_pk_fma_f32 v[0:1], v[168:169], v[0:1], v[16:17]
	v_pk_fma_f32 v[16:17], v[168:169], v[48:49], v[32:33]
	v_cvt_pk_bf16_f32 v113, v48, v49
	v_pk_fma_f32 v[2:3], v[170:171], v[16:17], v[2:3] neg_lo:[1,0,0] neg_hi:[1,0,0]
	v_pk_fma_f32 v[48:49], v[170:171], v[0:1], v[50:51]
	v_mov_b32_e32 v19, v4
	v_mov_b32_e32 v35, v52
	v_cvt_pk_bf16_f32 v32, v0, v1
	v_pk_fma_f32 v[0:1], v[168:169], v[0:1], v[2:3]
	v_pk_fma_f32 v[2:3], v[168:169], v[16:17], v[48:49]
	v_pk_fma_f32 v[34:35], v[170:171], v[0:1], v[34:35]
	v_pk_fma_f32 v[18:19], v[170:171], v[2:3], v[18:19] neg_lo:[1,0,0] neg_hi:[1,0,0]
	v_mov_b32_e32 v4, v37
	v_mov_b32_e32 v52, v21
	v_cvt_pk_bf16_f32 v33, v16, v17
	v_cvt_pk_bf16_f32 v16, v0, v1
	v_cvt_pk_bf16_f32 v17, v2, v3
	v_pk_fma_f32 v[0:1], v[168:169], v[0:1], v[18:19]
	v_pk_fma_f32 v[2:3], v[168:169], v[2:3], v[34:35]
	v_pk_fma_f32 v[18:19], v[170:171], v[0:1], v[52:53]
	v_pk_fma_f32 v[4:5], v[170:171], v[2:3], v[4:5] neg_lo:[1,0,0] neg_hi:[1,0,0]
	v_mov_b32_e32 v21, v6
	v_mov_b32_e32 v37, v54
	ds_write2_b64 v181, v[32:33], v[16:17] offset0:68 offset1:102
	v_cvt_pk_bf16_f32 v16, v0, v1
	v_cvt_pk_bf16_f32 v17, v2, v3
	v_pk_fma_f32 v[0:1], v[168:169], v[0:1], v[4:5]
	v_pk_fma_f32 v[2:3], v[168:169], v[2:3], v[18:19]
	v_mov_b32_e32 v6, v39
	v_pk_fma_f32 v[18:19], v[170:171], v[2:3], v[20:21] neg_lo:[1,0,0] neg_hi:[1,0,0]
	v_pk_fma_f32 v[20:21], v[170:171], v[0:1], v[36:37]
	v_mov_b32_e32 v54, v23
	v_cvt_pk_bf16_f32 v4, v0, v1
	v_cvt_pk_bf16_f32 v5, v2, v3
	v_pk_fma_f32 v[0:1], v[168:169], v[0:1], v[18:19]
	v_pk_fma_f32 v[2:3], v[168:169], v[2:3], v[20:21]
	ds_write2_b64 v182, v[16:17], v[4:5] offset0:16 offset1:50
	v_pk_fma_f32 v[6:7], v[170:171], v[2:3], v[6:7] neg_lo:[1,0,0] neg_hi:[1,0,0]
	v_pk_fma_f32 v[16:17], v[170:171], v[0:1], v[54:55]
	v_mov_b32_e32 v22, v40
	v_mov_b32_e32 v23, v8
	v_mov_b32_e32 v38, v24
	v_mov_b32_e32 v39, v56
	v_cvt_pk_bf16_f32 v4, v0, v1
	v_cvt_pk_bf16_f32 v5, v2, v3
	v_pk_fma_f32 v[0:1], v[168:169], v[0:1], v[6:7]
	v_pk_fma_f32 v[2:3], v[168:169], v[2:3], v[16:17]
	v_pk_fma_f32 v[18:19], v[170:171], v[0:1], v[38:39]
	v_pk_fma_f32 v[16:17], v[170:171], v[2:3], v[22:23] neg_lo:[1,0,0] neg_hi:[1,0,0]
	v_mov_b32_e32 v8, v41
	v_mov_b32_e32 v56, v25
	v_cvt_pk_bf16_f32 v6, v0, v1
	v_cvt_pk_bf16_f32 v7, v2, v3
	v_pk_fma_f32 v[0:1], v[168:169], v[0:1], v[16:17]
	v_pk_fma_f32 v[2:3], v[168:169], v[2:3], v[18:19]
	ds_write2_b64 v182, v[4:5], v[6:7] offset0:84 offset1:118
	v_pk_fma_f32 v[6:7], v[170:171], v[2:3], v[8:9] neg_lo:[1,0,0] neg_hi:[1,0,0]
	v_pk_fma_f32 v[8:9], v[170:171], v[0:1], v[56:57]
	v_mov_b32_e32 v24, v42
	v_mov_b32_e32 v25, v10
	v_cvt_pk_bf16_f32 v4, v0, v1
	v_cvt_pk_bf16_f32 v5, v2, v3
	v_pk_fma_f32 v[0:1], v[168:169], v[0:1], v[6:7]
	v_pk_fma_f32 v[2:3], v[168:169], v[2:3], v[8:9]
	v_mov_b32_e32 v40, v26
	v_mov_b32_e32 v41, v58
	v_cvt_pk_bf16_f32 v6, v0, v1
	v_cvt_pk_bf16_f32 v7, v2, v3
	v_pk_fma_f32 v[8:9], v[170:171], v[2:3], v[24:25] neg_lo:[1,0,0] neg_hi:[1,0,0]
	ds_write2_b64 v183, v[4:5], v[6:7] offset0:32 offset1:66
	v_pk_fma_f32 v[4:5], v[168:169], v[0:1], v[8:9]
	v_pk_fma_f32 v[0:1], v[170:171], v[0:1], v[40:41]
	v_mov_b32_e32 v10, v43
	v_pk_fma_f32 v[0:1], v[168:169], v[2:3], v[0:1]
	v_mov_b32_e32 v58, v27
	v_pk_fma_f32 v[6:7], v[170:171], v[0:1], v[10:11] neg_lo:[1,0,0] neg_hi:[1,0,0]
	v_cvt_pk_bf16_f32 v2, v4, v5
	v_pk_fma_f32 v[6:7], v[168:169], v[4:5], v[6:7]
	v_pk_fma_f32 v[4:5], v[170:171], v[4:5], v[58:59]
	v_cvt_pk_bf16_f32 v3, v0, v1
	v_pk_fma_f32 v[0:1], v[168:169], v[0:1], v[4:5]
	v_cvt_pk_bf16_f32 v4, v6, v7
	v_cvt_pk_bf16_f32 v5, v0, v1
	ds_write2_b64 v183, v[2:3], v[4:5] offset0:100 offset1:134
	v_mov_b32_e32 v4, v28
	v_mov_b32_e32 v5, v60
	v_mov_b32_e32 v2, v44
	v_mov_b32_e32 v3, v12
	v_pk_fma_f32 v[4:5], v[170:171], v[6:7], v[4:5]
	v_pk_fma_f32 v[2:3], v[170:171], v[0:1], v[2:3] neg_lo:[1,0,0] neg_hi:[1,0,0]
	v_pk_fma_f32 v[0:1], v[168:169], v[0:1], v[4:5]
	v_mov_b32_e32 v12, v45
	v_pk_fma_f32 v[2:3], v[168:169], v[6:7], v[2:3]
	v_mov_b32_e32 v60, v29
	v_pk_fma_f32 v[6:7], v[170:171], v[0:1], v[12:13] neg_lo:[1,0,0] neg_hi:[1,0,0]
	v_cvt_pk_bf16_f32 v4, v2, v3
	v_pk_fma_f32 v[6:7], v[168:169], v[2:3], v[6:7]
	v_pk_fma_f32 v[2:3], v[170:171], v[2:3], v[60:61]
	v_cvt_pk_bf16_f32 v5, v0, v1
	v_pk_fma_f32 v[0:1], v[168:169], v[0:1], v[2:3]
	v_cvt_pk_bf16_f32 v2, v6, v7
	v_cvt_pk_bf16_f32 v3, v0, v1
	ds_write2_b64 v184, v[4:5], v[2:3] offset0:48 offset1:82
	v_mov_b32_e32 v4, v30
	v_mov_b32_e32 v5, v62
	v_mov_b32_e32 v2, v46
	v_mov_b32_e32 v3, v14
	v_pk_fma_f32 v[4:5], v[170:171], v[6:7], v[4:5]
	v_pk_fma_f32 v[2:3], v[170:171], v[0:1], v[2:3] neg_lo:[1,0,0] neg_hi:[1,0,0]
	v_pk_fma_f32 v[0:1], v[168:169], v[0:1], v[4:5]
	v_mov_b32_e32 v14, v47
	v_pk_fma_f32 v[2:3], v[168:169], v[6:7], v[2:3]
	v_mov_b32_e32 v62, v31
	v_pk_fma_f32 v[6:7], v[170:171], v[0:1], v[14:15] neg_lo:[1,0,0] neg_hi:[1,0,0]
	v_cvt_pk_bf16_f32 v4, v2, v3
	v_pk_fma_f32 v[176:177], v[168:169], v[2:3], v[6:7]
	v_pk_fma_f32 v[2:3], v[170:171], v[2:3], v[62:63]
	v_cvt_pk_bf16_f32 v116, v114, v115
	v_pk_fma_f32 v[178:179], v[168:169], v[0:1], v[2:3]
	v_cvt_pk_bf16_f32 v5, v0, v1
	v_cvt_pk_bf16_f32 v0, v176, v177
	v_cvt_pk_bf16_f32 v1, v178, v179
	ds_write2_b64 v181, v[116:117], v[112:113] offset1:34
	ds_write2_b64 v184, v[4:5], v[0:1] offset0:116 offset1:150
	ds_read_b128 v[0:3], v180 offset:40960
	ds_read_b128 v[16:19], v180 offset:40992
	s_waitcnt lgkmcnt(1)
	v_mfma_f32_32x32x16_bf16 v[0:15], v[0:3], v[88:91], 0
	v_or_b32_e32 v20, 32, v118
	v_bitop3_b32 v21, s30, v222, v153 bitop3:0x36
	v_cndmask_b32_e64 v20, v21, v20, s[4:5]
	v_lshlrev_b32_e32 v142, 11, v20
	ds_read_b128 v[20:23], v180 offset:41024
	v_lshl_add_u64 v[24:25], v[172:173], 0, v[142:143]
	s_waitcnt lgkmcnt(1)
	v_mfma_f32_32x32x16_bf16 v[0:15], v[16:19], v[92:95], v[0:15]
	v_or_b32_e32 v16, 48, v118
	v_bitop3_b32 v17, s30, v223, v153 bitop3:0x36
	v_cndmask_b32_e64 v16, v17, v16, s[4:5]
	v_lshlrev_b32_e32 v142, 11, v16
	ds_read_b128 v[16:19], v180 offset:41056
	v_lshl_add_u64 v[26:27], v[172:173], 0, v[142:143]
	global_load_dwordx4 v[132:135], v[24:25], off
	global_load_dwordx4 v[128:131], v[26:27], off
	s_waitcnt lgkmcnt(1)
	v_mfma_f32_32x32x16_bf16 v[0:15], v[20:23], v[96:99], v[0:15]
	v_or_b32_e32 v20, 64, v118
	v_bitop3_b32 v21, s30, v224, v153 bitop3:0x36
	v_cndmask_b32_e64 v20, v21, v20, s[4:5]
	v_lshlrev_b32_e32 v142, 11, v20
	ds_read_b128 v[20:23], v180 offset:41088
	v_lshl_add_u64 v[24:25], v[172:173], 0, v[142:143]
	s_waitcnt lgkmcnt(1)
	v_mfma_f32_32x32x16_bf16 v[0:15], v[16:19], v[80:83], v[0:15]
	v_or_b32_e32 v16, 0x50, v118
	v_bitop3_b32 v17, s30, v225, v153 bitop3:0x36
	v_cndmask_b32_e64 v16, v17, v16, s[4:5]
	v_lshlrev_b32_e32 v142, 11, v16
	ds_read_b128 v[16:19], v180 offset:41120
	v_lshl_add_u64 v[26:27], v[172:173], 0, v[142:143]
	global_load_dwordx4 v[124:127], v[24:25], off
	global_load_dwordx4 v[120:123], v[26:27], off
	s_waitcnt lgkmcnt(1)
	v_mfma_f32_32x32x16_bf16 v[0:15], v[20:23], v[100:103], v[0:15]
	v_or_b32_e32 v20, 0x60, v118
	v_bitop3_b32 v21, s30, v226, v153 bitop3:0x36
	v_cndmask_b32_e64 v20, v21, v20, s[4:5]
	v_lshlrev_b32_e32 v142, 11, v20
	v_lshl_add_u64 v[24:25], v[172:173], 0, v[142:143]
	ds_read_b128 v[20:23], v180 offset:41152
	s_waitcnt lgkmcnt(1)
	v_mfma_f32_32x32x16_bf16 v[0:15], v[16:19], v[104:107], v[0:15]
	v_or_b32_e32 v16, 0x70, v118
	v_bitop3_b32 v17, s30, v227, v153 bitop3:0x36
	v_cndmask_b32_e64 v16, v17, v16, s[4:5]
	v_lshlrev_b32_e32 v142, 11, v16
	v_lshl_add_u64 v[26:27], v[172:173], 0, v[142:143]
	ds_read_b128 v[16:19], v180 offset:41184
	global_load_dwordx4 v[116:119], v[24:25], off
	global_load_dwordx4 v[112:115], v[26:27], off
	s_waitcnt lgkmcnt(1)
	v_mfma_f32_32x32x16_bf16 v[0:15], v[20:23], v[108:111], v[0:15]
	s_waitcnt lgkmcnt(0)
	v_mfma_f32_32x32x16_bf16 v[0:15], v[16:19], v[84:87], v[0:15]
	s_and_saveexec_b64 s[26:27], s[0:1]
	s_cbranch_execz .LBB0_830
	s_mov_b32 s20, s30
	s_xor_b32 s31, s30, 0xff
	s_lshl_b32 s20, s20, 4
	s_lshl_b32 s31, s31, 4
	s_and_b64 s[34:35], s[4:5], exec
	s_cselect_b32 s20, s20, s31
	v_lshl_add_u64 v[16:17], s[20:21], 2, v[174:175]
	s_cbranch_scc0 .Lys0_b
	s_nop 3
	global_store_dword v[16:17], v0, off
	global_store_dword v[16:17], v1, off offset:64
	global_store_dword v[16:17], v2, off offset:128
	global_store_dword v[16:17], v3, off offset:192
	global_store_dword v[16:17], v4, off offset:256
	global_store_dword v[16:17], v5, off offset:320
	global_store_dword v[16:17], v6, off offset:384
	global_store_dword v[16:17], v7, off offset:448
	global_store_dword v[16:17], v8, off offset:512
	global_store_dword v[16:17], v9, off offset:576
	global_store_dword v[16:17], v10, off offset:640
	global_store_dword v[16:17], v11, off offset:704
	global_store_dword v[16:17], v12, off offset:768
	global_store_dword v[16:17], v13, off offset:832
	global_store_dword v[16:17], v14, off offset:896
	global_store_dword v[16:17], v15, off offset:960
	s_branch .Lys0_e
.Lys0_b:
	s_nop 3
	global_store_dword v[16:17], v0, off
	global_store_dword v[16:17], v1, off offset:-64
	global_store_dword v[16:17], v2, off offset:-128
	global_store_dword v[16:17], v3, off offset:-192
	global_store_dword v[16:17], v4, off offset:-256
	global_store_dword v[16:17], v5, off offset:-320
	global_store_dword v[16:17], v6, off offset:-384
	global_store_dword v[16:17], v7, off offset:-448
	global_store_dword v[16:17], v8, off offset:-512
	global_store_dword v[16:17], v9, off offset:-576
	global_store_dword v[16:17], v10, off offset:-640
	global_store_dword v[16:17], v11, off offset:-704
	global_store_dword v[16:17], v12, off offset:-768
	global_store_dword v[16:17], v13, off offset:-832
	global_store_dword v[16:17], v14, off offset:-896
	global_store_dword v[16:17], v15, off offset:-960
.Lys0_e:
.LBB0_830:
	s_or_b64 exec, exec, s[26:27]
	s_waitcnt vmcnt(6)
	v_mfma_f32_32x32x16_bf16 v[32:47], v[136:139], v[64:67], 0
	v_mfma_f32_32x32x16_bf16 v[0:15], v[136:139], v[72:75], 0
	s_nop 10
	v_mov_b32_e32 v186, v32
	v_mfma_f32_32x32x16_bf16 v[16:31], v[136:139], v[68:71], 0
	v_mov_b32_e32 v187, v0
	v_mov_b32_e32 v0, v33
	v_mfma_f32_32x32x16_bf16 v[48:63], v[136:139], v[76:79], 0
	s_nop 8
	v_mov_b32_e32 v188, v16
	v_fma_f32 v136, -v170, v178, v186
	v_fma_f32 v137, -v171, v179, v187
	v_fma_f32 v136, v168, v176, v136
	v_fma_f32 v137, v169, v177, v137
	v_mov_b32_e32 v189, v48
	v_pk_fma_f32 v[138:139], v[170:171], v[176:177], v[188:189]
	v_mov_b32_e32 v48, v17
	v_pk_fma_f32 v[138:139], v[168:169], v[178:179], v[138:139]
	v_pk_fma_f32 v[16:17], v[170:171], v[136:137], v[48:49]
	v_pk_fma_f32 v[0:1], v[170:171], v[138:139], v[0:1] neg_lo:[1,0,0] neg_hi:[1,0,0]
	v_pk_fma_f32 v[16:17], v[168:169], v[138:139], v[16:17]
	v_pk_fma_f32 v[0:1], v[168:169], v[136:137], v[0:1]
	v_cvt_pk_bf16_f32 v176, v136, v137
	v_cvt_pk_bf16_f32 v177, v138, v139
	v_cvt_pk_bf16_f32 v32, v0, v1
	v_cvt_pk_bf16_f32 v33, v16, v17
	ds_write2_b64 v181, v[176:177], v[32:33] offset1:34
	v_mov_b32_e32 v32, v34
	v_mov_b32_e32 v33, v2
	v_mov_b32_e32 v48, v18
	v_mov_b32_e32 v49, v50
	v_pk_fma_f32 v[32:33], v[170:171], v[16:17], v[32:33] neg_lo:[1,0,0] neg_hi:[1,0,0]
	v_mov_b32_e32 v2, v35
	v_pk_fma_f32 v[32:33], v[168:169], v[0:1], v[32:33]
	v_pk_fma_f32 v[0:1], v[170:171], v[0:1], v[48:49]
	v_mov_b32_e32 v50, v19
	v_pk_fma_f32 v[0:1], v[168:169], v[16:17], v[0:1]
	v_pk_fma_f32 v[18:19], v[170:171], v[32:33], v[50:51]
	v_pk_fma_f32 v[2:3], v[170:171], v[0:1], v[2:3] neg_lo:[1,0,0] neg_hi:[1,0,0]
	v_cvt_pk_bf16_f32 v17, v0, v1
	v_pk_fma_f32 v[2:3], v[168:169], v[32:33], v[2:3]
	v_pk_fma_f32 v[0:1], v[168:169], v[0:1], v[18:19]
	v_cvt_pk_bf16_f32 v16, v32, v33
	v_cvt_pk_bf16_f32 v18, v2, v3
	v_cvt_pk_bf16_f32 v19, v0, v1
	ds_write2_b64 v181, v[16:17], v[18:19] offset0:68 offset1:102
	v_mov_b32_e32 v16, v36
	v_mov_b32_e32 v17, v4
	v_mov_b32_e32 v18, v20
	v_mov_b32_e32 v19, v52
	v_pk_fma_f32 v[16:17], v[170:171], v[0:1], v[16:17] neg_lo:[1,0,0] neg_hi:[1,0,0]
	v_mov_b32_e32 v4, v37
	v_pk_fma_f32 v[16:17], v[168:169], v[2:3], v[16:17]
	v_pk_fma_f32 v[2:3], v[170:171], v[2:3], v[18:19]
	v_mov_b32_e32 v52, v21
	v_pk_fma_f32 v[0:1], v[168:169], v[0:1], v[2:3]
	v_cvt_pk_bf16_f32 v2, v16, v17
	v_pk_fma_f32 v[4:5], v[170:171], v[0:1], v[4:5] neg_lo:[1,0,0] neg_hi:[1,0,0]
	v_cvt_pk_bf16_f32 v3, v0, v1
	v_pk_fma_f32 v[4:5], v[168:169], v[16:17], v[4:5]
	v_pk_fma_f32 v[16:17], v[170:171], v[16:17], v[52:53]
	s_nop 0
	v_pk_fma_f32 v[0:1], v[168:169], v[0:1], v[16:17]
	v_cvt_pk_bf16_f32 v16, v4, v5
	v_cvt_pk_bf16_f32 v17, v0, v1
	ds_write2_b64 v182, v[2:3], v[16:17] offset0:16 offset1:50
	v_mov_b32_e32 v2, v38
	v_mov_b32_e32 v3, v6
	v_mov_b32_e32 v16, v22
	v_mov_b32_e32 v17, v54
	v_pk_fma_f32 v[2:3], v[170:171], v[0:1], v[2:3] neg_lo:[1,0,0] neg_hi:[1,0,0]
	v_mov_b32_e32 v6, v39
	v_pk_fma_f32 v[2:3], v[168:169], v[4:5], v[2:3]
	v_pk_fma_f32 v[4:5], v[170:171], v[4:5], v[16:17]
	v_mov_b32_e32 v54, v23
	v_pk_fma_f32 v[0:1], v[168:169], v[0:1], v[4:5]
	v_cvt_pk_bf16_f32 v4, v2, v3
	v_pk_fma_f32 v[6:7], v[170:171], v[0:1], v[6:7] neg_lo:[1,0,0] neg_hi:[1,0,0]
	v_cvt_pk_bf16_f32 v5, v0, v1
	v_pk_fma_f32 v[6:7], v[168:169], v[2:3], v[6:7]
	v_pk_fma_f32 v[2:3], v[170:171], v[2:3], v[54:55]
	s_nop 0
	v_pk_fma_f32 v[0:1], v[168:169], v[0:1], v[2:3]
	v_cvt_pk_bf16_f32 v2, v6, v7
	v_cvt_pk_bf16_f32 v3, v0, v1
	ds_write2_b64 v182, v[4:5], v[2:3] offset0:84 offset1:118
	v_mov_b32_e32 v4, v24
	v_mov_b32_e32 v5, v56
	v_mov_b32_e32 v2, v40
	v_mov_b32_e32 v3, v8
	v_pk_fma_f32 v[4:5], v[170:171], v[6:7], v[4:5]
	v_pk_fma_f32 v[2:3], v[170:171], v[0:1], v[2:3] neg_lo:[1,0,0] neg_hi:[1,0,0]
	v_pk_fma_f32 v[0:1], v[168:169], v[0:1], v[4:5]
	v_mov_b32_e32 v8, v41
	v_pk_fma_f32 v[2:3], v[168:169], v[6:7], v[2:3]
	v_mov_b32_e32 v56, v25
	v_pk_fma_f32 v[6:7], v[170:171], v[0:1], v[8:9] neg_lo:[1,0,0] neg_hi:[1,0,0]
	v_cvt_pk_bf16_f32 v4, v2, v3
	v_pk_fma_f32 v[6:7], v[168:169], v[2:3], v[6:7]
	v_pk_fma_f32 v[2:3], v[170:171], v[2:3], v[56:57]
	v_cvt_pk_bf16_f32 v5, v0, v1
	v_pk_fma_f32 v[0:1], v[168:169], v[0:1], v[2:3]
	v_cvt_pk_bf16_f32 v2, v6, v7
	v_cvt_pk_bf16_f32 v3, v0, v1
	ds_write2_b64 v183, v[4:5], v[2:3] offset0:32 offset1:66
	v_mov_b32_e32 v4, v26
	v_mov_b32_e32 v5, v58
	v_mov_b32_e32 v2, v42
	v_mov_b32_e32 v3, v10
	v_pk_fma_f32 v[4:5], v[170:171], v[6:7], v[4:5]
	v_pk_fma_f32 v[2:3], v[170:171], v[0:1], v[2:3] neg_lo:[1,0,0] neg_hi:[1,0,0]
	v_pk_fma_f32 v[0:1], v[168:169], v[0:1], v[4:5]
	v_mov_b32_e32 v10, v43
	v_pk_fma_f32 v[2:3], v[168:169], v[6:7], v[2:3]
	v_mov_b32_e32 v58, v27
	v_pk_fma_f32 v[6:7], v[170:171], v[0:1], v[10:11] neg_lo:[1,0,0] neg_hi:[1,0,0]
	v_cvt_pk_bf16_f32 v4, v2, v3
	v_pk_fma_f32 v[6:7], v[168:169], v[2:3], v[6:7]
	v_pk_fma_f32 v[2:3], v[170:171], v[2:3], v[58:59]
	v_cvt_pk_bf16_f32 v5, v0, v1
	v_pk_fma_f32 v[0:1], v[168:169], v[0:1], v[2:3]
	v_cvt_pk_bf16_f32 v2, v6, v7
	v_cvt_pk_bf16_f32 v3, v0, v1
	ds_write2_b64 v183, v[4:5], v[2:3] offset0:100 offset1:134
	v_mov_b32_e32 v4, v28
	v_mov_b32_e32 v5, v60
	v_mov_b32_e32 v2, v44
	v_mov_b32_e32 v3, v12
	v_pk_fma_f32 v[4:5], v[170:171], v[6:7], v[4:5]
	v_pk_fma_f32 v[2:3], v[170:171], v[0:1], v[2:3] neg_lo:[1,0,0] neg_hi:[1,0,0]
	v_pk_fma_f32 v[0:1], v[168:169], v[0:1], v[4:5]
	v_mov_b32_e32 v12, v45
	v_pk_fma_f32 v[2:3], v[168:169], v[6:7], v[2:3]
	v_mov_b32_e32 v60, v29
	v_pk_fma_f32 v[6:7], v[170:171], v[0:1], v[12:13] neg_lo:[1,0,0] neg_hi:[1,0,0]
	v_cvt_pk_bf16_f32 v4, v2, v3
	v_pk_fma_f32 v[6:7], v[168:169], v[2:3], v[6:7]
	v_pk_fma_f32 v[2:3], v[170:171], v[2:3], v[60:61]
	v_cvt_pk_bf16_f32 v5, v0, v1
	v_pk_fma_f32 v[0:1], v[168:169], v[0:1], v[2:3]
	v_cvt_pk_bf16_f32 v2, v6, v7
	v_cvt_pk_bf16_f32 v3, v0, v1
	ds_write2_b64 v184, v[4:5], v[2:3] offset0:48 offset1:82
	v_mov_b32_e32 v4, v30
	v_mov_b32_e32 v5, v62
	v_mov_b32_e32 v2, v46
	v_mov_b32_e32 v3, v14
	v_pk_fma_f32 v[4:5], v[170:171], v[6:7], v[4:5]
	v_pk_fma_f32 v[2:3], v[170:171], v[0:1], v[2:3] neg_lo:[1,0,0] neg_hi:[1,0,0]
	v_pk_fma_f32 v[0:1], v[168:169], v[0:1], v[4:5]
	v_mov_b32_e32 v14, v47
	v_pk_fma_f32 v[2:3], v[168:169], v[6:7], v[2:3]
	v_mov_b32_e32 v62, v31
	v_pk_fma_f32 v[6:7], v[170:171], v[0:1], v[14:15] neg_lo:[1,0,0] neg_hi:[1,0,0]
	v_cvt_pk_bf16_f32 v4, v2, v3
	v_pk_fma_f32 v[136:137], v[168:169], v[2:3], v[6:7]
	v_pk_fma_f32 v[2:3], v[170:171], v[2:3], v[62:63]
	v_cvt_pk_bf16_f32 v5, v0, v1
	v_pk_fma_f32 v[138:139], v[168:169], v[0:1], v[2:3]
	v_cvt_pk_bf16_f32 v0, v136, v137
	v_cvt_pk_bf16_f32 v1, v138, v139
	ds_write2_b64 v184, v[4:5], v[0:1] offset0:116 offset1:150
	ds_read_b128 v[0:3], v180 offset:40960
	ds_read_b128 v[16:19], v180 offset:40992
	s_waitcnt lgkmcnt(1)
	v_mfma_f32_32x32x16_bf16 v[0:15], v[0:3], v[88:91], 0
	s_waitcnt lgkmcnt(0)
	v_mfma_f32_32x32x16_bf16 v[0:15], v[16:19], v[92:95], v[0:15]
	ds_read_b128 v[16:19], v180 offset:41024
	ds_read_b128 v[20:23], v180 offset:41056
	s_waitcnt lgkmcnt(1)
	v_mfma_f32_32x32x16_bf16 v[0:15], v[16:19], v[96:99], v[0:15]
	s_waitcnt lgkmcnt(0)
	v_mfma_f32_32x32x16_bf16 v[0:15], v[20:23], v[80:83], v[0:15]
	ds_read_b128 v[16:19], v180 offset:41088
	ds_read_b128 v[20:23], v180 offset:41120
	s_waitcnt lgkmcnt(1)
	v_mfma_f32_32x32x16_bf16 v[0:15], v[16:19], v[100:103], v[0:15]
	s_waitcnt lgkmcnt(0)
	v_mfma_f32_32x32x16_bf16 v[0:15], v[20:23], v[104:107], v[0:15]
	ds_read_b128 v[16:19], v180 offset:41152
	ds_read_b128 v[20:23], v180 offset:41184
	s_waitcnt lgkmcnt(1)
	v_mfma_f32_32x32x16_bf16 v[0:15], v[16:19], v[108:111], v[0:15]
	s_waitcnt lgkmcnt(0)
	v_mfma_f32_32x32x16_bf16 v[0:15], v[20:23], v[84:87], v[0:15]
	s_and_saveexec_b64 s[26:27], s[0:1]
	s_cbranch_execz .LBB0_832
	s_or_b32 s20, s30, 0x10
	s_xor_b32 s31, s30, 0xef
	s_lshl_b32 s20, s20, 4
	s_lshl_b32 s31, s31, 4
	s_and_b64 s[34:35], s[4:5], exec
	s_cselect_b32 s20, s20, s31
	v_lshl_add_u64 v[16:17], s[20:21], 2, v[174:175]
	s_cbranch_scc0 .Lys1_b
	s_nop 3
	global_store_dword v[16:17], v0, off
	global_store_dword v[16:17], v1, off offset:64
	global_store_dword v[16:17], v2, off offset:128
	global_store_dword v[16:17], v3, off offset:192
	global_store_dword v[16:17], v4, off offset:256
	global_store_dword v[16:17], v5, off offset:320
	global_store_dword v[16:17], v6, off offset:384
	global_store_dword v[16:17], v7, off offset:448
	global_store_dword v[16:17], v8, off offset:512
	global_store_dword v[16:17], v9, off offset:576
	global_store_dword v[16:17], v10, off offset:640
	global_store_dword v[16:17], v11, off offset:704
	global_store_dword v[16:17], v12, off offset:768
	global_store_dword v[16:17], v13, off offset:832
	global_store_dword v[16:17], v14, off offset:896
	global_store_dword v[16:17], v15, off offset:960
	s_branch .Lys1_e

.Lys1_e:
.LBB0_832:
	s_or_b64 exec, exec, s[26:27]
	s_waitcnt vmcnt(5)
	v_mfma_f32_32x32x16_bf16 v[32:47], v[132:135], v[64:67], 0
	v_mfma_f32_32x32x16_bf16 v[0:15], v[132:135], v[72:75], 0
	s_nop 10
	v_mov_b32_e32 v176, v32
	v_mfma_f32_32x32x16_bf16 v[16:31], v[132:135], v[68:71], 0
	v_mov_b32_e32 v177, v0
	v_mov_b32_e32 v0, v33
	v_mfma_f32_32x32x16_bf16 v[48:63], v[132:135], v[76:79], 0
	s_nop 8
	v_mov_b32_e32 v178, v16
	v_fma_f32 v132, -v170, v138, v176
	v_fma_f32 v133, -v171, v139, v177
	v_fma_f32 v132, v168, v136, v132
	v_fma_f32 v133, v169, v137, v133
	v_mov_b32_e32 v179, v48
	v_pk_fma_f32 v[134:135], v[170:171], v[136:137], v[178:179]
	v_mov_b32_e32 v48, v17
	v_pk_fma_f32 v[134:135], v[168:169], v[138:139], v[134:135]
	v_pk_fma_f32 v[16:17], v[170:171], v[132:133], v[48:49]
	v_pk_fma_f32 v[0:1], v[170:171], v[134:135], v[0:1] neg_lo:[1,0,0] neg_hi:[1,0,0]
	v_pk_fma_f32 v[16:17], v[168:169], v[134:135], v[16:17]
	v_pk_fma_f32 v[0:1], v[168:169], v[132:133], v[0:1]
	v_cvt_pk_bf16_f32 v136, v132, v133
	v_cvt_pk_bf16_f32 v137, v134, v135
	v_cvt_pk_bf16_f32 v32, v0, v1
	v_cvt_pk_bf16_f32 v33, v16, v17
	ds_write2_b64 v181, v[136:137], v[32:33] offset1:34
	v_mov_b32_e32 v32, v34
	v_mov_b32_e32 v33, v2
	v_mov_b32_e32 v48, v18
	v_mov_b32_e32 v49, v50
	v_pk_fma_f32 v[32:33], v[170:171], v[16:17], v[32:33] neg_lo:[1,0,0] neg_hi:[1,0,0]
	v_mov_b32_e32 v2, v35
	v_pk_fma_f32 v[32:33], v[168:169], v[0:1], v[32:33]
	v_pk_fma_f32 v[0:1], v[170:171], v[0:1], v[48:49]
	v_mov_b32_e32 v50, v19
	v_pk_fma_f32 v[0:1], v[168:169], v[16:17], v[0:1]
	v_pk_fma_f32 v[18:19], v[170:171], v[32:33], v[50:51]
	v_pk_fma_f32 v[2:3], v[170:171], v[0:1], v[2:3] neg_lo:[1,0,0] neg_hi:[1,0,0]
	v_cvt_pk_bf16_f32 v17, v0, v1
	v_pk_fma_f32 v[2:3], v[168:169], v[32:33], v[2:3]
	v_pk_fma_f32 v[0:1], v[168:169], v[0:1], v[18:19]
	v_cvt_pk_bf16_f32 v16, v32, v33
	v_cvt_pk_bf16_f32 v18, v2, v3
	v_cvt_pk_bf16_f32 v19, v0, v1
	ds_write2_b64 v181, v[16:17], v[18:19] offset0:68 offset1:102
	v_mov_b32_e32 v16, v36
	v_mov_b32_e32 v17, v4
	v_mov_b32_e32 v18, v20
	v_mov_b32_e32 v19, v52
	v_pk_fma_f32 v[16:17], v[170:171], v[0:1], v[16:17] neg_lo:[1,0,0] neg_hi:[1,0,0]
	v_mov_b32_e32 v4, v37
	v_pk_fma_f32 v[16:17], v[168:169], v[2:3], v[16:17]
	v_pk_fma_f32 v[2:3], v[170:171], v[2:3], v[18:19]
	v_mov_b32_e32 v52, v21
	v_pk_fma_f32 v[0:1], v[168:169], v[0:1], v[2:3]
	v_cvt_pk_bf16_f32 v2, v16, v17
	v_pk_fma_f32 v[4:5], v[170:171], v[0:1], v[4:5] neg_lo:[1,0,0] neg_hi:[1,0,0]
	v_cvt_pk_bf16_f32 v3, v0, v1
	v_pk_fma_f32 v[4:5], v[168:169], v[16:17], v[4:5]
	v_pk_fma_f32 v[16:17], v[170:171], v[16:17], v[52:53]
	s_nop 0
	v_pk_fma_f32 v[0:1], v[168:169], v[0:1], v[16:17]
	v_cvt_pk_bf16_f32 v16, v4, v5
	v_cvt_pk_bf16_f32 v17, v0, v1
	ds_write2_b64 v182, v[2:3], v[16:17] offset0:16 offset1:50
	v_mov_b32_e32 v2, v38
	v_mov_b32_e32 v3, v6
	v_mov_b32_e32 v16, v22
	v_mov_b32_e32 v17, v54
	v_pk_fma_f32 v[2:3], v[170:171], v[0:1], v[2:3] neg_lo:[1,0,0] neg_hi:[1,0,0]
	v_mov_b32_e32 v6, v39
	v_pk_fma_f32 v[2:3], v[168:169], v[4:5], v[2:3]
	v_pk_fma_f32 v[4:5], v[170:171], v[4:5], v[16:17]
	v_mov_b32_e32 v54, v23
	v_pk_fma_f32 v[0:1], v[168:169], v[0:1], v[4:5]
	v_cvt_pk_bf16_f32 v4, v2, v3
	v_pk_fma_f32 v[6:7], v[170:171], v[0:1], v[6:7] neg_lo:[1,0,0] neg_hi:[1,0,0]
	v_cvt_pk_bf16_f32 v5, v0, v1
	v_pk_fma_f32 v[6:7], v[168:169], v[2:3], v[6:7]
	v_pk_fma_f32 v[2:3], v[170:171], v[2:3], v[54:55]
	s_nop 0
	v_pk_fma_f32 v[0:1], v[168:169], v[0:1], v[2:3]
	v_cvt_pk_bf16_f32 v2, v6, v7
	v_cvt_pk_bf16_f32 v3, v0, v1
	ds_write2_b64 v182, v[4:5], v[2:3] offset0:84 offset1:118
	v_mov_b32_e32 v4, v24
	v_mov_b32_e32 v5, v56
	v_mov_b32_e32 v2, v40
	v_mov_b32_e32 v3, v8
	v_pk_fma_f32 v[4:5], v[170:171], v[6:7], v[4:5]
	v_pk_fma_f32 v[2:3], v[170:171], v[0:1], v[2:3] neg_lo:[1,0,0] neg_hi:[1,0,0]
	v_pk_fma_f32 v[0:1], v[168:169], v[0:1], v[4:5]
	v_mov_b32_e32 v8, v41
	v_pk_fma_f32 v[2:3], v[168:169], v[6:7], v[2:3]
	v_mov_b32_e32 v56, v25
	v_pk_fma_f32 v[6:7], v[170:171], v[0:1], v[8:9] neg_lo:[1,0,0] neg_hi:[1,0,0]
	v_cvt_pk_bf16_f32 v4, v2, v3
	v_pk_fma_f32 v[6:7], v[168:169], v[2:3], v[6:7]
	v_pk_fma_f32 v[2:3], v[170:171], v[2:3], v[56:57]
	v_cvt_pk_bf16_f32 v5, v0, v1
	v_pk_fma_f32 v[0:1], v[168:169], v[0:1], v[2:3]
	v_cvt_pk_bf16_f32 v2, v6, v7
	v_cvt_pk_bf16_f32 v3, v0, v1
	ds_write2_b64 v183, v[4:5], v[2:3] offset0:32 offset1:66
	v_mov_b32_e32 v4, v26
	v_mov_b32_e32 v5, v58
	v_mov_b32_e32 v2, v42
	v_mov_b32_e32 v3, v10
	v_pk_fma_f32 v[4:5], v[170:171], v[6:7], v[4:5]
	v_pk_fma_f32 v[2:3], v[170:171], v[0:1], v[2:3] neg_lo:[1,0,0] neg_hi:[1,0,0]
	v_pk_fma_f32 v[0:1], v[168:169], v[0:1], v[4:5]
	v_mov_b32_e32 v10, v43
	v_pk_fma_f32 v[2:3], v[168:169], v[6:7], v[2:3]
	v_mov_b32_e32 v58, v27
	v_pk_fma_f32 v[6:7], v[170:171], v[0:1], v[10:11] neg_lo:[1,0,0] neg_hi:[1,0,0]
	v_cvt_pk_bf16_f32 v4, v2, v3
	v_pk_fma_f32 v[6:7], v[168:169], v[2:3], v[6:7]
	v_pk_fma_f32 v[2:3], v[170:171], v[2:3], v[58:59]
	v_cvt_pk_bf16_f32 v5, v0, v1
	v_pk_fma_f32 v[0:1], v[168:169], v[0:1], v[2:3]
	v_cvt_pk_bf16_f32 v2, v6, v7
	v_cvt_pk_bf16_f32 v3, v0, v1
	ds_write2_b64 v183, v[4:5], v[2:3] offset0:100 offset1:134
	v_mov_b32_e32 v4, v28
	v_mov_b32_e32 v5, v60
	v_mov_b32_e32 v2, v44
	v_mov_b32_e32 v3, v12
	v_pk_fma_f32 v[4:5], v[170:171], v[6:7], v[4:5]
	v_pk_fma_f32 v[2:3], v[170:171], v[0:1], v[2:3] neg_lo:[1,0,0] neg_hi:[1,0,0]
	v_pk_fma_f32 v[0:1], v[168:169], v[0:1], v[4:5]
	v_mov_b32_e32 v12, v45
	v_pk_fma_f32 v[2:3], v[168:169], v[6:7], v[2:3]
	v_mov_b32_e32 v60, v29
	v_pk_fma_f32 v[6:7], v[170:171], v[0:1], v[12:13] neg_lo:[1,0,0] neg_hi:[1,0,0]
	v_cvt_pk_bf16_f32 v4, v2, v3
	v_pk_fma_f32 v[6:7], v[168:169], v[2:3], v[6:7]
	v_pk_fma_f32 v[2:3], v[170:171], v[2:3], v[60:61]
	v_cvt_pk_bf16_f32 v5, v0, v1
	v_pk_fma_f32 v[0:1], v[168:169], v[0:1], v[2:3]
	v_cvt_pk_bf16_f32 v2, v6, v7
	v_cvt_pk_bf16_f32 v3, v0, v1
	ds_write2_b64 v184, v[4:5], v[2:3] offset0:48 offset1:82
	v_mov_b32_e32 v4, v30
	v_mov_b32_e32 v5, v62
	v_mov_b32_e32 v2, v46
	v_mov_b32_e32 v3, v14
	v_pk_fma_f32 v[4:5], v[170:171], v[6:7], v[4:5]
	v_pk_fma_f32 v[2:3], v[170:171], v[0:1], v[2:3] neg_lo:[1,0,0] neg_hi:[1,0,0]
	v_pk_fma_f32 v[0:1], v[168:169], v[0:1], v[4:5]
	v_mov_b32_e32 v14, v47
	v_pk_fma_f32 v[2:3], v[168:169], v[6:7], v[2:3]
	v_mov_b32_e32 v62, v31
	v_pk_fma_f32 v[6:7], v[170:171], v[0:1], v[14:15] neg_lo:[1,0,0] neg_hi:[1,0,0]
	v_cvt_pk_bf16_f32 v4, v2, v3
	v_pk_fma_f32 v[132:133], v[168:169], v[2:3], v[6:7]
	v_pk_fma_f32 v[2:3], v[170:171], v[2:3], v[62:63]
	v_cvt_pk_bf16_f32 v5, v0, v1
	v_pk_fma_f32 v[134:135], v[168:169], v[0:1], v[2:3]
	v_cvt_pk_bf16_f32 v0, v132, v133
	v_cvt_pk_bf16_f32 v1, v134, v135
	ds_write2_b64 v184, v[4:5], v[0:1] offset0:116 offset1:150
	ds_read_b128 v[0:3], v180 offset:40960
	ds_read_b128 v[16:19], v180 offset:40992
	s_waitcnt lgkmcnt(1)
	v_mfma_f32_32x32x16_bf16 v[0:15], v[0:3], v[88:91], 0
	s_waitcnt lgkmcnt(0)
	v_mfma_f32_32x32x16_bf16 v[0:15], v[16:19], v[92:95], v[0:15]
	ds_read_b128 v[16:19], v180 offset:41024
	ds_read_b128 v[20:23], v180 offset:41056
	s_waitcnt lgkmcnt(1)
	v_mfma_f32_32x32x16_bf16 v[0:15], v[16:19], v[96:99], v[0:15]
	s_waitcnt lgkmcnt(0)
	v_mfma_f32_32x32x16_bf16 v[0:15], v[20:23], v[80:83], v[0:15]
	ds_read_b128 v[16:19], v180 offset:41088
	ds_read_b128 v[20:23], v180 offset:41120
	s_waitcnt lgkmcnt(1)
	v_mfma_f32_32x32x16_bf16 v[0:15], v[16:19], v[100:103], v[0:15]
	s_waitcnt lgkmcnt(0)
	v_mfma_f32_32x32x16_bf16 v[0:15], v[20:23], v[104:107], v[0:15]
	ds_read_b128 v[16:19], v180 offset:41152
	ds_read_b128 v[20:23], v180 offset:41184
	s_waitcnt lgkmcnt(1)
	v_mfma_f32_32x32x16_bf16 v[0:15], v[16:19], v[108:111], v[0:15]
	s_waitcnt lgkmcnt(0)
	v_mfma_f32_32x32x16_bf16 v[0:15], v[20:23], v[84:87], v[0:15]
	s_and_saveexec_b64 s[26:27], s[0:1]
	s_cbranch_execz .LBB0_834
	s_or_b32 s20, s30, 0x20
	s_xor_b32 s31, s30, 0xdf
	s_lshl_b32 s20, s20, 4
	s_lshl_b32 s31, s31, 4
	s_and_b64 s[34:35], s[4:5], exec
	s_cselect_b32 s20, s20, s31
	v_lshl_add_u64 v[16:17], s[20:21], 2, v[174:175]
	s_cbranch_scc0 .Lys2_b
	s_nop 3
	global_store_dword v[16:17], v0, off
	global_store_dword v[16:17], v1, off offset:64
	global_store_dword v[16:17], v2, off offset:128
	global_store_dword v[16:17], v3, off offset:192
	global_store_dword v[16:17], v4, off offset:256
	global_store_dword v[16:17], v5, off offset:320
	global_store_dword v[16:17], v6, off offset:384
	global_store_dword v[16:17], v7, off offset:448
	global_store_dword v[16:17], v8, off offset:512
	global_store_dword v[16:17], v9, off offset:576
	global_store_dword v[16:17], v10, off offset:640
	global_store_dword v[16:17], v11, off offset:704
	global_store_dword v[16:17], v12, off offset:768
	global_store_dword v[16:17], v13, off offset:832
	global_store_dword v[16:17], v14, off offset:896
	global_store_dword v[16:17], v15, off offset:960
	s_branch .Lys2_e

.Lys2_e:
.LBB0_834:
	s_or_b64 exec, exec, s[26:27]
	s_waitcnt vmcnt(4)
	v_mfma_f32_32x32x16_bf16 v[32:47], v[128:131], v[64:67], 0
	v_mfma_f32_32x32x16_bf16 v[0:15], v[128:131], v[72:75], 0
	s_nop 10
	v_mov_b32_e32 v136, v32
	v_mfma_f32_32x32x16_bf16 v[16:31], v[128:131], v[68:71], 0
	v_mov_b32_e32 v137, v0
	v_mov_b32_e32 v0, v33
	v_mfma_f32_32x32x16_bf16 v[48:63], v[128:131], v[76:79], 0
	s_nop 8
	v_mov_b32_e32 v138, v16
	v_fma_f32 v128, -v170, v134, v136
	v_fma_f32 v129, -v171, v135, v137
	v_fma_f32 v128, v168, v132, v128
	v_fma_f32 v129, v169, v133, v129
	v_mov_b32_e32 v139, v48
	v_pk_fma_f32 v[130:131], v[170:171], v[132:133], v[138:139]
	v_mov_b32_e32 v48, v17
	v_pk_fma_f32 v[130:131], v[168:169], v[134:135], v[130:131]
	v_pk_fma_f32 v[16:17], v[170:171], v[128:129], v[48:49]
	v_pk_fma_f32 v[0:1], v[170:171], v[130:131], v[0:1] neg_lo:[1,0,0] neg_hi:[1,0,0]
	v_pk_fma_f32 v[16:17], v[168:169], v[130:131], v[16:17]
	v_pk_fma_f32 v[0:1], v[168:169], v[128:129], v[0:1]
	v_cvt_pk_bf16_f32 v132, v128, v129
	v_cvt_pk_bf16_f32 v133, v130, v131
	v_cvt_pk_bf16_f32 v32, v0, v1
	v_cvt_pk_bf16_f32 v33, v16, v17
	ds_write2_b64 v181, v[132:133], v[32:33] offset1:34
	v_mov_b32_e32 v32, v34
	v_mov_b32_e32 v33, v2
	v_mov_b32_e32 v48, v18
	v_mov_b32_e32 v49, v50
	v_pk_fma_f32 v[32:33], v[170:171], v[16:17], v[32:33] neg_lo:[1,0,0] neg_hi:[1,0,0]
	v_mov_b32_e32 v2, v35
	v_pk_fma_f32 v[32:33], v[168:169], v[0:1], v[32:33]
	v_pk_fma_f32 v[0:1], v[170:171], v[0:1], v[48:49]
	v_mov_b32_e32 v50, v19
	v_pk_fma_f32 v[0:1], v[168:169], v[16:17], v[0:1]
	v_pk_fma_f32 v[18:19], v[170:171], v[32:33], v[50:51]
	v_pk_fma_f32 v[2:3], v[170:171], v[0:1], v[2:3] neg_lo:[1,0,0] neg_hi:[1,0,0]
	v_cvt_pk_bf16_f32 v17, v0, v1
	v_pk_fma_f32 v[2:3], v[168:169], v[32:33], v[2:3]
	v_pk_fma_f32 v[0:1], v[168:169], v[0:1], v[18:19]
	v_cvt_pk_bf16_f32 v16, v32, v33
	v_cvt_pk_bf16_f32 v18, v2, v3
	v_cvt_pk_bf16_f32 v19, v0, v1
	ds_write2_b64 v181, v[16:17], v[18:19] offset0:68 offset1:102
	v_mov_b32_e32 v16, v36
	v_mov_b32_e32 v17, v4
	v_mov_b32_e32 v18, v20
	v_mov_b32_e32 v19, v52
	v_pk_fma_f32 v[16:17], v[170:171], v[0:1], v[16:17] neg_lo:[1,0,0] neg_hi:[1,0,0]
	v_mov_b32_e32 v4, v37
	v_pk_fma_f32 v[16:17], v[168:169], v[2:3], v[16:17]
	v_pk_fma_f32 v[2:3], v[170:171], v[2:3], v[18:19]
	v_mov_b32_e32 v52, v21
	v_pk_fma_f32 v[0:1], v[168:169], v[0:1], v[2:3]
	v_cvt_pk_bf16_f32 v2, v16, v17
	v_pk_fma_f32 v[4:5], v[170:171], v[0:1], v[4:5] neg_lo:[1,0,0] neg_hi:[1,0,0]
	v_cvt_pk_bf16_f32 v3, v0, v1
	v_pk_fma_f32 v[4:5], v[168:169], v[16:17], v[4:5]
	v_pk_fma_f32 v[16:17], v[170:171], v[16:17], v[52:53]
	s_nop 0
	v_pk_fma_f32 v[0:1], v[168:169], v[0:1], v[16:17]
	v_cvt_pk_bf16_f32 v16, v4, v5
	v_cvt_pk_bf16_f32 v17, v0, v1
	ds_write2_b64 v182, v[2:3], v[16:17] offset0:16 offset1:50
	v_mov_b32_e32 v2, v38
	v_mov_b32_e32 v3, v6
	v_mov_b32_e32 v16, v22
	v_mov_b32_e32 v17, v54
	v_pk_fma_f32 v[2:3], v[170:171], v[0:1], v[2:3] neg_lo:[1,0,0] neg_hi:[1,0,0]
	v_mov_b32_e32 v6, v39
	v_pk_fma_f32 v[2:3], v[168:169], v[4:5], v[2:3]
	v_pk_fma_f32 v[4:5], v[170:171], v[4:5], v[16:17]
	v_mov_b32_e32 v54, v23
	v_pk_fma_f32 v[0:1], v[168:169], v[0:1], v[4:5]
	v_cvt_pk_bf16_f32 v4, v2, v3
	v_pk_fma_f32 v[6:7], v[170:171], v[0:1], v[6:7] neg_lo:[1,0,0] neg_hi:[1,0,0]
	v_cvt_pk_bf16_f32 v5, v0, v1
	v_pk_fma_f32 v[6:7], v[168:169], v[2:3], v[6:7]
	v_pk_fma_f32 v[2:3], v[170:171], v[2:3], v[54:55]
	s_nop 0
	v_pk_fma_f32 v[0:1], v[168:169], v[0:1], v[2:3]
	v_cvt_pk_bf16_f32 v2, v6, v7
	v_cvt_pk_bf16_f32 v3, v0, v1
	ds_write2_b64 v182, v[4:5], v[2:3] offset0:84 offset1:118
	v_mov_b32_e32 v4, v24
	v_mov_b32_e32 v5, v56
	v_mov_b32_e32 v2, v40
	v_mov_b32_e32 v3, v8
	v_pk_fma_f32 v[4:5], v[170:171], v[6:7], v[4:5]
	v_pk_fma_f32 v[2:3], v[170:171], v[0:1], v[2:3] neg_lo:[1,0,0] neg_hi:[1,0,0]
	v_pk_fma_f32 v[0:1], v[168:169], v[0:1], v[4:5]
	v_mov_b32_e32 v8, v41
	v_pk_fma_f32 v[2:3], v[168:169], v[6:7], v[2:3]
	v_mov_b32_e32 v56, v25
	v_pk_fma_f32 v[6:7], v[170:171], v[0:1], v[8:9] neg_lo:[1,0,0] neg_hi:[1,0,0]
	v_cvt_pk_bf16_f32 v4, v2, v3
	v_pk_fma_f32 v[6:7], v[168:169], v[2:3], v[6:7]
	v_pk_fma_f32 v[2:3], v[170:171], v[2:3], v[56:57]
	v_cvt_pk_bf16_f32 v5, v0, v1
	v_pk_fma_f32 v[0:1], v[168:169], v[0:1], v[2:3]
	v_cvt_pk_bf16_f32 v2, v6, v7
	v_cvt_pk_bf16_f32 v3, v0, v1
	ds_write2_b64 v183, v[4:5], v[2:3] offset0:32 offset1:66
	v_mov_b32_e32 v4, v26
	v_mov_b32_e32 v5, v58
	v_mov_b32_e32 v2, v42
	v_mov_b32_e32 v3, v10
	v_pk_fma_f32 v[4:5], v[170:171], v[6:7], v[4:5]
	v_pk_fma_f32 v[2:3], v[170:171], v[0:1], v[2:3] neg_lo:[1,0,0] neg_hi:[1,0,0]
	v_pk_fma_f32 v[0:1], v[168:169], v[0:1], v[4:5]
	v_mov_b32_e32 v10, v43
	v_pk_fma_f32 v[2:3], v[168:169], v[6:7], v[2:3]
	v_mov_b32_e32 v58, v27
	v_pk_fma_f32 v[6:7], v[170:171], v[0:1], v[10:11] neg_lo:[1,0,0] neg_hi:[1,0,0]
	v_cvt_pk_bf16_f32 v4, v2, v3
	v_pk_fma_f32 v[6:7], v[168:169], v[2:3], v[6:7]
	v_pk_fma_f32 v[2:3], v[170:171], v[2:3], v[58:59]
	v_cvt_pk_bf16_f32 v5, v0, v1
	v_pk_fma_f32 v[0:1], v[168:169], v[0:1], v[2:3]
	v_cvt_pk_bf16_f32 v2, v6, v7
	v_cvt_pk_bf16_f32 v3, v0, v1
	ds_write2_b64 v183, v[4:5], v[2:3] offset0:100 offset1:134
	v_mov_b32_e32 v4, v28
	v_mov_b32_e32 v5, v60
	v_mov_b32_e32 v2, v44
	v_mov_b32_e32 v3, v12
	v_pk_fma_f32 v[4:5], v[170:171], v[6:7], v[4:5]
	v_pk_fma_f32 v[2:3], v[170:171], v[0:1], v[2:3] neg_lo:[1,0,0] neg_hi:[1,0,0]
	v_pk_fma_f32 v[0:1], v[168:169], v[0:1], v[4:5]
	v_mov_b32_e32 v12, v45
	v_pk_fma_f32 v[2:3], v[168:169], v[6:7], v[2:3]
	v_mov_b32_e32 v60, v29
	v_pk_fma_f32 v[6:7], v[170:171], v[0:1], v[12:13] neg_lo:[1,0,0] neg_hi:[1,0,0]
	v_cvt_pk_bf16_f32 v4, v2, v3
	v_pk_fma_f32 v[6:7], v[168:169], v[2:3], v[6:7]
	v_pk_fma_f32 v[2:3], v[170:171], v[2:3], v[60:61]
	v_cvt_pk_bf16_f32 v5, v0, v1
	v_pk_fma_f32 v[0:1], v[168:169], v[0:1], v[2:3]
	v_cvt_pk_bf16_f32 v2, v6, v7
	v_cvt_pk_bf16_f32 v3, v0, v1
	ds_write2_b64 v184, v[4:5], v[2:3] offset0:48 offset1:82
	v_mov_b32_e32 v4, v30
	v_mov_b32_e32 v5, v62
	v_mov_b32_e32 v2, v46
	v_mov_b32_e32 v3, v14
	v_pk_fma_f32 v[4:5], v[170:171], v[6:7], v[4:5]
	v_pk_fma_f32 v[2:3], v[170:171], v[0:1], v[2:3] neg_lo:[1,0,0] neg_hi:[1,0,0]
	v_pk_fma_f32 v[0:1], v[168:169], v[0:1], v[4:5]
	v_mov_b32_e32 v14, v47
	v_pk_fma_f32 v[2:3], v[168:169], v[6:7], v[2:3]
	v_mov_b32_e32 v62, v31
	v_pk_fma_f32 v[6:7], v[170:171], v[0:1], v[14:15] neg_lo:[1,0,0] neg_hi:[1,0,0]
	v_cvt_pk_bf16_f32 v4, v2, v3
	v_pk_fma_f32 v[128:129], v[168:169], v[2:3], v[6:7]
	v_pk_fma_f32 v[2:3], v[170:171], v[2:3], v[62:63]
	v_cvt_pk_bf16_f32 v5, v0, v1
	v_pk_fma_f32 v[130:131], v[168:169], v[0:1], v[2:3]
	v_cvt_pk_bf16_f32 v0, v128, v129
	v_cvt_pk_bf16_f32 v1, v130, v131
	ds_write2_b64 v184, v[4:5], v[0:1] offset0:116 offset1:150
	ds_read_b128 v[0:3], v180 offset:40960
	ds_read_b128 v[16:19], v180 offset:40992
	s_waitcnt lgkmcnt(1)
	v_mfma_f32_32x32x16_bf16 v[0:15], v[0:3], v[88:91], 0
	s_waitcnt lgkmcnt(0)
	v_mfma_f32_32x32x16_bf16 v[0:15], v[16:19], v[92:95], v[0:15]
	ds_read_b128 v[16:19], v180 offset:41024
	ds_read_b128 v[20:23], v180 offset:41056
	s_waitcnt lgkmcnt(1)
	v_mfma_f32_32x32x16_bf16 v[0:15], v[16:19], v[96:99], v[0:15]
	s_waitcnt lgkmcnt(0)
	v_mfma_f32_32x32x16_bf16 v[0:15], v[20:23], v[80:83], v[0:15]
	ds_read_b128 v[16:19], v180 offset:41088
	ds_read_b128 v[20:23], v180 offset:41120
	s_waitcnt lgkmcnt(1)
	v_mfma_f32_32x32x16_bf16 v[0:15], v[16:19], v[100:103], v[0:15]
	s_waitcnt lgkmcnt(0)
	v_mfma_f32_32x32x16_bf16 v[0:15], v[20:23], v[104:107], v[0:15]
	ds_read_b128 v[16:19], v180 offset:41152
	ds_read_b128 v[20:23], v180 offset:41184
	s_waitcnt lgkmcnt(1)
	v_mfma_f32_32x32x16_bf16 v[0:15], v[16:19], v[108:111], v[0:15]
	s_waitcnt lgkmcnt(0)
	v_mfma_f32_32x32x16_bf16 v[0:15], v[20:23], v[84:87], v[0:15]
	s_and_saveexec_b64 s[26:27], s[0:1]
	s_cbranch_execz .LBB0_836
	s_or_b32 s20, s30, 0x30
	s_xor_b32 s31, s30, 0xcf
	s_lshl_b32 s20, s20, 4
	s_lshl_b32 s31, s31, 4
	s_and_b64 s[34:35], s[4:5], exec
	s_cselect_b32 s20, s20, s31
	v_lshl_add_u64 v[16:17], s[20:21], 2, v[174:175]
	s_cbranch_scc0 .Lys3_b
	s_nop 3
	global_store_dword v[16:17], v0, off
	global_store_dword v[16:17], v1, off offset:64
	global_store_dword v[16:17], v2, off offset:128
	global_store_dword v[16:17], v3, off offset:192
	global_store_dword v[16:17], v4, off offset:256
	global_store_dword v[16:17], v5, off offset:320
	global_store_dword v[16:17], v6, off offset:384
	global_store_dword v[16:17], v7, off offset:448
	global_store_dword v[16:17], v8, off offset:512
	global_store_dword v[16:17], v9, off offset:576
	global_store_dword v[16:17], v10, off offset:640
	global_store_dword v[16:17], v11, off offset:704
	global_store_dword v[16:17], v12, off offset:768
	global_store_dword v[16:17], v13, off offset:832
	global_store_dword v[16:17], v14, off offset:896
	global_store_dword v[16:17], v15, off offset:960
	s_branch .Lys3_e

.Lys3_e:
.LBB0_836:
	s_or_b64 exec, exec, s[26:27]
	s_waitcnt vmcnt(3)
	v_mfma_f32_32x32x16_bf16 v[32:47], v[124:127], v[64:67], 0
	v_mfma_f32_32x32x16_bf16 v[0:15], v[124:127], v[72:75], 0
	s_nop 10
	v_mov_b32_e32 v132, v32
	v_mfma_f32_32x32x16_bf16 v[16:31], v[124:127], v[68:71], 0
	v_mov_b32_e32 v133, v0
	v_mov_b32_e32 v0, v33
	v_mfma_f32_32x32x16_bf16 v[48:63], v[124:127], v[76:79], 0
	s_nop 8
	v_mov_b32_e32 v134, v16
	v_fma_f32 v124, -v170, v130, v132
	v_fma_f32 v125, -v171, v131, v133
	v_fma_f32 v124, v168, v128, v124
	v_fma_f32 v125, v169, v129, v125
	v_mov_b32_e32 v135, v48
	v_pk_fma_f32 v[126:127], v[170:171], v[128:129], v[134:135]
	v_mov_b32_e32 v48, v17
	v_pk_fma_f32 v[126:127], v[168:169], v[130:131], v[126:127]
	v_pk_fma_f32 v[16:17], v[170:171], v[124:125], v[48:49]
	v_pk_fma_f32 v[0:1], v[170:171], v[126:127], v[0:1] neg_lo:[1,0,0] neg_hi:[1,0,0]
	v_pk_fma_f32 v[16:17], v[168:169], v[126:127], v[16:17]
	v_pk_fma_f32 v[0:1], v[168:169], v[124:125], v[0:1]
	v_cvt_pk_bf16_f32 v128, v124, v125
	v_cvt_pk_bf16_f32 v129, v126, v127
	v_cvt_pk_bf16_f32 v32, v0, v1
	v_cvt_pk_bf16_f32 v33, v16, v17
	ds_write2_b64 v181, v[128:129], v[32:33] offset1:34
	v_mov_b32_e32 v32, v34
	v_mov_b32_e32 v33, v2
	v_mov_b32_e32 v48, v18
	v_mov_b32_e32 v49, v50
	v_pk_fma_f32 v[32:33], v[170:171], v[16:17], v[32:33] neg_lo:[1,0,0] neg_hi:[1,0,0]
	v_mov_b32_e32 v2, v35
	v_pk_fma_f32 v[32:33], v[168:169], v[0:1], v[32:33]
	v_pk_fma_f32 v[0:1], v[170:171], v[0:1], v[48:49]
	v_mov_b32_e32 v50, v19
	v_pk_fma_f32 v[0:1], v[168:169], v[16:17], v[0:1]
	v_pk_fma_f32 v[18:19], v[170:171], v[32:33], v[50:51]
	v_pk_fma_f32 v[2:3], v[170:171], v[0:1], v[2:3] neg_lo:[1,0,0] neg_hi:[1,0,0]
	v_cvt_pk_bf16_f32 v17, v0, v1
	v_pk_fma_f32 v[2:3], v[168:169], v[32:33], v[2:3]
	v_pk_fma_f32 v[0:1], v[168:169], v[0:1], v[18:19]
	v_cvt_pk_bf16_f32 v16, v32, v33
	v_cvt_pk_bf16_f32 v18, v2, v3
	v_cvt_pk_bf16_f32 v19, v0, v1
	ds_write2_b64 v181, v[16:17], v[18:19] offset0:68 offset1:102
	v_mov_b32_e32 v16, v36
	v_mov_b32_e32 v17, v4
	v_mov_b32_e32 v18, v20
	v_mov_b32_e32 v19, v52
	v_pk_fma_f32 v[16:17], v[170:171], v[0:1], v[16:17] neg_lo:[1,0,0] neg_hi:[1,0,0]
	v_mov_b32_e32 v4, v37
	v_pk_fma_f32 v[16:17], v[168:169], v[2:3], v[16:17]
	v_pk_fma_f32 v[2:3], v[170:171], v[2:3], v[18:19]
	v_mov_b32_e32 v52, v21
	v_pk_fma_f32 v[0:1], v[168:169], v[0:1], v[2:3]
	v_cvt_pk_bf16_f32 v2, v16, v17
	v_pk_fma_f32 v[4:5], v[170:171], v[0:1], v[4:5] neg_lo:[1,0,0] neg_hi:[1,0,0]
	v_cvt_pk_bf16_f32 v3, v0, v1
	v_pk_fma_f32 v[4:5], v[168:169], v[16:17], v[4:5]
	v_pk_fma_f32 v[16:17], v[170:171], v[16:17], v[52:53]
	s_nop 0
	v_pk_fma_f32 v[0:1], v[168:169], v[0:1], v[16:17]
	v_cvt_pk_bf16_f32 v16, v4, v5
	v_cvt_pk_bf16_f32 v17, v0, v1
	ds_write2_b64 v182, v[2:3], v[16:17] offset0:16 offset1:50
	v_mov_b32_e32 v2, v38
	v_mov_b32_e32 v3, v6
	v_mov_b32_e32 v16, v22
	v_mov_b32_e32 v17, v54
	v_pk_fma_f32 v[2:3], v[170:171], v[0:1], v[2:3] neg_lo:[1,0,0] neg_hi:[1,0,0]
	v_mov_b32_e32 v6, v39
	v_pk_fma_f32 v[2:3], v[168:169], v[4:5], v[2:3]
	v_pk_fma_f32 v[4:5], v[170:171], v[4:5], v[16:17]
	v_mov_b32_e32 v54, v23
	v_pk_fma_f32 v[0:1], v[168:169], v[0:1], v[4:5]
	v_cvt_pk_bf16_f32 v4, v2, v3
	v_pk_fma_f32 v[6:7], v[170:171], v[0:1], v[6:7] neg_lo:[1,0,0] neg_hi:[1,0,0]
	v_cvt_pk_bf16_f32 v5, v0, v1
	v_pk_fma_f32 v[6:7], v[168:169], v[2:3], v[6:7]
	v_pk_fma_f32 v[2:3], v[170:171], v[2:3], v[54:55]
	s_nop 0
	v_pk_fma_f32 v[0:1], v[168:169], v[0:1], v[2:3]
	v_cvt_pk_bf16_f32 v2, v6, v7
	v_cvt_pk_bf16_f32 v3, v0, v1
	ds_write2_b64 v182, v[4:5], v[2:3] offset0:84 offset1:118
	v_mov_b32_e32 v4, v24
	v_mov_b32_e32 v5, v56
	v_mov_b32_e32 v2, v40
	v_mov_b32_e32 v3, v8
	v_pk_fma_f32 v[4:5], v[170:171], v[6:7], v[4:5]
	v_pk_fma_f32 v[2:3], v[170:171], v[0:1], v[2:3] neg_lo:[1,0,0] neg_hi:[1,0,0]
	v_pk_fma_f32 v[0:1], v[168:169], v[0:1], v[4:5]
	v_mov_b32_e32 v8, v41
	v_pk_fma_f32 v[2:3], v[168:169], v[6:7], v[2:3]
	v_mov_b32_e32 v56, v25
	v_pk_fma_f32 v[6:7], v[170:171], v[0:1], v[8:9] neg_lo:[1,0,0] neg_hi:[1,0,0]
	v_cvt_pk_bf16_f32 v4, v2, v3
	v_pk_fma_f32 v[6:7], v[168:169], v[2:3], v[6:7]
	v_pk_fma_f32 v[2:3], v[170:171], v[2:3], v[56:57]
	v_cvt_pk_bf16_f32 v5, v0, v1
	v_pk_fma_f32 v[0:1], v[168:169], v[0:1], v[2:3]
	v_cvt_pk_bf16_f32 v2, v6, v7
	v_cvt_pk_bf16_f32 v3, v0, v1
	ds_write2_b64 v183, v[4:5], v[2:3] offset0:32 offset1:66
	v_mov_b32_e32 v4, v26
	v_mov_b32_e32 v5, v58
	v_mov_b32_e32 v2, v42
	v_mov_b32_e32 v3, v10
	v_pk_fma_f32 v[4:5], v[170:171], v[6:7], v[4:5]
	v_pk_fma_f32 v[2:3], v[170:171], v[0:1], v[2:3] neg_lo:[1,0,0] neg_hi:[1,0,0]
	v_pk_fma_f32 v[0:1], v[168:169], v[0:1], v[4:5]
	v_mov_b32_e32 v10, v43
	v_pk_fma_f32 v[2:3], v[168:169], v[6:7], v[2:3]
	v_mov_b32_e32 v58, v27
	v_pk_fma_f32 v[6:7], v[170:171], v[0:1], v[10:11] neg_lo:[1,0,0] neg_hi:[1,0,0]
	v_cvt_pk_bf16_f32 v4, v2, v3
	v_pk_fma_f32 v[6:7], v[168:169], v[2:3], v[6:7]
	v_pk_fma_f32 v[2:3], v[170:171], v[2:3], v[58:59]
	v_cvt_pk_bf16_f32 v5, v0, v1
	v_pk_fma_f32 v[0:1], v[168:169], v[0:1], v[2:3]
	v_cvt_pk_bf16_f32 v2, v6, v7
	v_cvt_pk_bf16_f32 v3, v0, v1
	ds_write2_b64 v183, v[4:5], v[2:3] offset0:100 offset1:134
	v_mov_b32_e32 v4, v28
	v_mov_b32_e32 v5, v60
	v_mov_b32_e32 v2, v44
	v_mov_b32_e32 v3, v12
	v_pk_fma_f32 v[4:5], v[170:171], v[6:7], v[4:5]
	v_pk_fma_f32 v[2:3], v[170:171], v[0:1], v[2:3] neg_lo:[1,0,0] neg_hi:[1,0,0]
	v_pk_fma_f32 v[0:1], v[168:169], v[0:1], v[4:5]
	v_mov_b32_e32 v12, v45
	v_pk_fma_f32 v[2:3], v[168:169], v[6:7], v[2:3]
	v_mov_b32_e32 v60, v29
	v_pk_fma_f32 v[6:7], v[170:171], v[0:1], v[12:13] neg_lo:[1,0,0] neg_hi:[1,0,0]
	v_cvt_pk_bf16_f32 v4, v2, v3
	v_pk_fma_f32 v[6:7], v[168:169], v[2:3], v[6:7]
	v_pk_fma_f32 v[2:3], v[170:171], v[2:3], v[60:61]
	v_cvt_pk_bf16_f32 v5, v0, v1
	v_pk_fma_f32 v[0:1], v[168:169], v[0:1], v[2:3]
	v_cvt_pk_bf16_f32 v2, v6, v7
	v_cvt_pk_bf16_f32 v3, v0, v1
	ds_write2_b64 v184, v[4:5], v[2:3] offset0:48 offset1:82
	v_mov_b32_e32 v4, v30
	v_mov_b32_e32 v5, v62
	v_mov_b32_e32 v2, v46
	v_mov_b32_e32 v3, v14
	v_pk_fma_f32 v[4:5], v[170:171], v[6:7], v[4:5]
	v_pk_fma_f32 v[2:3], v[170:171], v[0:1], v[2:3] neg_lo:[1,0,0] neg_hi:[1,0,0]
	v_pk_fma_f32 v[0:1], v[168:169], v[0:1], v[4:5]
	v_mov_b32_e32 v14, v47
	v_pk_fma_f32 v[2:3], v[168:169], v[6:7], v[2:3]
	v_mov_b32_e32 v62, v31
	v_pk_fma_f32 v[6:7], v[170:171], v[0:1], v[14:15] neg_lo:[1,0,0] neg_hi:[1,0,0]
	v_cvt_pk_bf16_f32 v4, v2, v3
	v_pk_fma_f32 v[124:125], v[168:169], v[2:3], v[6:7]
	v_pk_fma_f32 v[2:3], v[170:171], v[2:3], v[62:63]
	v_cvt_pk_bf16_f32 v5, v0, v1
	v_pk_fma_f32 v[126:127], v[168:169], v[0:1], v[2:3]
	v_cvt_pk_bf16_f32 v0, v124, v125
	v_cvt_pk_bf16_f32 v1, v126, v127
	ds_write2_b64 v184, v[4:5], v[0:1] offset0:116 offset1:150
	ds_read_b128 v[0:3], v180 offset:40960
	ds_read_b128 v[16:19], v180 offset:40992
	s_waitcnt lgkmcnt(1)
	v_mfma_f32_32x32x16_bf16 v[0:15], v[0:3], v[88:91], 0
	s_waitcnt lgkmcnt(0)
	v_mfma_f32_32x32x16_bf16 v[0:15], v[16:19], v[92:95], v[0:15]
	ds_read_b128 v[16:19], v180 offset:41024
	ds_read_b128 v[20:23], v180 offset:41056
	s_waitcnt lgkmcnt(1)
	v_mfma_f32_32x32x16_bf16 v[0:15], v[16:19], v[96:99], v[0:15]
	s_waitcnt lgkmcnt(0)
	v_mfma_f32_32x32x16_bf16 v[0:15], v[20:23], v[80:83], v[0:15]
	ds_read_b128 v[16:19], v180 offset:41088
	ds_read_b128 v[20:23], v180 offset:41120
	s_waitcnt lgkmcnt(1)
	v_mfma_f32_32x32x16_bf16 v[0:15], v[16:19], v[100:103], v[0:15]
	s_waitcnt lgkmcnt(0)
	v_mfma_f32_32x32x16_bf16 v[0:15], v[20:23], v[104:107], v[0:15]
	ds_read_b128 v[16:19], v180 offset:41152
	ds_read_b128 v[20:23], v180 offset:41184
	s_waitcnt lgkmcnt(1)
	v_mfma_f32_32x32x16_bf16 v[0:15], v[16:19], v[108:111], v[0:15]
	s_waitcnt lgkmcnt(0)
	v_mfma_f32_32x32x16_bf16 v[0:15], v[20:23], v[84:87], v[0:15]
	s_and_saveexec_b64 s[26:27], s[0:1]
	s_cbranch_execz .LBB0_838
	s_or_b32 s20, s30, 0x40
	s_xor_b32 s31, s30, 0xbf
	s_lshl_b32 s20, s20, 4
	s_lshl_b32 s31, s31, 4
	s_and_b64 s[34:35], s[4:5], exec
	s_cselect_b32 s20, s20, s31
	v_lshl_add_u64 v[16:17], s[20:21], 2, v[174:175]
	s_cbranch_scc0 .Lys4_b
	s_nop 3
	global_store_dword v[16:17], v0, off
	global_store_dword v[16:17], v1, off offset:64
	global_store_dword v[16:17], v2, off offset:128
	global_store_dword v[16:17], v3, off offset:192
	global_store_dword v[16:17], v4, off offset:256
	global_store_dword v[16:17], v5, off offset:320
	global_store_dword v[16:17], v6, off offset:384
	global_store_dword v[16:17], v7, off offset:448
	global_store_dword v[16:17], v8, off offset:512
	global_store_dword v[16:17], v9, off offset:576
	global_store_dword v[16:17], v10, off offset:640
	global_store_dword v[16:17], v11, off offset:704
	global_store_dword v[16:17], v12, off offset:768
	global_store_dword v[16:17], v13, off offset:832
	global_store_dword v[16:17], v14, off offset:896
	global_store_dword v[16:17], v15, off offset:960
	s_branch .Lys4_e

.Lys4_e:
.LBB0_838:
	s_or_b64 exec, exec, s[26:27]
	s_waitcnt vmcnt(2)
	v_mfma_f32_32x32x16_bf16 v[32:47], v[120:123], v[64:67], 0
	v_mfma_f32_32x32x16_bf16 v[0:15], v[120:123], v[72:75], 0
	s_nop 10
	v_mov_b32_e32 v128, v32
	v_mfma_f32_32x32x16_bf16 v[16:31], v[120:123], v[68:71], 0
	v_mov_b32_e32 v129, v0
	v_mov_b32_e32 v0, v33
	v_mfma_f32_32x32x16_bf16 v[48:63], v[120:123], v[76:79], 0
	s_nop 8
	v_mov_b32_e32 v130, v16
	v_fma_f32 v120, -v170, v126, v128
	v_fma_f32 v121, -v171, v127, v129
	v_fma_f32 v120, v168, v124, v120
	v_fma_f32 v121, v169, v125, v121
	v_mov_b32_e32 v131, v48
	v_pk_fma_f32 v[122:123], v[170:171], v[124:125], v[130:131]
	v_mov_b32_e32 v48, v17
	v_pk_fma_f32 v[122:123], v[168:169], v[126:127], v[122:123]
	v_pk_fma_f32 v[16:17], v[170:171], v[120:121], v[48:49]
	v_pk_fma_f32 v[0:1], v[170:171], v[122:123], v[0:1] neg_lo:[1,0,0] neg_hi:[1,0,0]
	v_pk_fma_f32 v[16:17], v[168:169], v[122:123], v[16:17]
	v_pk_fma_f32 v[0:1], v[168:169], v[120:121], v[0:1]
	v_cvt_pk_bf16_f32 v124, v120, v121
	v_cvt_pk_bf16_f32 v125, v122, v123
	v_cvt_pk_bf16_f32 v32, v0, v1
	v_cvt_pk_bf16_f32 v33, v16, v17
	ds_write2_b64 v181, v[124:125], v[32:33] offset1:34
	v_mov_b32_e32 v32, v34
	v_mov_b32_e32 v33, v2
	v_mov_b32_e32 v48, v18
	v_mov_b32_e32 v49, v50
	v_pk_fma_f32 v[32:33], v[170:171], v[16:17], v[32:33] neg_lo:[1,0,0] neg_hi:[1,0,0]
	v_mov_b32_e32 v2, v35
	v_pk_fma_f32 v[32:33], v[168:169], v[0:1], v[32:33]
	v_pk_fma_f32 v[0:1], v[170:171], v[0:1], v[48:49]
	v_mov_b32_e32 v50, v19
	v_pk_fma_f32 v[0:1], v[168:169], v[16:17], v[0:1]
	v_pk_fma_f32 v[18:19], v[170:171], v[32:33], v[50:51]
	v_pk_fma_f32 v[2:3], v[170:171], v[0:1], v[2:3] neg_lo:[1,0,0] neg_hi:[1,0,0]
	v_cvt_pk_bf16_f32 v17, v0, v1
	v_pk_fma_f32 v[2:3], v[168:169], v[32:33], v[2:3]
	v_pk_fma_f32 v[0:1], v[168:169], v[0:1], v[18:19]
	v_cvt_pk_bf16_f32 v16, v32, v33
	v_cvt_pk_bf16_f32 v18, v2, v3
	v_cvt_pk_bf16_f32 v19, v0, v1
	ds_write2_b64 v181, v[16:17], v[18:19] offset0:68 offset1:102
	v_mov_b32_e32 v16, v36
	v_mov_b32_e32 v17, v4
	v_mov_b32_e32 v18, v20
	v_mov_b32_e32 v19, v52
	v_pk_fma_f32 v[16:17], v[170:171], v[0:1], v[16:17] neg_lo:[1,0,0] neg_hi:[1,0,0]
	v_mov_b32_e32 v4, v37
	v_pk_fma_f32 v[16:17], v[168:169], v[2:3], v[16:17]
	v_pk_fma_f32 v[2:3], v[170:171], v[2:3], v[18:19]
	v_mov_b32_e32 v52, v21
	v_pk_fma_f32 v[0:1], v[168:169], v[0:1], v[2:3]
	v_cvt_pk_bf16_f32 v2, v16, v17
	v_pk_fma_f32 v[4:5], v[170:171], v[0:1], v[4:5] neg_lo:[1,0,0] neg_hi:[1,0,0]
	v_cvt_pk_bf16_f32 v3, v0, v1
	v_pk_fma_f32 v[4:5], v[168:169], v[16:17], v[4:5]
	v_pk_fma_f32 v[16:17], v[170:171], v[16:17], v[52:53]
	s_nop 0
	v_pk_fma_f32 v[0:1], v[168:169], v[0:1], v[16:17]
	v_cvt_pk_bf16_f32 v16, v4, v5
	v_cvt_pk_bf16_f32 v17, v0, v1
	ds_write2_b64 v182, v[2:3], v[16:17] offset0:16 offset1:50
	v_mov_b32_e32 v2, v38
	v_mov_b32_e32 v3, v6
	v_mov_b32_e32 v16, v22
	v_mov_b32_e32 v17, v54
	v_pk_fma_f32 v[2:3], v[170:171], v[0:1], v[2:3] neg_lo:[1,0,0] neg_hi:[1,0,0]
	v_mov_b32_e32 v6, v39
	v_pk_fma_f32 v[2:3], v[168:169], v[4:5], v[2:3]
	v_pk_fma_f32 v[4:5], v[170:171], v[4:5], v[16:17]
	v_mov_b32_e32 v54, v23
	v_pk_fma_f32 v[0:1], v[168:169], v[0:1], v[4:5]
	v_cvt_pk_bf16_f32 v4, v2, v3
	v_pk_fma_f32 v[6:7], v[170:171], v[0:1], v[6:7] neg_lo:[1,0,0] neg_hi:[1,0,0]
	v_cvt_pk_bf16_f32 v5, v0, v1
	v_pk_fma_f32 v[6:7], v[168:169], v[2:3], v[6:7]
	v_pk_fma_f32 v[2:3], v[170:171], v[2:3], v[54:55]
	s_nop 0
	v_pk_fma_f32 v[0:1], v[168:169], v[0:1], v[2:3]
	v_cvt_pk_bf16_f32 v2, v6, v7
	v_cvt_pk_bf16_f32 v3, v0, v1
	ds_write2_b64 v182, v[4:5], v[2:3] offset0:84 offset1:118
	v_mov_b32_e32 v4, v24
	v_mov_b32_e32 v5, v56
	v_mov_b32_e32 v2, v40
	v_mov_b32_e32 v3, v8
	v_pk_fma_f32 v[4:5], v[170:171], v[6:7], v[4:5]
	v_pk_fma_f32 v[2:3], v[170:171], v[0:1], v[2:3] neg_lo:[1,0,0] neg_hi:[1,0,0]
	v_pk_fma_f32 v[0:1], v[168:169], v[0:1], v[4:5]
	v_mov_b32_e32 v8, v41
	v_pk_fma_f32 v[2:3], v[168:169], v[6:7], v[2:3]
	v_mov_b32_e32 v56, v25
	v_pk_fma_f32 v[6:7], v[170:171], v[0:1], v[8:9] neg_lo:[1,0,0] neg_hi:[1,0,0]
	v_cvt_pk_bf16_f32 v4, v2, v3
	v_pk_fma_f32 v[6:7], v[168:169], v[2:3], v[6:7]
	v_pk_fma_f32 v[2:3], v[170:171], v[2:3], v[56:57]
	v_cvt_pk_bf16_f32 v5, v0, v1
	v_pk_fma_f32 v[0:1], v[168:169], v[0:1], v[2:3]
	v_cvt_pk_bf16_f32 v2, v6, v7
	v_cvt_pk_bf16_f32 v3, v0, v1
	ds_write2_b64 v183, v[4:5], v[2:3] offset0:32 offset1:66
	v_mov_b32_e32 v4, v26
	v_mov_b32_e32 v5, v58
	v_mov_b32_e32 v2, v42
	v_mov_b32_e32 v3, v10
	v_pk_fma_f32 v[4:5], v[170:171], v[6:7], v[4:5]
	v_pk_fma_f32 v[2:3], v[170:171], v[0:1], v[2:3] neg_lo:[1,0,0] neg_hi:[1,0,0]
	v_pk_fma_f32 v[0:1], v[168:169], v[0:1], v[4:5]
	v_mov_b32_e32 v10, v43
	v_pk_fma_f32 v[2:3], v[168:169], v[6:7], v[2:3]
	v_mov_b32_e32 v58, v27
	v_pk_fma_f32 v[6:7], v[170:171], v[0:1], v[10:11] neg_lo:[1,0,0] neg_hi:[1,0,0]
	v_cvt_pk_bf16_f32 v4, v2, v3
	v_pk_fma_f32 v[6:7], v[168:169], v[2:3], v[6:7]
	v_pk_fma_f32 v[2:3], v[170:171], v[2:3], v[58:59]
	v_cvt_pk_bf16_f32 v5, v0, v1
	v_pk_fma_f32 v[0:1], v[168:169], v[0:1], v[2:3]
	v_cvt_pk_bf16_f32 v2, v6, v7
	v_cvt_pk_bf16_f32 v3, v0, v1
	ds_write2_b64 v183, v[4:5], v[2:3] offset0:100 offset1:134
	v_mov_b32_e32 v4, v28
	v_mov_b32_e32 v5, v60
	v_mov_b32_e32 v2, v44
	v_mov_b32_e32 v3, v12
	v_pk_fma_f32 v[4:5], v[170:171], v[6:7], v[4:5]
	v_pk_fma_f32 v[2:3], v[170:171], v[0:1], v[2:3] neg_lo:[1,0,0] neg_hi:[1,0,0]
	v_pk_fma_f32 v[0:1], v[168:169], v[0:1], v[4:5]
	v_mov_b32_e32 v12, v45
	v_pk_fma_f32 v[2:3], v[168:169], v[6:7], v[2:3]
	v_mov_b32_e32 v60, v29
	v_pk_fma_f32 v[6:7], v[170:171], v[0:1], v[12:13] neg_lo:[1,0,0] neg_hi:[1,0,0]
	v_cvt_pk_bf16_f32 v4, v2, v3
	v_pk_fma_f32 v[6:7], v[168:169], v[2:3], v[6:7]
	v_pk_fma_f32 v[2:3], v[170:171], v[2:3], v[60:61]
	v_cvt_pk_bf16_f32 v5, v0, v1
	v_pk_fma_f32 v[0:1], v[168:169], v[0:1], v[2:3]
	v_cvt_pk_bf16_f32 v2, v6, v7
	v_cvt_pk_bf16_f32 v3, v0, v1
	ds_write2_b64 v184, v[4:5], v[2:3] offset0:48 offset1:82
	v_mov_b32_e32 v4, v30
	v_mov_b32_e32 v5, v62
	v_mov_b32_e32 v2, v46
	v_mov_b32_e32 v3, v14
	v_pk_fma_f32 v[4:5], v[170:171], v[6:7], v[4:5]
	v_pk_fma_f32 v[2:3], v[170:171], v[0:1], v[2:3] neg_lo:[1,0,0] neg_hi:[1,0,0]
	v_pk_fma_f32 v[0:1], v[168:169], v[0:1], v[4:5]
	v_mov_b32_e32 v14, v47
	v_pk_fma_f32 v[2:3], v[168:169], v[6:7], v[2:3]
	v_mov_b32_e32 v62, v31
	v_pk_fma_f32 v[6:7], v[170:171], v[0:1], v[14:15] neg_lo:[1,0,0] neg_hi:[1,0,0]
	v_cvt_pk_bf16_f32 v4, v2, v3
	v_pk_fma_f32 v[120:121], v[168:169], v[2:3], v[6:7]
	v_pk_fma_f32 v[2:3], v[170:171], v[2:3], v[62:63]
	v_cvt_pk_bf16_f32 v5, v0, v1
	v_pk_fma_f32 v[122:123], v[168:169], v[0:1], v[2:3]
	v_cvt_pk_bf16_f32 v0, v120, v121
	v_cvt_pk_bf16_f32 v1, v122, v123
	ds_write2_b64 v184, v[4:5], v[0:1] offset0:116 offset1:150
	ds_read_b128 v[0:3], v180 offset:40960
	ds_read_b128 v[16:19], v180 offset:40992
	s_waitcnt lgkmcnt(1)
	v_mfma_f32_32x32x16_bf16 v[0:15], v[0:3], v[88:91], 0
	s_waitcnt lgkmcnt(0)
	v_mfma_f32_32x32x16_bf16 v[0:15], v[16:19], v[92:95], v[0:15]
	ds_read_b128 v[16:19], v180 offset:41024
	ds_read_b128 v[20:23], v180 offset:41056
	s_waitcnt lgkmcnt(1)
	v_mfma_f32_32x32x16_bf16 v[0:15], v[16:19], v[96:99], v[0:15]
	s_waitcnt lgkmcnt(0)
	v_mfma_f32_32x32x16_bf16 v[0:15], v[20:23], v[80:83], v[0:15]
	ds_read_b128 v[16:19], v180 offset:41088
	ds_read_b128 v[20:23], v180 offset:41120
	s_waitcnt lgkmcnt(1)
	v_mfma_f32_32x32x16_bf16 v[0:15], v[16:19], v[100:103], v[0:15]
	s_waitcnt lgkmcnt(0)
	v_mfma_f32_32x32x16_bf16 v[0:15], v[20:23], v[104:107], v[0:15]
	ds_read_b128 v[16:19], v180 offset:41152
	ds_read_b128 v[20:23], v180 offset:41184
	s_waitcnt lgkmcnt(1)
	v_mfma_f32_32x32x16_bf16 v[0:15], v[16:19], v[108:111], v[0:15]
	s_waitcnt lgkmcnt(0)
	v_mfma_f32_32x32x16_bf16 v[0:15], v[20:23], v[84:87], v[0:15]
	s_and_saveexec_b64 s[26:27], s[0:1]
	s_cbranch_execz .LBB0_840
	s_or_b32 s20, s30, 0x50
	s_xor_b32 s31, s30, 0xaf
	s_lshl_b32 s20, s20, 4
	s_lshl_b32 s31, s31, 4
	s_and_b64 s[34:35], s[4:5], exec
	s_cselect_b32 s20, s20, s31
	v_lshl_add_u64 v[16:17], s[20:21], 2, v[174:175]
	s_cbranch_scc0 .Lys5_b
	s_nop 3
	global_store_dword v[16:17], v0, off
	global_store_dword v[16:17], v1, off offset:64
	global_store_dword v[16:17], v2, off offset:128
	global_store_dword v[16:17], v3, off offset:192
	global_store_dword v[16:17], v4, off offset:256
	global_store_dword v[16:17], v5, off offset:320
	global_store_dword v[16:17], v6, off offset:384
	global_store_dword v[16:17], v7, off offset:448
	global_store_dword v[16:17], v8, off offset:512
	global_store_dword v[16:17], v9, off offset:576
	global_store_dword v[16:17], v10, off offset:640
	global_store_dword v[16:17], v11, off offset:704
	global_store_dword v[16:17], v12, off offset:768
	global_store_dword v[16:17], v13, off offset:832
	global_store_dword v[16:17], v14, off offset:896
	global_store_dword v[16:17], v15, off offset:960
	s_branch .Lys5_e

.Lys5_e:
.LBB0_840:
	s_or_b64 exec, exec, s[26:27]
	s_waitcnt vmcnt(1)
	v_mfma_f32_32x32x16_bf16 v[32:47], v[116:119], v[64:67], 0
	v_mfma_f32_32x32x16_bf16 v[0:15], v[116:119], v[72:75], 0
	s_nop 10
	v_mov_b32_e32 v124, v32
	v_mfma_f32_32x32x16_bf16 v[16:31], v[116:119], v[68:71], 0
	v_mov_b32_e32 v125, v0
	v_mov_b32_e32 v0, v33
	v_mfma_f32_32x32x16_bf16 v[48:63], v[116:119], v[76:79], 0
	s_nop 8
	v_mov_b32_e32 v126, v16
	v_fma_f32 v116, -v170, v122, v124
	v_fma_f32 v117, -v171, v123, v125
	v_fma_f32 v116, v168, v120, v116
	v_fma_f32 v117, v169, v121, v117
	v_mov_b32_e32 v127, v48
	v_pk_fma_f32 v[118:119], v[170:171], v[120:121], v[126:127]
	v_mov_b32_e32 v48, v17
	v_pk_fma_f32 v[118:119], v[168:169], v[122:123], v[118:119]
	v_pk_fma_f32 v[16:17], v[170:171], v[116:117], v[48:49]
	v_pk_fma_f32 v[0:1], v[170:171], v[118:119], v[0:1] neg_lo:[1,0,0] neg_hi:[1,0,0]
	v_pk_fma_f32 v[16:17], v[168:169], v[118:119], v[16:17]
	v_pk_fma_f32 v[0:1], v[168:169], v[116:117], v[0:1]
	v_cvt_pk_bf16_f32 v120, v116, v117
	v_cvt_pk_bf16_f32 v121, v118, v119
	v_cvt_pk_bf16_f32 v32, v0, v1
	v_cvt_pk_bf16_f32 v33, v16, v17
	ds_write2_b64 v181, v[120:121], v[32:33] offset1:34
	v_mov_b32_e32 v32, v34
	v_mov_b32_e32 v33, v2
	v_mov_b32_e32 v48, v18
	v_mov_b32_e32 v49, v50
	v_pk_fma_f32 v[32:33], v[170:171], v[16:17], v[32:33] neg_lo:[1,0,0] neg_hi:[1,0,0]
	v_mov_b32_e32 v2, v35
	v_pk_fma_f32 v[32:33], v[168:169], v[0:1], v[32:33]
	v_pk_fma_f32 v[0:1], v[170:171], v[0:1], v[48:49]
	v_mov_b32_e32 v50, v19
	v_pk_fma_f32 v[0:1], v[168:169], v[16:17], v[0:1]
	v_pk_fma_f32 v[18:19], v[170:171], v[32:33], v[50:51]
	v_pk_fma_f32 v[2:3], v[170:171], v[0:1], v[2:3] neg_lo:[1,0,0] neg_hi:[1,0,0]
	v_cvt_pk_bf16_f32 v17, v0, v1
	v_pk_fma_f32 v[2:3], v[168:169], v[32:33], v[2:3]
	v_pk_fma_f32 v[0:1], v[168:169], v[0:1], v[18:19]
	v_cvt_pk_bf16_f32 v16, v32, v33
	v_cvt_pk_bf16_f32 v18, v2, v3
	v_cvt_pk_bf16_f32 v19, v0, v1
	ds_write2_b64 v181, v[16:17], v[18:19] offset0:68 offset1:102
	v_mov_b32_e32 v16, v36
	v_mov_b32_e32 v17, v4
	v_mov_b32_e32 v18, v20
	v_mov_b32_e32 v19, v52
	v_pk_fma_f32 v[16:17], v[170:171], v[0:1], v[16:17] neg_lo:[1,0,0] neg_hi:[1,0,0]
	v_mov_b32_e32 v4, v37
	v_pk_fma_f32 v[16:17], v[168:169], v[2:3], v[16:17]
	v_pk_fma_f32 v[2:3], v[170:171], v[2:3], v[18:19]
	v_mov_b32_e32 v52, v21
	v_pk_fma_f32 v[0:1], v[168:169], v[0:1], v[2:3]
	v_cvt_pk_bf16_f32 v2, v16, v17
	v_pk_fma_f32 v[4:5], v[170:171], v[0:1], v[4:5] neg_lo:[1,0,0] neg_hi:[1,0,0]
	v_cvt_pk_bf16_f32 v3, v0, v1
	v_pk_fma_f32 v[4:5], v[168:169], v[16:17], v[4:5]
	v_pk_fma_f32 v[16:17], v[170:171], v[16:17], v[52:53]
	s_nop 0
	v_pk_fma_f32 v[0:1], v[168:169], v[0:1], v[16:17]
	v_cvt_pk_bf16_f32 v16, v4, v5
	v_cvt_pk_bf16_f32 v17, v0, v1
	ds_write2_b64 v182, v[2:3], v[16:17] offset0:16 offset1:50
	v_mov_b32_e32 v2, v38
	v_mov_b32_e32 v3, v6
	v_mov_b32_e32 v16, v22
	v_mov_b32_e32 v17, v54
	v_pk_fma_f32 v[2:3], v[170:171], v[0:1], v[2:3] neg_lo:[1,0,0] neg_hi:[1,0,0]
	v_mov_b32_e32 v6, v39
	v_pk_fma_f32 v[2:3], v[168:169], v[4:5], v[2:3]
	v_pk_fma_f32 v[4:5], v[170:171], v[4:5], v[16:17]
	v_mov_b32_e32 v54, v23
	v_pk_fma_f32 v[0:1], v[168:169], v[0:1], v[4:5]
	v_cvt_pk_bf16_f32 v4, v2, v3
	v_pk_fma_f32 v[6:7], v[170:171], v[0:1], v[6:7] neg_lo:[1,0,0] neg_hi:[1,0,0]
	v_cvt_pk_bf16_f32 v5, v0, v1
	v_pk_fma_f32 v[6:7], v[168:169], v[2:3], v[6:7]
	v_pk_fma_f32 v[2:3], v[170:171], v[2:3], v[54:55]
	s_nop 0
	v_pk_fma_f32 v[0:1], v[168:169], v[0:1], v[2:3]
	v_cvt_pk_bf16_f32 v2, v6, v7
	v_cvt_pk_bf16_f32 v3, v0, v1
	ds_write2_b64 v182, v[4:5], v[2:3] offset0:84 offset1:118
	v_mov_b32_e32 v4, v24
	v_mov_b32_e32 v5, v56
	v_mov_b32_e32 v2, v40
	v_mov_b32_e32 v3, v8
	v_pk_fma_f32 v[4:5], v[170:171], v[6:7], v[4:5]
	v_pk_fma_f32 v[2:3], v[170:171], v[0:1], v[2:3] neg_lo:[1,0,0] neg_hi:[1,0,0]
	v_pk_fma_f32 v[0:1], v[168:169], v[0:1], v[4:5]
	v_mov_b32_e32 v8, v41
	v_pk_fma_f32 v[2:3], v[168:169], v[6:7], v[2:3]
	v_mov_b32_e32 v56, v25
	v_pk_fma_f32 v[6:7], v[170:171], v[0:1], v[8:9] neg_lo:[1,0,0] neg_hi:[1,0,0]
	v_cvt_pk_bf16_f32 v4, v2, v3
	v_pk_fma_f32 v[6:7], v[168:169], v[2:3], v[6:7]
	v_pk_fma_f32 v[2:3], v[170:171], v[2:3], v[56:57]
	v_cvt_pk_bf16_f32 v5, v0, v1
	v_pk_fma_f32 v[0:1], v[168:169], v[0:1], v[2:3]
	v_cvt_pk_bf16_f32 v2, v6, v7
	v_cvt_pk_bf16_f32 v3, v0, v1
	ds_write2_b64 v183, v[4:5], v[2:3] offset0:32 offset1:66
	v_mov_b32_e32 v4, v26
	v_mov_b32_e32 v5, v58
	v_mov_b32_e32 v2, v42
	v_mov_b32_e32 v3, v10
	v_pk_fma_f32 v[4:5], v[170:171], v[6:7], v[4:5]
	v_pk_fma_f32 v[2:3], v[170:171], v[0:1], v[2:3] neg_lo:[1,0,0] neg_hi:[1,0,0]
	v_pk_fma_f32 v[0:1], v[168:169], v[0:1], v[4:5]
	v_mov_b32_e32 v10, v43
	v_pk_fma_f32 v[2:3], v[168:169], v[6:7], v[2:3]
	v_mov_b32_e32 v58, v27
	v_pk_fma_f32 v[6:7], v[170:171], v[0:1], v[10:11] neg_lo:[1,0,0] neg_hi:[1,0,0]
	v_cvt_pk_bf16_f32 v4, v2, v3
	v_pk_fma_f32 v[6:7], v[168:169], v[2:3], v[6:7]
	v_pk_fma_f32 v[2:3], v[170:171], v[2:3], v[58:59]
	v_cvt_pk_bf16_f32 v5, v0, v1
	v_pk_fma_f32 v[0:1], v[168:169], v[0:1], v[2:3]
	v_cvt_pk_bf16_f32 v2, v6, v7
	v_cvt_pk_bf16_f32 v3, v0, v1
	ds_write2_b64 v183, v[4:5], v[2:3] offset0:100 offset1:134
	v_mov_b32_e32 v4, v28
	v_mov_b32_e32 v5, v60
	v_mov_b32_e32 v2, v44
	v_mov_b32_e32 v3, v12
	v_pk_fma_f32 v[4:5], v[170:171], v[6:7], v[4:5]
	v_pk_fma_f32 v[2:3], v[170:171], v[0:1], v[2:3] neg_lo:[1,0,0] neg_hi:[1,0,0]
	v_pk_fma_f32 v[0:1], v[168:169], v[0:1], v[4:5]
	v_mov_b32_e32 v12, v45
	v_pk_fma_f32 v[2:3], v[168:169], v[6:7], v[2:3]
	v_mov_b32_e32 v60, v29
	v_pk_fma_f32 v[6:7], v[170:171], v[0:1], v[12:13] neg_lo:[1,0,0] neg_hi:[1,0,0]
	v_cvt_pk_bf16_f32 v4, v2, v3
	v_pk_fma_f32 v[6:7], v[168:169], v[2:3], v[6:7]
	v_pk_fma_f32 v[2:3], v[170:171], v[2:3], v[60:61]
	v_cvt_pk_bf16_f32 v5, v0, v1
	v_pk_fma_f32 v[0:1], v[168:169], v[0:1], v[2:3]
	v_cvt_pk_bf16_f32 v2, v6, v7
	v_cvt_pk_bf16_f32 v3, v0, v1
	ds_write2_b64 v184, v[4:5], v[2:3] offset0:48 offset1:82
	v_mov_b32_e32 v4, v30
	v_mov_b32_e32 v5, v62
	v_mov_b32_e32 v2, v46
	v_mov_b32_e32 v3, v14
	v_pk_fma_f32 v[4:5], v[170:171], v[6:7], v[4:5]
	v_pk_fma_f32 v[2:3], v[170:171], v[0:1], v[2:3] neg_lo:[1,0,0] neg_hi:[1,0,0]
	v_pk_fma_f32 v[0:1], v[168:169], v[0:1], v[4:5]
	v_mov_b32_e32 v14, v47
	v_pk_fma_f32 v[2:3], v[168:169], v[6:7], v[2:3]
	v_mov_b32_e32 v62, v31
	v_pk_fma_f32 v[6:7], v[170:171], v[0:1], v[14:15] neg_lo:[1,0,0] neg_hi:[1,0,0]
	v_cvt_pk_bf16_f32 v4, v2, v3
	v_pk_fma_f32 v[116:117], v[168:169], v[2:3], v[6:7]
	v_pk_fma_f32 v[2:3], v[170:171], v[2:3], v[62:63]
	v_cvt_pk_bf16_f32 v5, v0, v1
	v_pk_fma_f32 v[118:119], v[168:169], v[0:1], v[2:3]
	v_cvt_pk_bf16_f32 v0, v116, v117
	v_cvt_pk_bf16_f32 v1, v118, v119
	ds_write2_b64 v184, v[4:5], v[0:1] offset0:116 offset1:150
	ds_read_b128 v[0:3], v180 offset:40960
	ds_read_b128 v[16:19], v180 offset:40992
	s_waitcnt lgkmcnt(1)
	v_mfma_f32_32x32x16_bf16 v[0:15], v[0:3], v[88:91], 0
	s_waitcnt lgkmcnt(0)
	v_mfma_f32_32x32x16_bf16 v[0:15], v[16:19], v[92:95], v[0:15]
	ds_read_b128 v[16:19], v180 offset:41024
	ds_read_b128 v[20:23], v180 offset:41056
	s_waitcnt lgkmcnt(1)
	v_mfma_f32_32x32x16_bf16 v[0:15], v[16:19], v[96:99], v[0:15]
	s_waitcnt lgkmcnt(0)
	v_mfma_f32_32x32x16_bf16 v[0:15], v[20:23], v[80:83], v[0:15]
	ds_read_b128 v[16:19], v180 offset:41088
	ds_read_b128 v[20:23], v180 offset:41120
	s_waitcnt lgkmcnt(1)
	v_mfma_f32_32x32x16_bf16 v[0:15], v[16:19], v[100:103], v[0:15]
	s_waitcnt lgkmcnt(0)
	v_mfma_f32_32x32x16_bf16 v[0:15], v[20:23], v[104:107], v[0:15]
	ds_read_b128 v[16:19], v180 offset:41152
	ds_read_b128 v[20:23], v180 offset:41184
	s_waitcnt lgkmcnt(1)
	v_mfma_f32_32x32x16_bf16 v[0:15], v[16:19], v[108:111], v[0:15]
	s_waitcnt lgkmcnt(0)
	v_mfma_f32_32x32x16_bf16 v[0:15], v[20:23], v[84:87], v[0:15]
	s_and_saveexec_b64 s[26:27], s[0:1]
	s_cbranch_execz .LBB0_842
	s_or_b32 s20, s30, 0x60
	s_xor_b32 s31, s30, 0x9f
	s_lshl_b32 s20, s20, 4
	s_lshl_b32 s31, s31, 4
	s_and_b64 s[34:35], s[4:5], exec
	s_cselect_b32 s20, s20, s31
	v_lshl_add_u64 v[16:17], s[20:21], 2, v[174:175]
	s_cbranch_scc0 .Lys6_b
	s_nop 3
	global_store_dword v[16:17], v0, off
	global_store_dword v[16:17], v1, off offset:64
	global_store_dword v[16:17], v2, off offset:128
	global_store_dword v[16:17], v3, off offset:192
	global_store_dword v[16:17], v4, off offset:256
	global_store_dword v[16:17], v5, off offset:320
	global_store_dword v[16:17], v6, off offset:384
	global_store_dword v[16:17], v7, off offset:448
	global_store_dword v[16:17], v8, off offset:512
	global_store_dword v[16:17], v9, off offset:576
	global_store_dword v[16:17], v10, off offset:640
	global_store_dword v[16:17], v11, off offset:704
	global_store_dword v[16:17], v12, off offset:768
	global_store_dword v[16:17], v13, off offset:832
	global_store_dword v[16:17], v14, off offset:896
	global_store_dword v[16:17], v15, off offset:960
	s_branch .Lys6_e

.Lys6_e:
.LBB0_842:
	s_or_b64 exec, exec, s[26:27]
	s_waitcnt vmcnt(0)
	v_mfma_f32_32x32x16_bf16 v[32:47], v[112:115], v[64:67], 0
	v_mfma_f32_32x32x16_bf16 v[0:15], v[112:115], v[72:75], 0
	s_nop 10
	v_mov_b32_e32 v120, v32
	v_mfma_f32_32x32x16_bf16 v[16:31], v[112:115], v[68:71], 0
	v_mov_b32_e32 v121, v0
	v_mov_b32_e32 v0, v33
	v_mfma_f32_32x32x16_bf16 v[48:63], v[112:115], v[76:79], 0
	s_nop 8
	v_mov_b32_e32 v122, v16
	v_fma_f32 v112, -v170, v118, v120
	v_fma_f32 v113, -v171, v119, v121
	v_fma_f32 v112, v168, v116, v112
	v_fma_f32 v113, v169, v117, v113
	v_mov_b32_e32 v123, v48
	v_pk_fma_f32 v[114:115], v[170:171], v[116:117], v[122:123]
	v_mov_b32_e32 v48, v17
	v_pk_fma_f32 v[114:115], v[168:169], v[118:119], v[114:115]
	v_pk_fma_f32 v[16:17], v[170:171], v[112:113], v[48:49]
	v_pk_fma_f32 v[0:1], v[170:171], v[114:115], v[0:1] neg_lo:[1,0,0] neg_hi:[1,0,0]
	v_pk_fma_f32 v[16:17], v[168:169], v[114:115], v[16:17]
	v_pk_fma_f32 v[0:1], v[168:169], v[112:113], v[0:1]
	v_cvt_pk_bf16_f32 v116, v112, v113
	v_cvt_pk_bf16_f32 v117, v114, v115
	v_cvt_pk_bf16_f32 v32, v0, v1
	v_cvt_pk_bf16_f32 v33, v16, v17
	ds_write2_b64 v181, v[116:117], v[32:33] offset1:34
	v_mov_b32_e32 v32, v34
	v_mov_b32_e32 v33, v2
	v_mov_b32_e32 v48, v18
	v_mov_b32_e32 v49, v50
	v_pk_fma_f32 v[32:33], v[170:171], v[16:17], v[32:33] neg_lo:[1,0,0] neg_hi:[1,0,0]
	v_mov_b32_e32 v2, v35
	v_pk_fma_f32 v[32:33], v[168:169], v[0:1], v[32:33]
	v_pk_fma_f32 v[0:1], v[170:171], v[0:1], v[48:49]
	v_mov_b32_e32 v50, v19
	v_pk_fma_f32 v[0:1], v[168:169], v[16:17], v[0:1]
	v_pk_fma_f32 v[18:19], v[170:171], v[32:33], v[50:51]
	v_pk_fma_f32 v[2:3], v[170:171], v[0:1], v[2:3] neg_lo:[1,0,0] neg_hi:[1,0,0]
	v_cvt_pk_bf16_f32 v17, v0, v1
	v_pk_fma_f32 v[2:3], v[168:169], v[32:33], v[2:3]
	v_pk_fma_f32 v[0:1], v[168:169], v[0:1], v[18:19]
	v_cvt_pk_bf16_f32 v16, v32, v33
	v_cvt_pk_bf16_f32 v18, v2, v3
	v_cvt_pk_bf16_f32 v19, v0, v1
	ds_write2_b64 v181, v[16:17], v[18:19] offset0:68 offset1:102
	v_mov_b32_e32 v16, v36
	v_mov_b32_e32 v17, v4
	v_mov_b32_e32 v18, v20
	v_mov_b32_e32 v19, v52
	v_pk_fma_f32 v[16:17], v[170:171], v[0:1], v[16:17] neg_lo:[1,0,0] neg_hi:[1,0,0]
	v_mov_b32_e32 v4, v37
	v_pk_fma_f32 v[16:17], v[168:169], v[2:3], v[16:17]
	v_pk_fma_f32 v[2:3], v[170:171], v[2:3], v[18:19]
	v_mov_b32_e32 v52, v21
	v_pk_fma_f32 v[0:1], v[168:169], v[0:1], v[2:3]
	v_cvt_pk_bf16_f32 v2, v16, v17
	v_pk_fma_f32 v[4:5], v[170:171], v[0:1], v[4:5] neg_lo:[1,0,0] neg_hi:[1,0,0]
	v_cvt_pk_bf16_f32 v3, v0, v1
	v_pk_fma_f32 v[4:5], v[168:169], v[16:17], v[4:5]
	v_pk_fma_f32 v[16:17], v[170:171], v[16:17], v[52:53]
	s_nop 0
	v_pk_fma_f32 v[0:1], v[168:169], v[0:1], v[16:17]
	v_cvt_pk_bf16_f32 v16, v4, v5
	v_cvt_pk_bf16_f32 v17, v0, v1
	ds_write2_b64 v182, v[2:3], v[16:17] offset0:16 offset1:50
	v_mov_b32_e32 v2, v38
	v_mov_b32_e32 v3, v6
	v_mov_b32_e32 v16, v22
	v_mov_b32_e32 v17, v54
	v_pk_fma_f32 v[2:3], v[170:171], v[0:1], v[2:3] neg_lo:[1,0,0] neg_hi:[1,0,0]
	v_mov_b32_e32 v6, v39
	v_pk_fma_f32 v[2:3], v[168:169], v[4:5], v[2:3]
	v_pk_fma_f32 v[4:5], v[170:171], v[4:5], v[16:17]
	v_mov_b32_e32 v54, v23
	v_pk_fma_f32 v[0:1], v[168:169], v[0:1], v[4:5]
	v_cvt_pk_bf16_f32 v4, v2, v3
	v_pk_fma_f32 v[6:7], v[170:171], v[0:1], v[6:7] neg_lo:[1,0,0] neg_hi:[1,0,0]
	v_cvt_pk_bf16_f32 v5, v0, v1
	v_pk_fma_f32 v[6:7], v[168:169], v[2:3], v[6:7]
	v_pk_fma_f32 v[2:3], v[170:171], v[2:3], v[54:55]
	s_nop 0
	v_pk_fma_f32 v[0:1], v[168:169], v[0:1], v[2:3]
	v_cvt_pk_bf16_f32 v2, v6, v7
	v_cvt_pk_bf16_f32 v3, v0, v1
	ds_write2_b64 v182, v[4:5], v[2:3] offset0:84 offset1:118
	v_mov_b32_e32 v4, v24
	v_mov_b32_e32 v5, v56
	v_mov_b32_e32 v2, v40
	v_mov_b32_e32 v3, v8
	v_pk_fma_f32 v[4:5], v[170:171], v[6:7], v[4:5]
	v_pk_fma_f32 v[2:3], v[170:171], v[0:1], v[2:3] neg_lo:[1,0,0] neg_hi:[1,0,0]
	v_pk_fma_f32 v[0:1], v[168:169], v[0:1], v[4:5]
	v_mov_b32_e32 v8, v41
	v_pk_fma_f32 v[2:3], v[168:169], v[6:7], v[2:3]
	v_mov_b32_e32 v56, v25
	v_pk_fma_f32 v[6:7], v[170:171], v[0:1], v[8:9] neg_lo:[1,0,0] neg_hi:[1,0,0]
	v_cvt_pk_bf16_f32 v4, v2, v3
	v_pk_fma_f32 v[6:7], v[168:169], v[2:3], v[6:7]
	v_pk_fma_f32 v[2:3], v[170:171], v[2:3], v[56:57]
	v_cvt_pk_bf16_f32 v5, v0, v1
	v_pk_fma_f32 v[0:1], v[168:169], v[0:1], v[2:3]
	v_cvt_pk_bf16_f32 v2, v6, v7
	v_cvt_pk_bf16_f32 v3, v0, v1
	ds_write2_b64 v183, v[4:5], v[2:3] offset0:32 offset1:66
	v_mov_b32_e32 v4, v26
	v_mov_b32_e32 v5, v58
	v_mov_b32_e32 v2, v42
	v_mov_b32_e32 v3, v10
	v_pk_fma_f32 v[4:5], v[170:171], v[6:7], v[4:5]
	v_pk_fma_f32 v[2:3], v[170:171], v[0:1], v[2:3] neg_lo:[1,0,0] neg_hi:[1,0,0]
	v_pk_fma_f32 v[0:1], v[168:169], v[0:1], v[4:5]
	v_mov_b32_e32 v10, v43
	v_pk_fma_f32 v[2:3], v[168:169], v[6:7], v[2:3]
	v_mov_b32_e32 v58, v27
	v_pk_fma_f32 v[6:7], v[170:171], v[0:1], v[10:11] neg_lo:[1,0,0] neg_hi:[1,0,0]
	v_cvt_pk_bf16_f32 v4, v2, v3
	v_pk_fma_f32 v[6:7], v[168:169], v[2:3], v[6:7]
	v_pk_fma_f32 v[2:3], v[170:171], v[2:3], v[58:59]
	v_cvt_pk_bf16_f32 v5, v0, v1
	v_pk_fma_f32 v[0:1], v[168:169], v[0:1], v[2:3]
	v_cvt_pk_bf16_f32 v2, v6, v7
	v_cvt_pk_bf16_f32 v3, v0, v1
	ds_write2_b64 v183, v[4:5], v[2:3] offset0:100 offset1:134
	v_mov_b32_e32 v4, v28
	v_mov_b32_e32 v5, v60
	v_mov_b32_e32 v2, v44
	v_mov_b32_e32 v3, v12
	v_pk_fma_f32 v[4:5], v[170:171], v[6:7], v[4:5]
	v_pk_fma_f32 v[2:3], v[170:171], v[0:1], v[2:3] neg_lo:[1,0,0] neg_hi:[1,0,0]
	v_pk_fma_f32 v[0:1], v[168:169], v[0:1], v[4:5]
	v_mov_b32_e32 v12, v45
	v_pk_fma_f32 v[2:3], v[168:169], v[6:7], v[2:3]
	v_mov_b32_e32 v60, v29
	v_pk_fma_f32 v[6:7], v[170:171], v[0:1], v[12:13] neg_lo:[1,0,0] neg_hi:[1,0,0]
	v_cvt_pk_bf16_f32 v4, v2, v3
	v_pk_fma_f32 v[6:7], v[168:169], v[2:3], v[6:7]
	v_pk_fma_f32 v[2:3], v[170:171], v[2:3], v[60:61]
	v_cvt_pk_bf16_f32 v5, v0, v1
	v_pk_fma_f32 v[0:1], v[168:169], v[0:1], v[2:3]
	v_cvt_pk_bf16_f32 v2, v6, v7
	v_cvt_pk_bf16_f32 v3, v0, v1
	ds_write2_b64 v184, v[4:5], v[2:3] offset0:48 offset1:82
	v_mov_b32_e32 v4, v30
	v_mov_b32_e32 v5, v62
	v_mov_b32_e32 v2, v46
	v_mov_b32_e32 v3, v14
	v_pk_fma_f32 v[4:5], v[170:171], v[6:7], v[4:5]
	v_pk_fma_f32 v[2:3], v[170:171], v[0:1], v[2:3] neg_lo:[1,0,0] neg_hi:[1,0,0]
	v_pk_fma_f32 v[0:1], v[168:169], v[0:1], v[4:5]
	v_mov_b32_e32 v14, v47
	v_pk_fma_f32 v[2:3], v[168:169], v[6:7], v[2:3]
	v_mov_b32_e32 v62, v31
	v_pk_fma_f32 v[6:7], v[170:171], v[0:1], v[14:15] neg_lo:[1,0,0] neg_hi:[1,0,0]
	v_cvt_pk_bf16_f32 v4, v2, v3
	v_pk_fma_f32 v[206:207], v[168:169], v[2:3], v[6:7]
	v_pk_fma_f32 v[2:3], v[170:171], v[2:3], v[62:63]
	v_cvt_pk_bf16_f32 v5, v0, v1
	v_pk_fma_f32 v[112:113], v[168:169], v[0:1], v[2:3]
	v_cvt_pk_bf16_f32 v0, v206, v207
	v_cvt_pk_bf16_f32 v1, v112, v113
	ds_write2_b64 v184, v[4:5], v[0:1] offset0:116 offset1:150
	ds_read_b128 v[0:3], v180 offset:40960
	ds_read_b128 v[16:19], v180 offset:40992
	s_waitcnt lgkmcnt(1)
	v_mfma_f32_32x32x16_bf16 v[0:15], v[0:3], v[88:91], 0
	s_waitcnt lgkmcnt(0)
	v_mfma_f32_32x32x16_bf16 v[0:15], v[16:19], v[92:95], v[0:15]
	ds_read_b128 v[16:19], v180 offset:41024
	ds_read_b128 v[20:23], v180 offset:41056
	s_waitcnt lgkmcnt(1)
	v_mfma_f32_32x32x16_bf16 v[0:15], v[16:19], v[96:99], v[0:15]
	s_waitcnt lgkmcnt(0)
	v_mfma_f32_32x32x16_bf16 v[0:15], v[20:23], v[80:83], v[0:15]
	ds_read_b128 v[16:19], v180 offset:41088
	ds_read_b128 v[20:23], v180 offset:41120
	s_waitcnt lgkmcnt(1)
	v_mfma_f32_32x32x16_bf16 v[0:15], v[16:19], v[100:103], v[0:15]
	s_waitcnt lgkmcnt(0)
	v_mfma_f32_32x32x16_bf16 v[0:15], v[20:23], v[104:107], v[0:15]
	ds_read_b128 v[16:19], v180 offset:41152
	ds_read_b128 v[20:23], v180 offset:41184
	s_waitcnt lgkmcnt(1)
	v_mfma_f32_32x32x16_bf16 v[0:15], v[16:19], v[108:111], v[0:15]
	s_waitcnt lgkmcnt(0)
	v_mfma_f32_32x32x16_bf16 v[0:15], v[20:23], v[84:87], v[0:15]
	s_and_saveexec_b64 s[26:27], s[0:1]
	s_cbranch_execz .LBB0_827
	s_or_b32 s20, s30, 0x70
	s_xor_b32 s31, s30, 0x8f
	s_lshl_b32 s20, s20, 4
	s_lshl_b32 s31, s31, 4
	s_and_b64 s[34:35], s[4:5], exec
	s_cselect_b32 s20, s20, s31
	v_lshl_add_u64 v[16:17], s[20:21], 2, v[174:175]
	s_cbranch_scc0 .Lys7_b
	s_nop 3
	global_store_dword v[16:17], v0, off
	global_store_dword v[16:17], v1, off offset:64
	global_store_dword v[16:17], v2, off offset:128
	global_store_dword v[16:17], v3, off offset:192
	global_store_dword v[16:17], v4, off offset:256
	global_store_dword v[16:17], v5, off offset:320
	global_store_dword v[16:17], v6, off offset:384
	global_store_dword v[16:17], v7, off offset:448
	global_store_dword v[16:17], v8, off offset:512
	global_store_dword v[16:17], v9, off offset:576
	global_store_dword v[16:17], v10, off offset:640
	global_store_dword v[16:17], v11, off offset:704
	global_store_dword v[16:17], v12, off offset:768
	global_store_dword v[16:17], v13, off offset:832
	global_store_dword v[16:17], v14, off offset:896
	global_store_dword v[16:17], v15, off offset:960
	s_branch .LBB0_827
.Lys7_b:
	s_nop 3
	global_store_dword v[16:17], v0, off
	global_store_dword v[16:17], v1, off offset:-64
	global_store_dword v[16:17], v2, off offset:-128
	global_store_dword v[16:17], v3, off offset:-192
	global_store_dword v[16:17], v4, off offset:-256
	global_store_dword v[16:17], v5, off offset:-320
	global_store_dword v[16:17], v6, off offset:-384
	global_store_dword v[16:17], v7, off offset:-448
	global_store_dword v[16:17], v8, off offset:-512
	global_store_dword v[16:17], v9, off offset:-576
	global_store_dword v[16:17], v10, off offset:-640
	global_store_dword v[16:17], v11, off offset:-704
	global_store_dword v[16:17], v12, off offset:-768
	global_store_dword v[16:17], v13, off offset:-832
	global_store_dword v[16:17], v14, off offset:-896
	global_store_dword v[16:17], v15, off offset:-960
	s_branch .LBB0_827

.LBB0_859:
	s_lshl_b32 s25, s50, 7
	v_or_b32_e32 v192, s25, v141
	s_nop 1
	v_lshlrev_b32_e32 v0, 10, v192
	v_xor_b32_e32 v1, 0x3fc00, v0
	v_cndmask_b32_e64 v0, v1, v0, s[4:5]
	v_lshlrev_b32_e32 v142, 1, v0
	v_lshl_add_u64 v[0:1], v[172:173], 0, v[142:143]
	global_load_dwordx4 v[48:51], v[0:1], off
	v_mov_b32_e32 v193, s25
	v_or_b32_e32 v0, 16, v192
	v_bitop3_b32 v1, v141, s31, v193 bitop3:0x36
	v_cndmask_b32_e64 v0, v1, v0, s[4:5]
	v_lshlrev_b32_e32 v142, 11, v0
	v_lshl_add_u64 v[0:1], v[172:173], 0, v[142:143]
	global_load_dwordx4 v[136:139], v[0:1], off
	v_add_u32_e32 v188, 0xa000, v165
	v_add_u32_e32 v189, 0xa800, v165
	v_add_u32_e32 v190, 0xb000, v165
	v_add_u32_e32 v191, 0xb800, v165
	s_waitcnt vmcnt(1)
	v_mfma_f32_32x32x16_bf16 v[32:47], v[48:51], v[64:67], 0
	s_nop 11
	v_mov_b32_e32 v116, v32
	v_mfma_f32_32x32x16_bf16 v[0:15], v[48:51], v[72:75], 0
	v_mfma_f32_32x32x16_bf16 v[16:31], v[48:51], v[68:71], 0
	s_nop 10
	v_mov_b32_e32 v117, v0
	v_fma_f32 v116, -v170, v112, v116
	v_fma_f32 v117, -v171, v113, v117
	v_mov_b32_e32 v0, v33
	v_mfma_f32_32x32x16_bf16 v[48:63], v[48:51], v[76:79], 0
	v_mov_b32_e32 v118, v16
	v_mov_b32_e32 v16, v34
	v_mov_b32_e32 v32, v18
	v_mov_b32_e32 v18, v36
	v_mov_b32_e32 v34, v20
	v_mov_b32_e32 v20, v38
	v_mov_b32_e32 v36, v22
	s_nop 4
	v_mov_b32_e32 v119, v48
	v_pk_fma_f32 v[118:119], v[170:171], v[114:115], v[118:119]
	v_mov_b32_e32 v48, v17
	v_pk_fma_f32 v[114:115], v[168:169], v[114:115], v[116:117]
	v_pk_fma_f32 v[112:113], v[168:169], v[112:113], v[118:119]
	v_pk_fma_f32 v[48:49], v[170:171], v[114:115], v[48:49]
	v_pk_fma_f32 v[0:1], v[170:171], v[112:113], v[0:1] neg_lo:[1,0,0] neg_hi:[1,0,0]
	v_mov_b32_e32 v17, v2
	v_mov_b32_e32 v33, v50
	v_pk_fma_f32 v[0:1], v[168:169], v[114:115], v[0:1]
	v_pk_fma_f32 v[48:49], v[168:169], v[112:113], v[48:49]
	v_pk_fma_f32 v[32:33], v[170:171], v[0:1], v[32:33]
	v_pk_fma_f32 v[16:17], v[170:171], v[48:49], v[16:17] neg_lo:[1,0,0] neg_hi:[1,0,0]
	v_mov_b32_e32 v2, v35
	v_mov_b32_e32 v50, v19
	v_cvt_pk_bf16_f32 v117, v112, v113
	v_cvt_pk_bf16_f32 v112, v0, v1
	v_pk_fma_f32 v[0:1], v[168:169], v[0:1], v[16:17]
	v_pk_fma_f32 v[16:17], v[168:169], v[48:49], v[32:33]
	v_cvt_pk_bf16_f32 v113, v48, v49
	v_pk_fma_f32 v[2:3], v[170:171], v[16:17], v[2:3] neg_lo:[1,0,0] neg_hi:[1,0,0]
	v_pk_fma_f32 v[48:49], v[170:171], v[0:1], v[50:51]
	v_mov_b32_e32 v19, v4
	v_mov_b32_e32 v35, v52
	v_cvt_pk_bf16_f32 v32, v0, v1
	v_pk_fma_f32 v[0:1], v[168:169], v[0:1], v[2:3]
	v_pk_fma_f32 v[2:3], v[168:169], v[16:17], v[48:49]
	v_pk_fma_f32 v[34:35], v[170:171], v[0:1], v[34:35]
	v_pk_fma_f32 v[18:19], v[170:171], v[2:3], v[18:19] neg_lo:[1,0,0] neg_hi:[1,0,0]
	v_mov_b32_e32 v4, v37
	v_mov_b32_e32 v52, v21
	v_cvt_pk_bf16_f32 v33, v16, v17
	v_cvt_pk_bf16_f32 v16, v0, v1
	v_cvt_pk_bf16_f32 v17, v2, v3
	v_pk_fma_f32 v[0:1], v[168:169], v[0:1], v[18:19]
	v_pk_fma_f32 v[2:3], v[168:169], v[2:3], v[34:35]
	v_pk_fma_f32 v[18:19], v[170:171], v[0:1], v[52:53]
	v_pk_fma_f32 v[4:5], v[170:171], v[2:3], v[4:5] neg_lo:[1,0,0] neg_hi:[1,0,0]
	v_mov_b32_e32 v21, v6
	v_mov_b32_e32 v37, v54
	ds_write2_b64 v188, v[32:33], v[16:17] offset0:68 offset1:102
	v_cvt_pk_bf16_f32 v16, v0, v1
	v_cvt_pk_bf16_f32 v17, v2, v3
	v_pk_fma_f32 v[0:1], v[168:169], v[0:1], v[4:5]
	v_pk_fma_f32 v[2:3], v[168:169], v[2:3], v[18:19]
	v_mov_b32_e32 v6, v39
	v_pk_fma_f32 v[18:19], v[170:171], v[2:3], v[20:21] neg_lo:[1,0,0] neg_hi:[1,0,0]
	v_pk_fma_f32 v[20:21], v[170:171], v[0:1], v[36:37]
	v_mov_b32_e32 v54, v23
	v_cvt_pk_bf16_f32 v4, v0, v1
	v_cvt_pk_bf16_f32 v5, v2, v3
	v_pk_fma_f32 v[0:1], v[168:169], v[0:1], v[18:19]
	v_pk_fma_f32 v[2:3], v[168:169], v[2:3], v[20:21]
	ds_write2_b64 v189, v[16:17], v[4:5] offset0:16 offset1:50
	v_pk_fma_f32 v[6:7], v[170:171], v[2:3], v[6:7] neg_lo:[1,0,0] neg_hi:[1,0,0]
	v_pk_fma_f32 v[16:17], v[170:171], v[0:1], v[54:55]
	v_mov_b32_e32 v22, v40
	v_mov_b32_e32 v23, v8
	v_mov_b32_e32 v38, v24
	v_mov_b32_e32 v39, v56
	v_cvt_pk_bf16_f32 v4, v0, v1
	v_cvt_pk_bf16_f32 v5, v2, v3
	v_pk_fma_f32 v[0:1], v[168:169], v[0:1], v[6:7]
	v_pk_fma_f32 v[2:3], v[168:169], v[2:3], v[16:17]
	v_pk_fma_f32 v[18:19], v[170:171], v[0:1], v[38:39]
	v_pk_fma_f32 v[16:17], v[170:171], v[2:3], v[22:23] neg_lo:[1,0,0] neg_hi:[1,0,0]
	v_mov_b32_e32 v8, v41
	v_mov_b32_e32 v56, v25
	v_cvt_pk_bf16_f32 v6, v0, v1
	v_cvt_pk_bf16_f32 v7, v2, v3
	v_pk_fma_f32 v[0:1], v[168:169], v[0:1], v[16:17]
	v_pk_fma_f32 v[2:3], v[168:169], v[2:3], v[18:19]
	ds_write2_b64 v189, v[4:5], v[6:7] offset0:84 offset1:118
	v_pk_fma_f32 v[6:7], v[170:171], v[2:3], v[8:9] neg_lo:[1,0,0] neg_hi:[1,0,0]
	v_pk_fma_f32 v[8:9], v[170:171], v[0:1], v[56:57]
	v_mov_b32_e32 v24, v42
	v_mov_b32_e32 v25, v10
	v_cvt_pk_bf16_f32 v4, v0, v1
	v_cvt_pk_bf16_f32 v5, v2, v3
	v_pk_fma_f32 v[0:1], v[168:169], v[0:1], v[6:7]
	v_pk_fma_f32 v[2:3], v[168:169], v[2:3], v[8:9]
	v_mov_b32_e32 v40, v26
	v_mov_b32_e32 v41, v58
	v_cvt_pk_bf16_f32 v6, v0, v1
	v_cvt_pk_bf16_f32 v7, v2, v3
	v_pk_fma_f32 v[8:9], v[170:171], v[2:3], v[24:25] neg_lo:[1,0,0] neg_hi:[1,0,0]
	ds_write2_b64 v190, v[4:5], v[6:7] offset0:32 offset1:66
	v_pk_fma_f32 v[4:5], v[168:169], v[0:1], v[8:9]
	v_pk_fma_f32 v[0:1], v[170:171], v[0:1], v[40:41]
	v_mov_b32_e32 v10, v43
	v_pk_fma_f32 v[0:1], v[168:169], v[2:3], v[0:1]
	v_mov_b32_e32 v58, v27
	v_pk_fma_f32 v[6:7], v[170:171], v[0:1], v[10:11] neg_lo:[1,0,0] neg_hi:[1,0,0]
	v_cvt_pk_bf16_f32 v2, v4, v5
	v_pk_fma_f32 v[6:7], v[168:169], v[4:5], v[6:7]
	v_pk_fma_f32 v[4:5], v[170:171], v[4:5], v[58:59]
	v_cvt_pk_bf16_f32 v3, v0, v1
	v_pk_fma_f32 v[0:1], v[168:169], v[0:1], v[4:5]
	v_cvt_pk_bf16_f32 v4, v6, v7
	v_cvt_pk_bf16_f32 v5, v0, v1
	ds_write2_b64 v190, v[2:3], v[4:5] offset0:100 offset1:134
	v_mov_b32_e32 v4, v28
	v_mov_b32_e32 v5, v60
	v_mov_b32_e32 v2, v44
	v_mov_b32_e32 v3, v12
	v_pk_fma_f32 v[4:5], v[170:171], v[6:7], v[4:5]
	v_pk_fma_f32 v[2:3], v[170:171], v[0:1], v[2:3] neg_lo:[1,0,0] neg_hi:[1,0,0]
	v_pk_fma_f32 v[0:1], v[168:169], v[0:1], v[4:5]
	v_mov_b32_e32 v12, v45
	v_pk_fma_f32 v[2:3], v[168:169], v[6:7], v[2:3]
	v_mov_b32_e32 v60, v29
	v_pk_fma_f32 v[6:7], v[170:171], v[0:1], v[12:13] neg_lo:[1,0,0] neg_hi:[1,0,0]
	v_cvt_pk_bf16_f32 v4, v2, v3
	v_pk_fma_f32 v[6:7], v[168:169], v[2:3], v[6:7]
	v_pk_fma_f32 v[2:3], v[170:171], v[2:3], v[60:61]
	v_cvt_pk_bf16_f32 v5, v0, v1
	v_pk_fma_f32 v[0:1], v[168:169], v[0:1], v[2:3]
	v_cvt_pk_bf16_f32 v2, v6, v7
	v_cvt_pk_bf16_f32 v3, v0, v1
	ds_write2_b64 v191, v[4:5], v[2:3] offset0:48 offset1:82
	v_mov_b32_e32 v4, v30
	v_mov_b32_e32 v5, v62
	v_mov_b32_e32 v2, v46
	v_mov_b32_e32 v3, v14
	v_pk_fma_f32 v[4:5], v[170:171], v[6:7], v[4:5]
	v_pk_fma_f32 v[2:3], v[170:171], v[0:1], v[2:3] neg_lo:[1,0,0] neg_hi:[1,0,0]
	v_pk_fma_f32 v[0:1], v[168:169], v[0:1], v[4:5]
	v_mov_b32_e32 v14, v47
	v_pk_fma_f32 v[2:3], v[168:169], v[6:7], v[2:3]
	v_mov_b32_e32 v62, v31
	v_pk_fma_f32 v[6:7], v[170:171], v[0:1], v[14:15] neg_lo:[1,0,0] neg_hi:[1,0,0]
	v_cvt_pk_bf16_f32 v4, v2, v3
	v_pk_fma_f32 v[176:177], v[168:169], v[2:3], v[6:7]
	v_pk_fma_f32 v[2:3], v[170:171], v[2:3], v[62:63]
	v_cvt_pk_bf16_f32 v116, v114, v115
	v_pk_fma_f32 v[178:179], v[168:169], v[0:1], v[2:3]
	v_cvt_pk_bf16_f32 v5, v0, v1
	v_cvt_pk_bf16_f32 v0, v176, v177
	v_cvt_pk_bf16_f32 v1, v178, v179
	ds_write2_b64 v188, v[116:117], v[112:113] offset1:34
	ds_write2_b64 v191, v[4:5], v[0:1] offset0:116 offset1:150
	ds_read_b128 v[0:3], v167 offset:40960
	ds_read_b128 v[16:19], v167 offset:40992
	s_waitcnt lgkmcnt(1)
	v_mfma_f32_32x32x16_bf16 v[0:15], v[0:3], v[80:83], 0
	v_or_b32_e32 v20, 32, v192
	v_bitop3_b32 v21, v141, s33, v193 bitop3:0x36
	v_cndmask_b32_e64 v20, v21, v20, s[4:5]
	v_lshlrev_b32_e32 v142, 11, v20
	ds_read_b128 v[20:23], v167 offset:41024
	v_lshl_add_u64 v[24:25], v[172:173], 0, v[142:143]
	s_waitcnt lgkmcnt(1)
	v_mfma_f32_32x32x16_bf16 v[0:15], v[16:19], v[84:87], v[0:15]
	v_or_b32_e32 v16, 48, v192
	v_bitop3_b32 v17, v141, s35, v193 bitop3:0x36
	v_cndmask_b32_e64 v16, v17, v16, s[4:5]
	v_lshlrev_b32_e32 v142, 11, v16
	ds_read_b128 v[16:19], v167 offset:41056
	v_lshl_add_u64 v[26:27], v[172:173], 0, v[142:143]
	global_load_dwordx4 v[132:135], v[24:25], off
	global_load_dwordx4 v[128:131], v[26:27], off
	s_waitcnt lgkmcnt(1)
	v_mfma_f32_32x32x16_bf16 v[0:15], v[20:23], v[88:91], v[0:15]
	v_or_b32_e32 v20, 64, v192
	v_bitop3_b32 v21, v141, s38, v193 bitop3:0x36
	v_cndmask_b32_e64 v20, v21, v20, s[4:5]
	v_lshlrev_b32_e32 v142, 11, v20
	ds_read_b128 v[20:23], v167 offset:41088
	v_lshl_add_u64 v[24:25], v[172:173], 0, v[142:143]
	s_waitcnt lgkmcnt(1)
	v_mfma_f32_32x32x16_bf16 v[0:15], v[16:19], v[92:95], v[0:15]
	v_or_b32_e32 v16, 0x50, v192
	v_bitop3_b32 v17, v141, s39, v193 bitop3:0x36
	v_cndmask_b32_e64 v16, v17, v16, s[4:5]
	v_lshlrev_b32_e32 v142, 11, v16
	ds_read_b128 v[16:19], v167 offset:41120
	v_lshl_add_u64 v[26:27], v[172:173], 0, v[142:143]
	global_load_dwordx4 v[124:127], v[24:25], off
	global_load_dwordx4 v[120:123], v[26:27], off
	s_waitcnt lgkmcnt(1)
	v_mfma_f32_32x32x16_bf16 v[0:15], v[20:23], v[96:99], v[0:15]
	v_or_b32_e32 v20, 0x60, v192
	v_bitop3_b32 v21, v141, s42, v193 bitop3:0x36
	v_cndmask_b32_e64 v20, v21, v20, s[4:5]
	v_lshlrev_b32_e32 v142, 11, v20
	v_lshl_add_u64 v[24:25], v[172:173], 0, v[142:143]
	ds_read_b128 v[20:23], v167 offset:41152
	s_waitcnt lgkmcnt(1)
	v_mfma_f32_32x32x16_bf16 v[0:15], v[16:19], v[100:103], v[0:15]
	v_or_b32_e32 v16, 0x70, v192
	v_bitop3_b32 v17, v141, s43, v193 bitop3:0x36
	v_cndmask_b32_e64 v16, v17, v16, s[4:5]
	v_lshlrev_b32_e32 v142, 11, v16
	v_lshl_add_u64 v[26:27], v[172:173], 0, v[142:143]
	ds_read_b128 v[16:19], v167 offset:41184
	global_load_dwordx4 v[116:119], v[24:25], off
	global_load_dwordx4 v[112:115], v[26:27], off
	s_waitcnt lgkmcnt(1)
	v_mfma_f32_32x32x16_bf16 v[0:15], v[20:23], v[104:107], v[0:15]
	s_waitcnt lgkmcnt(0)
	v_mfma_f32_32x32x16_bf16 v[0:15], v[16:19], v[108:111], v[0:15]
	s_and_saveexec_b64 s[26:27], s[0:1]
	s_cbranch_execz .LBB0_861
	s_mov_b32 s22, s25
	s_xor_b32 s56, s25, 0xff
	s_lshl_b32 s22, s22, 4
	s_lshl_b32 s56, s56, 4
	s_and_b64 s[50:51], s[4:5], exec
	s_cselect_b32 s22, s22, s56
	v_lshl_add_u64 v[16:17], s[22:23], 2, v[174:175]
	s_cbranch_scc0 .Lys8_b
	s_nop 3
	global_store_dword v[16:17], v0, off
	global_store_dword v[16:17], v1, off offset:64
	global_store_dword v[16:17], v2, off offset:128
	global_store_dword v[16:17], v3, off offset:192
	global_store_dword v[16:17], v4, off offset:256
	global_store_dword v[16:17], v5, off offset:320
	global_store_dword v[16:17], v6, off offset:384
	global_store_dword v[16:17], v7, off offset:448
	global_store_dword v[16:17], v8, off offset:512
	global_store_dword v[16:17], v9, off offset:576
	global_store_dword v[16:17], v10, off offset:640
	global_store_dword v[16:17], v11, off offset:704
	global_store_dword v[16:17], v12, off offset:768
	global_store_dword v[16:17], v13, off offset:832
	global_store_dword v[16:17], v14, off offset:896
	global_store_dword v[16:17], v15, off offset:960
	s_branch .Lys8_e

.Lys8_e:
.LBB0_861:
	s_or_b64 exec, exec, s[26:27]
	s_waitcnt vmcnt(6)
	v_mfma_f32_32x32x16_bf16 v[32:47], v[136:139], v[64:67], 0
	v_mfma_f32_32x32x16_bf16 v[0:15], v[136:139], v[72:75], 0
	s_nop 10
	v_mov_b32_e32 v192, v32
	v_mfma_f32_32x32x16_bf16 v[16:31], v[136:139], v[68:71], 0
	v_mov_b32_e32 v193, v0
	v_mov_b32_e32 v0, v33
	v_mfma_f32_32x32x16_bf16 v[48:63], v[136:139], v[76:79], 0
	s_nop 8
	v_mov_b32_e32 v194, v16
	v_fma_f32 v136, -v170, v178, v192
	v_fma_f32 v137, -v171, v179, v193
	v_fma_f32 v136, v168, v176, v136
	v_fma_f32 v137, v169, v177, v137
	v_mov_b32_e32 v195, v48
	v_pk_fma_f32 v[138:139], v[170:171], v[176:177], v[194:195]
	v_mov_b32_e32 v48, v17
	v_pk_fma_f32 v[138:139], v[168:169], v[178:179], v[138:139]
	v_pk_fma_f32 v[16:17], v[170:171], v[136:137], v[48:49]
	v_pk_fma_f32 v[0:1], v[170:171], v[138:139], v[0:1] neg_lo:[1,0,0] neg_hi:[1,0,0]
	v_pk_fma_f32 v[16:17], v[168:169], v[138:139], v[16:17]
	v_pk_fma_f32 v[0:1], v[168:169], v[136:137], v[0:1]
	v_cvt_pk_bf16_f32 v176, v136, v137
	v_cvt_pk_bf16_f32 v177, v138, v139
	v_cvt_pk_bf16_f32 v32, v0, v1
	v_cvt_pk_bf16_f32 v33, v16, v17
	ds_write2_b64 v188, v[176:177], v[32:33] offset1:34
	v_mov_b32_e32 v32, v34
	v_mov_b32_e32 v33, v2
	v_mov_b32_e32 v48, v18
	v_mov_b32_e32 v49, v50
	v_pk_fma_f32 v[32:33], v[170:171], v[16:17], v[32:33] neg_lo:[1,0,0] neg_hi:[1,0,0]
	v_mov_b32_e32 v2, v35
	v_pk_fma_f32 v[32:33], v[168:169], v[0:1], v[32:33]
	v_pk_fma_f32 v[0:1], v[170:171], v[0:1], v[48:49]
	v_mov_b32_e32 v50, v19
	v_pk_fma_f32 v[0:1], v[168:169], v[16:17], v[0:1]
	v_pk_fma_f32 v[18:19], v[170:171], v[32:33], v[50:51]
	v_pk_fma_f32 v[2:3], v[170:171], v[0:1], v[2:3] neg_lo:[1,0,0] neg_hi:[1,0,0]
	v_cvt_pk_bf16_f32 v17, v0, v1
	v_pk_fma_f32 v[2:3], v[168:169], v[32:33], v[2:3]
	v_pk_fma_f32 v[0:1], v[168:169], v[0:1], v[18:19]
	v_cvt_pk_bf16_f32 v16, v32, v33
	v_cvt_pk_bf16_f32 v18, v2, v3
	v_cvt_pk_bf16_f32 v19, v0, v1
	ds_write2_b64 v188, v[16:17], v[18:19] offset0:68 offset1:102
	v_mov_b32_e32 v16, v36
	v_mov_b32_e32 v17, v4
	v_mov_b32_e32 v18, v20
	v_mov_b32_e32 v19, v52
	v_pk_fma_f32 v[16:17], v[170:171], v[0:1], v[16:17] neg_lo:[1,0,0] neg_hi:[1,0,0]
	v_mov_b32_e32 v4, v37
	v_pk_fma_f32 v[16:17], v[168:169], v[2:3], v[16:17]
	v_pk_fma_f32 v[2:3], v[170:171], v[2:3], v[18:19]
	v_mov_b32_e32 v52, v21
	v_pk_fma_f32 v[0:1], v[168:169], v[0:1], v[2:3]
	v_cvt_pk_bf16_f32 v2, v16, v17
	v_pk_fma_f32 v[4:5], v[170:171], v[0:1], v[4:5] neg_lo:[1,0,0] neg_hi:[1,0,0]
	v_cvt_pk_bf16_f32 v3, v0, v1
	v_pk_fma_f32 v[4:5], v[168:169], v[16:17], v[4:5]
	v_pk_fma_f32 v[16:17], v[170:171], v[16:17], v[52:53]
	s_nop 0
	v_pk_fma_f32 v[0:1], v[168:169], v[0:1], v[16:17]
	v_cvt_pk_bf16_f32 v16, v4, v5
	v_cvt_pk_bf16_f32 v17, v0, v1
	ds_write2_b64 v189, v[2:3], v[16:17] offset0:16 offset1:50
	v_mov_b32_e32 v2, v38
	v_mov_b32_e32 v3, v6
	v_mov_b32_e32 v16, v22
	v_mov_b32_e32 v17, v54
	v_pk_fma_f32 v[2:3], v[170:171], v[0:1], v[2:3] neg_lo:[1,0,0] neg_hi:[1,0,0]
	v_mov_b32_e32 v6, v39
	v_pk_fma_f32 v[2:3], v[168:169], v[4:5], v[2:3]
	v_pk_fma_f32 v[4:5], v[170:171], v[4:5], v[16:17]
	v_mov_b32_e32 v54, v23
	v_pk_fma_f32 v[0:1], v[168:169], v[0:1], v[4:5]
	v_cvt_pk_bf16_f32 v4, v2, v3
	v_pk_fma_f32 v[6:7], v[170:171], v[0:1], v[6:7] neg_lo:[1,0,0] neg_hi:[1,0,0]
	v_cvt_pk_bf16_f32 v5, v0, v1
	v_pk_fma_f32 v[6:7], v[168:169], v[2:3], v[6:7]
	v_pk_fma_f32 v[2:3], v[170:171], v[2:3], v[54:55]
	s_nop 0
	v_pk_fma_f32 v[0:1], v[168:169], v[0:1], v[2:3]
	v_cvt_pk_bf16_f32 v2, v6, v7
	v_cvt_pk_bf16_f32 v3, v0, v1
	ds_write2_b64 v189, v[4:5], v[2:3] offset0:84 offset1:118
	v_mov_b32_e32 v4, v24
	v_mov_b32_e32 v5, v56
	v_mov_b32_e32 v2, v40
	v_mov_b32_e32 v3, v8
	v_pk_fma_f32 v[4:5], v[170:171], v[6:7], v[4:5]
	v_pk_fma_f32 v[2:3], v[170:171], v[0:1], v[2:3] neg_lo:[1,0,0] neg_hi:[1,0,0]
	v_pk_fma_f32 v[0:1], v[168:169], v[0:1], v[4:5]
	v_mov_b32_e32 v8, v41
	v_pk_fma_f32 v[2:3], v[168:169], v[6:7], v[2:3]
	v_mov_b32_e32 v56, v25
	v_pk_fma_f32 v[6:7], v[170:171], v[0:1], v[8:9] neg_lo:[1,0,0] neg_hi:[1,0,0]
	v_cvt_pk_bf16_f32 v4, v2, v3
	v_pk_fma_f32 v[6:7], v[168:169], v[2:3], v[6:7]
	v_pk_fma_f32 v[2:3], v[170:171], v[2:3], v[56:57]
	v_cvt_pk_bf16_f32 v5, v0, v1
	v_pk_fma_f32 v[0:1], v[168:169], v[0:1], v[2:3]
	v_cvt_pk_bf16_f32 v2, v6, v7
	v_cvt_pk_bf16_f32 v3, v0, v1
	ds_write2_b64 v190, v[4:5], v[2:3] offset0:32 offset1:66
	v_mov_b32_e32 v4, v26
	v_mov_b32_e32 v5, v58
	v_mov_b32_e32 v2, v42
	v_mov_b32_e32 v3, v10
	v_pk_fma_f32 v[4:5], v[170:171], v[6:7], v[4:5]
	v_pk_fma_f32 v[2:3], v[170:171], v[0:1], v[2:3] neg_lo:[1,0,0] neg_hi:[1,0,0]
	v_pk_fma_f32 v[0:1], v[168:169], v[0:1], v[4:5]
	v_mov_b32_e32 v10, v43
	v_pk_fma_f32 v[2:3], v[168:169], v[6:7], v[2:3]
	v_mov_b32_e32 v58, v27
	v_pk_fma_f32 v[6:7], v[170:171], v[0:1], v[10:11] neg_lo:[1,0,0] neg_hi:[1,0,0]
	v_cvt_pk_bf16_f32 v4, v2, v3
	v_pk_fma_f32 v[6:7], v[168:169], v[2:3], v[6:7]
	v_pk_fma_f32 v[2:3], v[170:171], v[2:3], v[58:59]
	v_cvt_pk_bf16_f32 v5, v0, v1
	v_pk_fma_f32 v[0:1], v[168:169], v[0:1], v[2:3]
	v_cvt_pk_bf16_f32 v2, v6, v7
	v_cvt_pk_bf16_f32 v3, v0, v1
	ds_write2_b64 v190, v[4:5], v[2:3] offset0:100 offset1:134
	v_mov_b32_e32 v4, v28
	v_mov_b32_e32 v5, v60
	v_mov_b32_e32 v2, v44
	v_mov_b32_e32 v3, v12
	v_pk_fma_f32 v[4:5], v[170:171], v[6:7], v[4:5]
	v_pk_fma_f32 v[2:3], v[170:171], v[0:1], v[2:3] neg_lo:[1,0,0] neg_hi:[1,0,0]
	v_pk_fma_f32 v[0:1], v[168:169], v[0:1], v[4:5]
	v_mov_b32_e32 v12, v45
	v_pk_fma_f32 v[2:3], v[168:169], v[6:7], v[2:3]
	v_mov_b32_e32 v60, v29
	v_pk_fma_f32 v[6:7], v[170:171], v[0:1], v[12:13] neg_lo:[1,0,0] neg_hi:[1,0,0]
	v_cvt_pk_bf16_f32 v4, v2, v3
	v_pk_fma_f32 v[6:7], v[168:169], v[2:3], v[6:7]
	v_pk_fma_f32 v[2:3], v[170:171], v[2:3], v[60:61]
	v_cvt_pk_bf16_f32 v5, v0, v1
	v_pk_fma_f32 v[0:1], v[168:169], v[0:1], v[2:3]
	v_cvt_pk_bf16_f32 v2, v6, v7
	v_cvt_pk_bf16_f32 v3, v0, v1
	ds_write2_b64 v191, v[4:5], v[2:3] offset0:48 offset1:82
	v_mov_b32_e32 v4, v30
	v_mov_b32_e32 v5, v62
	v_mov_b32_e32 v2, v46
	v_mov_b32_e32 v3, v14
	v_pk_fma_f32 v[4:5], v[170:171], v[6:7], v[4:5]
	v_pk_fma_f32 v[2:3], v[170:171], v[0:1], v[2:3] neg_lo:[1,0,0] neg_hi:[1,0,0]
	v_pk_fma_f32 v[0:1], v[168:169], v[0:1], v[4:5]
	v_mov_b32_e32 v14, v47
	v_pk_fma_f32 v[2:3], v[168:169], v[6:7], v[2:3]
	v_mov_b32_e32 v62, v31
	v_pk_fma_f32 v[6:7], v[170:171], v[0:1], v[14:15] neg_lo:[1,0,0] neg_hi:[1,0,0]
	v_cvt_pk_bf16_f32 v4, v2, v3
	v_pk_fma_f32 v[136:137], v[168:169], v[2:3], v[6:7]
	v_pk_fma_f32 v[2:3], v[170:171], v[2:3], v[62:63]
	v_cvt_pk_bf16_f32 v5, v0, v1
	v_pk_fma_f32 v[138:139], v[168:169], v[0:1], v[2:3]
	v_cvt_pk_bf16_f32 v0, v136, v137
	v_cvt_pk_bf16_f32 v1, v138, v139
	ds_write2_b64 v191, v[4:5], v[0:1] offset0:116 offset1:150
	ds_read_b128 v[0:3], v167 offset:40960
	ds_read_b128 v[16:19], v167 offset:40992
	s_waitcnt lgkmcnt(1)
	v_mfma_f32_32x32x16_bf16 v[0:15], v[0:3], v[80:83], 0
	s_waitcnt lgkmcnt(0)
	v_mfma_f32_32x32x16_bf16 v[0:15], v[16:19], v[84:87], v[0:15]
	ds_read_b128 v[16:19], v167 offset:41024
	ds_read_b128 v[20:23], v167 offset:41056
	s_waitcnt lgkmcnt(1)
	v_mfma_f32_32x32x16_bf16 v[0:15], v[16:19], v[88:91], v[0:15]
	s_waitcnt lgkmcnt(0)
	v_mfma_f32_32x32x16_bf16 v[0:15], v[20:23], v[92:95], v[0:15]
	ds_read_b128 v[16:19], v167 offset:41088
	ds_read_b128 v[20:23], v167 offset:41120
	s_waitcnt lgkmcnt(1)
	v_mfma_f32_32x32x16_bf16 v[0:15], v[16:19], v[96:99], v[0:15]
	s_waitcnt lgkmcnt(0)
	v_mfma_f32_32x32x16_bf16 v[0:15], v[20:23], v[100:103], v[0:15]
	ds_read_b128 v[16:19], v167 offset:41152
	ds_read_b128 v[20:23], v167 offset:41184
	s_waitcnt lgkmcnt(1)
	v_mfma_f32_32x32x16_bf16 v[0:15], v[16:19], v[104:107], v[0:15]
	s_waitcnt lgkmcnt(0)
	v_mfma_f32_32x32x16_bf16 v[0:15], v[20:23], v[108:111], v[0:15]
	s_and_saveexec_b64 s[26:27], s[0:1]
	s_cbranch_execz .LBB0_863
	s_or_b32 s22, s25, 0x10
	s_xor_b32 s56, s25, 0xef
	s_lshl_b32 s22, s22, 4
	s_lshl_b32 s56, s56, 4
	s_and_b64 s[50:51], s[4:5], exec
	s_cselect_b32 s22, s22, s56
	v_lshl_add_u64 v[16:17], s[22:23], 2, v[174:175]
	s_cbranch_scc0 .Lys9_b
	s_nop 3
	global_store_dword v[16:17], v0, off
	global_store_dword v[16:17], v1, off offset:64
	global_store_dword v[16:17], v2, off offset:128
	global_store_dword v[16:17], v3, off offset:192
	global_store_dword v[16:17], v4, off offset:256
	global_store_dword v[16:17], v5, off offset:320
	global_store_dword v[16:17], v6, off offset:384
	global_store_dword v[16:17], v7, off offset:448
	global_store_dword v[16:17], v8, off offset:512
	global_store_dword v[16:17], v9, off offset:576
	global_store_dword v[16:17], v10, off offset:640
	global_store_dword v[16:17], v11, off offset:704
	global_store_dword v[16:17], v12, off offset:768
	global_store_dword v[16:17], v13, off offset:832
	global_store_dword v[16:17], v14, off offset:896
	global_store_dword v[16:17], v15, off offset:960
	s_branch .Lys9_e

.Lys9_e:
.LBB0_863:
	s_or_b64 exec, exec, s[26:27]
	s_waitcnt vmcnt(5)
	v_mfma_f32_32x32x16_bf16 v[32:47], v[132:135], v[64:67], 0
	v_mfma_f32_32x32x16_bf16 v[0:15], v[132:135], v[72:75], 0
	s_nop 10
	v_mov_b32_e32 v176, v32
	v_mfma_f32_32x32x16_bf16 v[16:31], v[132:135], v[68:71], 0
	v_mov_b32_e32 v177, v0
	v_mov_b32_e32 v0, v33
	v_mfma_f32_32x32x16_bf16 v[48:63], v[132:135], v[76:79], 0
	s_nop 8
	v_mov_b32_e32 v178, v16
	v_fma_f32 v132, -v170, v138, v176
	v_fma_f32 v133, -v171, v139, v177
	v_fma_f32 v132, v168, v136, v132
	v_fma_f32 v133, v169, v137, v133
	v_mov_b32_e32 v179, v48
	v_pk_fma_f32 v[134:135], v[170:171], v[136:137], v[178:179]
	v_mov_b32_e32 v48, v17
	v_pk_fma_f32 v[134:135], v[168:169], v[138:139], v[134:135]
	v_pk_fma_f32 v[16:17], v[170:171], v[132:133], v[48:49]
	v_pk_fma_f32 v[0:1], v[170:171], v[134:135], v[0:1] neg_lo:[1,0,0] neg_hi:[1,0,0]
	v_pk_fma_f32 v[16:17], v[168:169], v[134:135], v[16:17]
	v_pk_fma_f32 v[0:1], v[168:169], v[132:133], v[0:1]
	v_cvt_pk_bf16_f32 v136, v132, v133
	v_cvt_pk_bf16_f32 v137, v134, v135
	v_cvt_pk_bf16_f32 v32, v0, v1
	v_cvt_pk_bf16_f32 v33, v16, v17
	ds_write2_b64 v188, v[136:137], v[32:33] offset1:34
	v_mov_b32_e32 v32, v34
	v_mov_b32_e32 v33, v2
	v_mov_b32_e32 v48, v18
	v_mov_b32_e32 v49, v50
	v_pk_fma_f32 v[32:33], v[170:171], v[16:17], v[32:33] neg_lo:[1,0,0] neg_hi:[1,0,0]
	v_mov_b32_e32 v2, v35
	v_pk_fma_f32 v[32:33], v[168:169], v[0:1], v[32:33]
	v_pk_fma_f32 v[0:1], v[170:171], v[0:1], v[48:49]
	v_mov_b32_e32 v50, v19
	v_pk_fma_f32 v[0:1], v[168:169], v[16:17], v[0:1]
	v_pk_fma_f32 v[18:19], v[170:171], v[32:33], v[50:51]
	v_pk_fma_f32 v[2:3], v[170:171], v[0:1], v[2:3] neg_lo:[1,0,0] neg_hi:[1,0,0]
	v_cvt_pk_bf16_f32 v17, v0, v1
	v_pk_fma_f32 v[2:3], v[168:169], v[32:33], v[2:3]
	v_pk_fma_f32 v[0:1], v[168:169], v[0:1], v[18:19]
	v_cvt_pk_bf16_f32 v16, v32, v33
	v_cvt_pk_bf16_f32 v18, v2, v3
	v_cvt_pk_bf16_f32 v19, v0, v1
	ds_write2_b64 v188, v[16:17], v[18:19] offset0:68 offset1:102
	v_mov_b32_e32 v16, v36
	v_mov_b32_e32 v17, v4
	v_mov_b32_e32 v18, v20
	v_mov_b32_e32 v19, v52
	v_pk_fma_f32 v[16:17], v[170:171], v[0:1], v[16:17] neg_lo:[1,0,0] neg_hi:[1,0,0]
	v_mov_b32_e32 v4, v37
	v_pk_fma_f32 v[16:17], v[168:169], v[2:3], v[16:17]
	v_pk_fma_f32 v[2:3], v[170:171], v[2:3], v[18:19]
	v_mov_b32_e32 v52, v21
	v_pk_fma_f32 v[0:1], v[168:169], v[0:1], v[2:3]
	v_cvt_pk_bf16_f32 v2, v16, v17
	v_pk_fma_f32 v[4:5], v[170:171], v[0:1], v[4:5] neg_lo:[1,0,0] neg_hi:[1,0,0]
	v_cvt_pk_bf16_f32 v3, v0, v1
	v_pk_fma_f32 v[4:5], v[168:169], v[16:17], v[4:5]
	v_pk_fma_f32 v[16:17], v[170:171], v[16:17], v[52:53]
	s_nop 0
	v_pk_fma_f32 v[0:1], v[168:169], v[0:1], v[16:17]
	v_cvt_pk_bf16_f32 v16, v4, v5
	v_cvt_pk_bf16_f32 v17, v0, v1
	ds_write2_b64 v189, v[2:3], v[16:17] offset0:16 offset1:50
	v_mov_b32_e32 v2, v38
	v_mov_b32_e32 v3, v6
	v_mov_b32_e32 v16, v22
	v_mov_b32_e32 v17, v54
	v_pk_fma_f32 v[2:3], v[170:171], v[0:1], v[2:3] neg_lo:[1,0,0] neg_hi:[1,0,0]
	v_mov_b32_e32 v6, v39
	v_pk_fma_f32 v[2:3], v[168:169], v[4:5], v[2:3]
	v_pk_fma_f32 v[4:5], v[170:171], v[4:5], v[16:17]
	v_mov_b32_e32 v54, v23
	v_pk_fma_f32 v[0:1], v[168:169], v[0:1], v[4:5]
	v_cvt_pk_bf16_f32 v4, v2, v3
	v_pk_fma_f32 v[6:7], v[170:171], v[0:1], v[6:7] neg_lo:[1,0,0] neg_hi:[1,0,0]
	v_cvt_pk_bf16_f32 v5, v0, v1
	v_pk_fma_f32 v[6:7], v[168:169], v[2:3], v[6:7]
	v_pk_fma_f32 v[2:3], v[170:171], v[2:3], v[54:55]
	s_nop 0
	v_pk_fma_f32 v[0:1], v[168:169], v[0:1], v[2:3]
	v_cvt_pk_bf16_f32 v2, v6, v7
	v_cvt_pk_bf16_f32 v3, v0, v1
	ds_write2_b64 v189, v[4:5], v[2:3] offset0:84 offset1:118
	v_mov_b32_e32 v4, v24
	v_mov_b32_e32 v5, v56
	v_mov_b32_e32 v2, v40
	v_mov_b32_e32 v3, v8
	v_pk_fma_f32 v[4:5], v[170:171], v[6:7], v[4:5]
	v_pk_fma_f32 v[2:3], v[170:171], v[0:1], v[2:3] neg_lo:[1,0,0] neg_hi:[1,0,0]
	v_pk_fma_f32 v[0:1], v[168:169], v[0:1], v[4:5]
	v_mov_b32_e32 v8, v41
	v_pk_fma_f32 v[2:3], v[168:169], v[6:7], v[2:3]
	v_mov_b32_e32 v56, v25
	v_pk_fma_f32 v[6:7], v[170:171], v[0:1], v[8:9] neg_lo:[1,0,0] neg_hi:[1,0,0]
	v_cvt_pk_bf16_f32 v4, v2, v3
	v_pk_fma_f32 v[6:7], v[168:169], v[2:3], v[6:7]
	v_pk_fma_f32 v[2:3], v[170:171], v[2:3], v[56:57]
	v_cvt_pk_bf16_f32 v5, v0, v1
	v_pk_fma_f32 v[0:1], v[168:169], v[0:1], v[2:3]
	v_cvt_pk_bf16_f32 v2, v6, v7
	v_cvt_pk_bf16_f32 v3, v0, v1
	ds_write2_b64 v190, v[4:5], v[2:3] offset0:32 offset1:66
	v_mov_b32_e32 v4, v26
	v_mov_b32_e32 v5, v58
	v_mov_b32_e32 v2, v42
	v_mov_b32_e32 v3, v10
	v_pk_fma_f32 v[4:5], v[170:171], v[6:7], v[4:5]
	v_pk_fma_f32 v[2:3], v[170:171], v[0:1], v[2:3] neg_lo:[1,0,0] neg_hi:[1,0,0]
	v_pk_fma_f32 v[0:1], v[168:169], v[0:1], v[4:5]
	v_mov_b32_e32 v10, v43
	v_pk_fma_f32 v[2:3], v[168:169], v[6:7], v[2:3]
	v_mov_b32_e32 v58, v27
	v_pk_fma_f32 v[6:7], v[170:171], v[0:1], v[10:11] neg_lo:[1,0,0] neg_hi:[1,0,0]
	v_cvt_pk_bf16_f32 v4, v2, v3
	v_pk_fma_f32 v[6:7], v[168:169], v[2:3], v[6:7]
	v_pk_fma_f32 v[2:3], v[170:171], v[2:3], v[58:59]
	v_cvt_pk_bf16_f32 v5, v0, v1
	v_pk_fma_f32 v[0:1], v[168:169], v[0:1], v[2:3]
	v_cvt_pk_bf16_f32 v2, v6, v7
	v_cvt_pk_bf16_f32 v3, v0, v1
	ds_write2_b64 v190, v[4:5], v[2:3] offset0:100 offset1:134
	v_mov_b32_e32 v4, v28
	v_mov_b32_e32 v5, v60
	v_mov_b32_e32 v2, v44
	v_mov_b32_e32 v3, v12
	v_pk_fma_f32 v[4:5], v[170:171], v[6:7], v[4:5]
	v_pk_fma_f32 v[2:3], v[170:171], v[0:1], v[2:3] neg_lo:[1,0,0] neg_hi:[1,0,0]
	v_pk_fma_f32 v[0:1], v[168:169], v[0:1], v[4:5]
	v_mov_b32_e32 v12, v45
	v_pk_fma_f32 v[2:3], v[168:169], v[6:7], v[2:3]
	v_mov_b32_e32 v60, v29
	v_pk_fma_f32 v[6:7], v[170:171], v[0:1], v[12:13] neg_lo:[1,0,0] neg_hi:[1,0,0]
	v_cvt_pk_bf16_f32 v4, v2, v3
	v_pk_fma_f32 v[6:7], v[168:169], v[2:3], v[6:7]
	v_pk_fma_f32 v[2:3], v[170:171], v[2:3], v[60:61]
	v_cvt_pk_bf16_f32 v5, v0, v1
	v_pk_fma_f32 v[0:1], v[168:169], v[0:1], v[2:3]
	v_cvt_pk_bf16_f32 v2, v6, v7
	v_cvt_pk_bf16_f32 v3, v0, v1
	ds_write2_b64 v191, v[4:5], v[2:3] offset0:48 offset1:82
	v_mov_b32_e32 v4, v30
	v_mov_b32_e32 v5, v62
	v_mov_b32_e32 v2, v46
	v_mov_b32_e32 v3, v14
	v_pk_fma_f32 v[4:5], v[170:171], v[6:7], v[4:5]
	v_pk_fma_f32 v[2:3], v[170:171], v[0:1], v[2:3] neg_lo:[1,0,0] neg_hi:[1,0,0]
	v_pk_fma_f32 v[0:1], v[168:169], v[0:1], v[4:5]
	v_mov_b32_e32 v14, v47
	v_pk_fma_f32 v[2:3], v[168:169], v[6:7], v[2:3]
	v_mov_b32_e32 v62, v31
	v_pk_fma_f32 v[6:7], v[170:171], v[0:1], v[14:15] neg_lo:[1,0,0] neg_hi:[1,0,0]
	v_cvt_pk_bf16_f32 v4, v2, v3
	v_pk_fma_f32 v[132:133], v[168:169], v[2:3], v[6:7]
	v_pk_fma_f32 v[2:3], v[170:171], v[2:3], v[62:63]
	v_cvt_pk_bf16_f32 v5, v0, v1
	v_pk_fma_f32 v[134:135], v[168:169], v[0:1], v[2:3]
	v_cvt_pk_bf16_f32 v0, v132, v133
	v_cvt_pk_bf16_f32 v1, v134, v135
	ds_write2_b64 v191, v[4:5], v[0:1] offset0:116 offset1:150
	ds_read_b128 v[0:3], v167 offset:40960
	ds_read_b128 v[16:19], v167 offset:40992
	s_waitcnt lgkmcnt(1)
	v_mfma_f32_32x32x16_bf16 v[0:15], v[0:3], v[80:83], 0
	s_waitcnt lgkmcnt(0)
	v_mfma_f32_32x32x16_bf16 v[0:15], v[16:19], v[84:87], v[0:15]
	ds_read_b128 v[16:19], v167 offset:41024
	ds_read_b128 v[20:23], v167 offset:41056
	s_waitcnt lgkmcnt(1)
	v_mfma_f32_32x32x16_bf16 v[0:15], v[16:19], v[88:91], v[0:15]
	s_waitcnt lgkmcnt(0)
	v_mfma_f32_32x32x16_bf16 v[0:15], v[20:23], v[92:95], v[0:15]
	ds_read_b128 v[16:19], v167 offset:41088
	ds_read_b128 v[20:23], v167 offset:41120
	s_waitcnt lgkmcnt(1)
	v_mfma_f32_32x32x16_bf16 v[0:15], v[16:19], v[96:99], v[0:15]
	s_waitcnt lgkmcnt(0)
	v_mfma_f32_32x32x16_bf16 v[0:15], v[20:23], v[100:103], v[0:15]
	ds_read_b128 v[16:19], v167 offset:41152
	ds_read_b128 v[20:23], v167 offset:41184
	s_waitcnt lgkmcnt(1)
	v_mfma_f32_32x32x16_bf16 v[0:15], v[16:19], v[104:107], v[0:15]
	s_waitcnt lgkmcnt(0)
	v_mfma_f32_32x32x16_bf16 v[0:15], v[20:23], v[108:111], v[0:15]
	s_and_saveexec_b64 s[26:27], s[0:1]
	s_cbranch_execz .LBB0_865
	s_or_b32 s22, s25, 0x20
	s_xor_b32 s56, s25, 0xdf
	s_lshl_b32 s22, s22, 4
	s_lshl_b32 s56, s56, 4
	s_and_b64 s[50:51], s[4:5], exec
	s_cselect_b32 s22, s22, s56
	v_lshl_add_u64 v[16:17], s[22:23], 2, v[174:175]
	s_cbranch_scc0 .Lys10_b
	s_nop 3
	global_store_dword v[16:17], v0, off
	global_store_dword v[16:17], v1, off offset:64
	global_store_dword v[16:17], v2, off offset:128
	global_store_dword v[16:17], v3, off offset:192
	global_store_dword v[16:17], v4, off offset:256
	global_store_dword v[16:17], v5, off offset:320
	global_store_dword v[16:17], v6, off offset:384
	global_store_dword v[16:17], v7, off offset:448
	global_store_dword v[16:17], v8, off offset:512
	global_store_dword v[16:17], v9, off offset:576
	global_store_dword v[16:17], v10, off offset:640
	global_store_dword v[16:17], v11, off offset:704
	global_store_dword v[16:17], v12, off offset:768
	global_store_dword v[16:17], v13, off offset:832
	global_store_dword v[16:17], v14, off offset:896
	global_store_dword v[16:17], v15, off offset:960
	s_branch .Lys10_e

.Lys10_e:
.LBB0_865:
	s_or_b64 exec, exec, s[26:27]
	s_waitcnt vmcnt(4)
	v_mfma_f32_32x32x16_bf16 v[32:47], v[128:131], v[64:67], 0
	v_mfma_f32_32x32x16_bf16 v[0:15], v[128:131], v[72:75], 0
	s_nop 10
	v_mov_b32_e32 v136, v32
	v_mfma_f32_32x32x16_bf16 v[16:31], v[128:131], v[68:71], 0
	v_mov_b32_e32 v137, v0
	v_mov_b32_e32 v0, v33
	v_mfma_f32_32x32x16_bf16 v[48:63], v[128:131], v[76:79], 0
	s_nop 8
	v_mov_b32_e32 v138, v16
	v_fma_f32 v128, -v170, v134, v136
	v_fma_f32 v129, -v171, v135, v137
	v_fma_f32 v128, v168, v132, v128
	v_fma_f32 v129, v169, v133, v129
	v_mov_b32_e32 v139, v48
	v_pk_fma_f32 v[130:131], v[170:171], v[132:133], v[138:139]
	v_mov_b32_e32 v48, v17
	v_pk_fma_f32 v[130:131], v[168:169], v[134:135], v[130:131]
	v_pk_fma_f32 v[16:17], v[170:171], v[128:129], v[48:49]
	v_pk_fma_f32 v[0:1], v[170:171], v[130:131], v[0:1] neg_lo:[1,0,0] neg_hi:[1,0,0]
	v_pk_fma_f32 v[16:17], v[168:169], v[130:131], v[16:17]
	v_pk_fma_f32 v[0:1], v[168:169], v[128:129], v[0:1]
	v_cvt_pk_bf16_f32 v132, v128, v129
	v_cvt_pk_bf16_f32 v133, v130, v131
	v_cvt_pk_bf16_f32 v32, v0, v1
	v_cvt_pk_bf16_f32 v33, v16, v17
	ds_write2_b64 v188, v[132:133], v[32:33] offset1:34
	v_mov_b32_e32 v32, v34
	v_mov_b32_e32 v33, v2
	v_mov_b32_e32 v48, v18
	v_mov_b32_e32 v49, v50
	v_pk_fma_f32 v[32:33], v[170:171], v[16:17], v[32:33] neg_lo:[1,0,0] neg_hi:[1,0,0]
	v_mov_b32_e32 v2, v35
	v_pk_fma_f32 v[32:33], v[168:169], v[0:1], v[32:33]
	v_pk_fma_f32 v[0:1], v[170:171], v[0:1], v[48:49]
	v_mov_b32_e32 v50, v19
	v_pk_fma_f32 v[0:1], v[168:169], v[16:17], v[0:1]
	v_pk_fma_f32 v[18:19], v[170:171], v[32:33], v[50:51]
	v_pk_fma_f32 v[2:3], v[170:171], v[0:1], v[2:3] neg_lo:[1,0,0] neg_hi:[1,0,0]
	v_cvt_pk_bf16_f32 v17, v0, v1
	v_pk_fma_f32 v[2:3], v[168:169], v[32:33], v[2:3]
	v_pk_fma_f32 v[0:1], v[168:169], v[0:1], v[18:19]
	v_cvt_pk_bf16_f32 v16, v32, v33
	v_cvt_pk_bf16_f32 v18, v2, v3
	v_cvt_pk_bf16_f32 v19, v0, v1
	ds_write2_b64 v188, v[16:17], v[18:19] offset0:68 offset1:102
	v_mov_b32_e32 v16, v36
	v_mov_b32_e32 v17, v4
	v_mov_b32_e32 v18, v20
	v_mov_b32_e32 v19, v52
	v_pk_fma_f32 v[16:17], v[170:171], v[0:1], v[16:17] neg_lo:[1,0,0] neg_hi:[1,0,0]
	v_mov_b32_e32 v4, v37
	v_pk_fma_f32 v[16:17], v[168:169], v[2:3], v[16:17]
	v_pk_fma_f32 v[2:3], v[170:171], v[2:3], v[18:19]
	v_mov_b32_e32 v52, v21
	v_pk_fma_f32 v[0:1], v[168:169], v[0:1], v[2:3]
	v_cvt_pk_bf16_f32 v2, v16, v17
	v_pk_fma_f32 v[4:5], v[170:171], v[0:1], v[4:5] neg_lo:[1,0,0] neg_hi:[1,0,0]
	v_cvt_pk_bf16_f32 v3, v0, v1
	v_pk_fma_f32 v[4:5], v[168:169], v[16:17], v[4:5]
	v_pk_fma_f32 v[16:17], v[170:171], v[16:17], v[52:53]
	s_nop 0
	v_pk_fma_f32 v[0:1], v[168:169], v[0:1], v[16:17]
	v_cvt_pk_bf16_f32 v16, v4, v5
	v_cvt_pk_bf16_f32 v17, v0, v1
	ds_write2_b64 v189, v[2:3], v[16:17] offset0:16 offset1:50
	v_mov_b32_e32 v2, v38
	v_mov_b32_e32 v3, v6
	v_mov_b32_e32 v16, v22
	v_mov_b32_e32 v17, v54
	v_pk_fma_f32 v[2:3], v[170:171], v[0:1], v[2:3] neg_lo:[1,0,0] neg_hi:[1,0,0]
	v_mov_b32_e32 v6, v39
	v_pk_fma_f32 v[2:3], v[168:169], v[4:5], v[2:3]
	v_pk_fma_f32 v[4:5], v[170:171], v[4:5], v[16:17]
	v_mov_b32_e32 v54, v23
	v_pk_fma_f32 v[0:1], v[168:169], v[0:1], v[4:5]
	v_cvt_pk_bf16_f32 v4, v2, v3
	v_pk_fma_f32 v[6:7], v[170:171], v[0:1], v[6:7] neg_lo:[1,0,0] neg_hi:[1,0,0]
	v_cvt_pk_bf16_f32 v5, v0, v1
	v_pk_fma_f32 v[6:7], v[168:169], v[2:3], v[6:7]
	v_pk_fma_f32 v[2:3], v[170:171], v[2:3], v[54:55]
	s_nop 0
	v_pk_fma_f32 v[0:1], v[168:169], v[0:1], v[2:3]
	v_cvt_pk_bf16_f32 v2, v6, v7
	v_cvt_pk_bf16_f32 v3, v0, v1
	ds_write2_b64 v189, v[4:5], v[2:3] offset0:84 offset1:118
	v_mov_b32_e32 v4, v24
	v_mov_b32_e32 v5, v56
	v_mov_b32_e32 v2, v40
	v_mov_b32_e32 v3, v8
	v_pk_fma_f32 v[4:5], v[170:171], v[6:7], v[4:5]
	v_pk_fma_f32 v[2:3], v[170:171], v[0:1], v[2:3] neg_lo:[1,0,0] neg_hi:[1,0,0]
	v_pk_fma_f32 v[0:1], v[168:169], v[0:1], v[4:5]
	v_mov_b32_e32 v8, v41
	v_pk_fma_f32 v[2:3], v[168:169], v[6:7], v[2:3]
	v_mov_b32_e32 v56, v25
	v_pk_fma_f32 v[6:7], v[170:171], v[0:1], v[8:9] neg_lo:[1,0,0] neg_hi:[1,0,0]
	v_cvt_pk_bf16_f32 v4, v2, v3
	v_pk_fma_f32 v[6:7], v[168:169], v[2:3], v[6:7]
	v_pk_fma_f32 v[2:3], v[170:171], v[2:3], v[56:57]
	v_cvt_pk_bf16_f32 v5, v0, v1
	v_pk_fma_f32 v[0:1], v[168:169], v[0:1], v[2:3]
	v_cvt_pk_bf16_f32 v2, v6, v7
	v_cvt_pk_bf16_f32 v3, v0, v1
	ds_write2_b64 v190, v[4:5], v[2:3] offset0:32 offset1:66
	v_mov_b32_e32 v4, v26
	v_mov_b32_e32 v5, v58
	v_mov_b32_e32 v2, v42
	v_mov_b32_e32 v3, v10
	v_pk_fma_f32 v[4:5], v[170:171], v[6:7], v[4:5]
	v_pk_fma_f32 v[2:3], v[170:171], v[0:1], v[2:3] neg_lo:[1,0,0] neg_hi:[1,0,0]
	v_pk_fma_f32 v[0:1], v[168:169], v[0:1], v[4:5]
	v_mov_b32_e32 v10, v43
	v_pk_fma_f32 v[2:3], v[168:169], v[6:7], v[2:3]
	v_mov_b32_e32 v58, v27
	v_pk_fma_f32 v[6:7], v[170:171], v[0:1], v[10:11] neg_lo:[1,0,0] neg_hi:[1,0,0]
	v_cvt_pk_bf16_f32 v4, v2, v3
	v_pk_fma_f32 v[6:7], v[168:169], v[2:3], v[6:7]
	v_pk_fma_f32 v[2:3], v[170:171], v[2:3], v[58:59]
	v_cvt_pk_bf16_f32 v5, v0, v1
	v_pk_fma_f32 v[0:1], v[168:169], v[0:1], v[2:3]
	v_cvt_pk_bf16_f32 v2, v6, v7
	v_cvt_pk_bf16_f32 v3, v0, v1
	ds_write2_b64 v190, v[4:5], v[2:3] offset0:100 offset1:134
	v_mov_b32_e32 v4, v28
	v_mov_b32_e32 v5, v60
	v_mov_b32_e32 v2, v44
	v_mov_b32_e32 v3, v12
	v_pk_fma_f32 v[4:5], v[170:171], v[6:7], v[4:5]
	v_pk_fma_f32 v[2:3], v[170:171], v[0:1], v[2:3] neg_lo:[1,0,0] neg_hi:[1,0,0]
	v_pk_fma_f32 v[0:1], v[168:169], v[0:1], v[4:5]
	v_mov_b32_e32 v12, v45
	v_pk_fma_f32 v[2:3], v[168:169], v[6:7], v[2:3]
	v_mov_b32_e32 v60, v29
	v_pk_fma_f32 v[6:7], v[170:171], v[0:1], v[12:13] neg_lo:[1,0,0] neg_hi:[1,0,0]
	v_cvt_pk_bf16_f32 v4, v2, v3
	v_pk_fma_f32 v[6:7], v[168:169], v[2:3], v[6:7]
	v_pk_fma_f32 v[2:3], v[170:171], v[2:3], v[60:61]
	v_cvt_pk_bf16_f32 v5, v0, v1
	v_pk_fma_f32 v[0:1], v[168:169], v[0:1], v[2:3]
	v_cvt_pk_bf16_f32 v2, v6, v7
	v_cvt_pk_bf16_f32 v3, v0, v1
	ds_write2_b64 v191, v[4:5], v[2:3] offset0:48 offset1:82
	v_mov_b32_e32 v4, v30
	v_mov_b32_e32 v5, v62
	v_mov_b32_e32 v2, v46
	v_mov_b32_e32 v3, v14
	v_pk_fma_f32 v[4:5], v[170:171], v[6:7], v[4:5]
	v_pk_fma_f32 v[2:3], v[170:171], v[0:1], v[2:3] neg_lo:[1,0,0] neg_hi:[1,0,0]
	v_pk_fma_f32 v[0:1], v[168:169], v[0:1], v[4:5]
	v_mov_b32_e32 v14, v47
	v_pk_fma_f32 v[2:3], v[168:169], v[6:7], v[2:3]
	v_mov_b32_e32 v62, v31
	v_pk_fma_f32 v[6:7], v[170:171], v[0:1], v[14:15] neg_lo:[1,0,0] neg_hi:[1,0,0]
	v_cvt_pk_bf16_f32 v4, v2, v3
	v_pk_fma_f32 v[128:129], v[168:169], v[2:3], v[6:7]
	v_pk_fma_f32 v[2:3], v[170:171], v[2:3], v[62:63]
	v_cvt_pk_bf16_f32 v5, v0, v1
	v_pk_fma_f32 v[130:131], v[168:169], v[0:1], v[2:3]
	v_cvt_pk_bf16_f32 v0, v128, v129
	v_cvt_pk_bf16_f32 v1, v130, v131
	ds_write2_b64 v191, v[4:5], v[0:1] offset0:116 offset1:150
	ds_read_b128 v[0:3], v167 offset:40960
	ds_read_b128 v[16:19], v167 offset:40992
	s_waitcnt lgkmcnt(1)
	v_mfma_f32_32x32x16_bf16 v[0:15], v[0:3], v[80:83], 0
	s_waitcnt lgkmcnt(0)
	v_mfma_f32_32x32x16_bf16 v[0:15], v[16:19], v[84:87], v[0:15]
	ds_read_b128 v[16:19], v167 offset:41024
	ds_read_b128 v[20:23], v167 offset:41056
	s_waitcnt lgkmcnt(1)
	v_mfma_f32_32x32x16_bf16 v[0:15], v[16:19], v[88:91], v[0:15]
	s_waitcnt lgkmcnt(0)
	v_mfma_f32_32x32x16_bf16 v[0:15], v[20:23], v[92:95], v[0:15]
	ds_read_b128 v[16:19], v167 offset:41088
	ds_read_b128 v[20:23], v167 offset:41120
	s_waitcnt lgkmcnt(1)
	v_mfma_f32_32x32x16_bf16 v[0:15], v[16:19], v[96:99], v[0:15]
	s_waitcnt lgkmcnt(0)
	v_mfma_f32_32x32x16_bf16 v[0:15], v[20:23], v[100:103], v[0:15]
	ds_read_b128 v[16:19], v167 offset:41152
	ds_read_b128 v[20:23], v167 offset:41184
	s_waitcnt lgkmcnt(1)
	v_mfma_f32_32x32x16_bf16 v[0:15], v[16:19], v[104:107], v[0:15]
	s_waitcnt lgkmcnt(0)
	v_mfma_f32_32x32x16_bf16 v[0:15], v[20:23], v[108:111], v[0:15]
	s_and_saveexec_b64 s[26:27], s[0:1]
	s_cbranch_execz .LBB0_867
	s_or_b32 s22, s25, 0x30
	s_xor_b32 s56, s25, 0xcf
	s_lshl_b32 s22, s22, 4
	s_lshl_b32 s56, s56, 4
	s_and_b64 s[50:51], s[4:5], exec
	s_cselect_b32 s22, s22, s56
	v_lshl_add_u64 v[16:17], s[22:23], 2, v[174:175]
	s_cbranch_scc0 .Lys11_b
	s_nop 3
	global_store_dword v[16:17], v0, off
	global_store_dword v[16:17], v1, off offset:64
	global_store_dword v[16:17], v2, off offset:128
	global_store_dword v[16:17], v3, off offset:192
	global_store_dword v[16:17], v4, off offset:256
	global_store_dword v[16:17], v5, off offset:320
	global_store_dword v[16:17], v6, off offset:384
	global_store_dword v[16:17], v7, off offset:448
	global_store_dword v[16:17], v8, off offset:512
	global_store_dword v[16:17], v9, off offset:576
	global_store_dword v[16:17], v10, off offset:640
	global_store_dword v[16:17], v11, off offset:704
	global_store_dword v[16:17], v12, off offset:768
	global_store_dword v[16:17], v13, off offset:832
	global_store_dword v[16:17], v14, off offset:896
	global_store_dword v[16:17], v15, off offset:960
	s_branch .Lys11_e

.Lys11_e:
.LBB0_867:
	s_or_b64 exec, exec, s[26:27]
	s_waitcnt vmcnt(3)
	v_mfma_f32_32x32x16_bf16 v[32:47], v[124:127], v[64:67], 0
	v_mfma_f32_32x32x16_bf16 v[0:15], v[124:127], v[72:75], 0
	s_nop 10
	v_mov_b32_e32 v132, v32
	v_mfma_f32_32x32x16_bf16 v[16:31], v[124:127], v[68:71], 0
	v_mov_b32_e32 v133, v0
	v_mov_b32_e32 v0, v33
	v_mfma_f32_32x32x16_bf16 v[48:63], v[124:127], v[76:79], 0
	s_nop 8
	v_mov_b32_e32 v134, v16
	v_fma_f32 v124, -v170, v130, v132
	v_fma_f32 v125, -v171, v131, v133
	v_fma_f32 v124, v168, v128, v124
	v_fma_f32 v125, v169, v129, v125
	v_mov_b32_e32 v135, v48
	v_pk_fma_f32 v[126:127], v[170:171], v[128:129], v[134:135]
	v_mov_b32_e32 v48, v17
	v_pk_fma_f32 v[126:127], v[168:169], v[130:131], v[126:127]
	v_pk_fma_f32 v[16:17], v[170:171], v[124:125], v[48:49]
	v_pk_fma_f32 v[0:1], v[170:171], v[126:127], v[0:1] neg_lo:[1,0,0] neg_hi:[1,0,0]
	v_pk_fma_f32 v[16:17], v[168:169], v[126:127], v[16:17]
	v_pk_fma_f32 v[0:1], v[168:169], v[124:125], v[0:1]
	v_cvt_pk_bf16_f32 v128, v124, v125
	v_cvt_pk_bf16_f32 v129, v126, v127
	v_cvt_pk_bf16_f32 v32, v0, v1
	v_cvt_pk_bf16_f32 v33, v16, v17
	ds_write2_b64 v188, v[128:129], v[32:33] offset1:34
	v_mov_b32_e32 v32, v34
	v_mov_b32_e32 v33, v2
	v_mov_b32_e32 v48, v18
	v_mov_b32_e32 v49, v50
	v_pk_fma_f32 v[32:33], v[170:171], v[16:17], v[32:33] neg_lo:[1,0,0] neg_hi:[1,0,0]
	v_mov_b32_e32 v2, v35
	v_pk_fma_f32 v[32:33], v[168:169], v[0:1], v[32:33]
	v_pk_fma_f32 v[0:1], v[170:171], v[0:1], v[48:49]
	v_mov_b32_e32 v50, v19
	v_pk_fma_f32 v[0:1], v[168:169], v[16:17], v[0:1]
	v_pk_fma_f32 v[18:19], v[170:171], v[32:33], v[50:51]
	v_pk_fma_f32 v[2:3], v[170:171], v[0:1], v[2:3] neg_lo:[1,0,0] neg_hi:[1,0,0]
	v_cvt_pk_bf16_f32 v17, v0, v1
	v_pk_fma_f32 v[2:3], v[168:169], v[32:33], v[2:3]
	v_pk_fma_f32 v[0:1], v[168:169], v[0:1], v[18:19]
	v_cvt_pk_bf16_f32 v16, v32, v33
	v_cvt_pk_bf16_f32 v18, v2, v3
	v_cvt_pk_bf16_f32 v19, v0, v1
	ds_write2_b64 v188, v[16:17], v[18:19] offset0:68 offset1:102
	v_mov_b32_e32 v16, v36
	v_mov_b32_e32 v17, v4
	v_mov_b32_e32 v18, v20
	v_mov_b32_e32 v19, v52
	v_pk_fma_f32 v[16:17], v[170:171], v[0:1], v[16:17] neg_lo:[1,0,0] neg_hi:[1,0,0]
	v_mov_b32_e32 v4, v37
	v_pk_fma_f32 v[16:17], v[168:169], v[2:3], v[16:17]
	v_pk_fma_f32 v[2:3], v[170:171], v[2:3], v[18:19]
	v_mov_b32_e32 v52, v21
	v_pk_fma_f32 v[0:1], v[168:169], v[0:1], v[2:3]
	v_cvt_pk_bf16_f32 v2, v16, v17
	v_pk_fma_f32 v[4:5], v[170:171], v[0:1], v[4:5] neg_lo:[1,0,0] neg_hi:[1,0,0]
	v_cvt_pk_bf16_f32 v3, v0, v1
	v_pk_fma_f32 v[4:5], v[168:169], v[16:17], v[4:5]
	v_pk_fma_f32 v[16:17], v[170:171], v[16:17], v[52:53]
	s_nop 0
	v_pk_fma_f32 v[0:1], v[168:169], v[0:1], v[16:17]
	v_cvt_pk_bf16_f32 v16, v4, v5
	v_cvt_pk_bf16_f32 v17, v0, v1
	ds_write2_b64 v189, v[2:3], v[16:17] offset0:16 offset1:50
	v_mov_b32_e32 v2, v38
	v_mov_b32_e32 v3, v6
	v_mov_b32_e32 v16, v22
	v_mov_b32_e32 v17, v54
	v_pk_fma_f32 v[2:3], v[170:171], v[0:1], v[2:3] neg_lo:[1,0,0] neg_hi:[1,0,0]
	v_mov_b32_e32 v6, v39
	v_pk_fma_f32 v[2:3], v[168:169], v[4:5], v[2:3]
	v_pk_fma_f32 v[4:5], v[170:171], v[4:5], v[16:17]
	v_mov_b32_e32 v54, v23
	v_pk_fma_f32 v[0:1], v[168:169], v[0:1], v[4:5]
	v_cvt_pk_bf16_f32 v4, v2, v3
	v_pk_fma_f32 v[6:7], v[170:171], v[0:1], v[6:7] neg_lo:[1,0,0] neg_hi:[1,0,0]
	v_cvt_pk_bf16_f32 v5, v0, v1
	v_pk_fma_f32 v[6:7], v[168:169], v[2:3], v[6:7]
	v_pk_fma_f32 v[2:3], v[170:171], v[2:3], v[54:55]
	s_nop 0
	v_pk_fma_f32 v[0:1], v[168:169], v[0:1], v[2:3]
	v_cvt_pk_bf16_f32 v2, v6, v7
	v_cvt_pk_bf16_f32 v3, v0, v1
	ds_write2_b64 v189, v[4:5], v[2:3] offset0:84 offset1:118
	v_mov_b32_e32 v4, v24
	v_mov_b32_e32 v5, v56
	v_mov_b32_e32 v2, v40
	v_mov_b32_e32 v3, v8
	v_pk_fma_f32 v[4:5], v[170:171], v[6:7], v[4:5]
	v_pk_fma_f32 v[2:3], v[170:171], v[0:1], v[2:3] neg_lo:[1,0,0] neg_hi:[1,0,0]
	v_pk_fma_f32 v[0:1], v[168:169], v[0:1], v[4:5]
	v_mov_b32_e32 v8, v41
	v_pk_fma_f32 v[2:3], v[168:169], v[6:7], v[2:3]
	v_mov_b32_e32 v56, v25
	v_pk_fma_f32 v[6:7], v[170:171], v[0:1], v[8:9] neg_lo:[1,0,0] neg_hi:[1,0,0]
	v_cvt_pk_bf16_f32 v4, v2, v3
	v_pk_fma_f32 v[6:7], v[168:169], v[2:3], v[6:7]
	v_pk_fma_f32 v[2:3], v[170:171], v[2:3], v[56:57]
	v_cvt_pk_bf16_f32 v5, v0, v1
	v_pk_fma_f32 v[0:1], v[168:169], v[0:1], v[2:3]
	v_cvt_pk_bf16_f32 v2, v6, v7
	v_cvt_pk_bf16_f32 v3, v0, v1
	ds_write2_b64 v190, v[4:5], v[2:3] offset0:32 offset1:66
	v_mov_b32_e32 v4, v26
	v_mov_b32_e32 v5, v58
	v_mov_b32_e32 v2, v42
	v_mov_b32_e32 v3, v10
	v_pk_fma_f32 v[4:5], v[170:171], v[6:7], v[4:5]
	v_pk_fma_f32 v[2:3], v[170:171], v[0:1], v[2:3] neg_lo:[1,0,0] neg_hi:[1,0,0]
	v_pk_fma_f32 v[0:1], v[168:169], v[0:1], v[4:5]
	v_mov_b32_e32 v10, v43
	v_pk_fma_f32 v[2:3], v[168:169], v[6:7], v[2:3]
	v_mov_b32_e32 v58, v27
	v_pk_fma_f32 v[6:7], v[170:171], v[0:1], v[10:11] neg_lo:[1,0,0] neg_hi:[1,0,0]
	v_cvt_pk_bf16_f32 v4, v2, v3
	v_pk_fma_f32 v[6:7], v[168:169], v[2:3], v[6:7]
	v_pk_fma_f32 v[2:3], v[170:171], v[2:3], v[58:59]
	v_cvt_pk_bf16_f32 v5, v0, v1
	v_pk_fma_f32 v[0:1], v[168:169], v[0:1], v[2:3]
	v_cvt_pk_bf16_f32 v2, v6, v7
	v_cvt_pk_bf16_f32 v3, v0, v1
	ds_write2_b64 v190, v[4:5], v[2:3] offset0:100 offset1:134
	v_mov_b32_e32 v4, v28
	v_mov_b32_e32 v5, v60
	v_mov_b32_e32 v2, v44
	v_mov_b32_e32 v3, v12
	v_pk_fma_f32 v[4:5], v[170:171], v[6:7], v[4:5]
	v_pk_fma_f32 v[2:3], v[170:171], v[0:1], v[2:3] neg_lo:[1,0,0] neg_hi:[1,0,0]
	v_pk_fma_f32 v[0:1], v[168:169], v[0:1], v[4:5]
	v_mov_b32_e32 v12, v45
	v_pk_fma_f32 v[2:3], v[168:169], v[6:7], v[2:3]
	v_mov_b32_e32 v60, v29
	v_pk_fma_f32 v[6:7], v[170:171], v[0:1], v[12:13] neg_lo:[1,0,0] neg_hi:[1,0,0]
	v_cvt_pk_bf16_f32 v4, v2, v3
	v_pk_fma_f32 v[6:7], v[168:169], v[2:3], v[6:7]
	v_pk_fma_f32 v[2:3], v[170:171], v[2:3], v[60:61]
	v_cvt_pk_bf16_f32 v5, v0, v1
	v_pk_fma_f32 v[0:1], v[168:169], v[0:1], v[2:3]
	v_cvt_pk_bf16_f32 v2, v6, v7
	v_cvt_pk_bf16_f32 v3, v0, v1
	ds_write2_b64 v191, v[4:5], v[2:3] offset0:48 offset1:82
	v_mov_b32_e32 v4, v30
	v_mov_b32_e32 v5, v62
	v_mov_b32_e32 v2, v46
	v_mov_b32_e32 v3, v14
	v_pk_fma_f32 v[4:5], v[170:171], v[6:7], v[4:5]
	v_pk_fma_f32 v[2:3], v[170:171], v[0:1], v[2:3] neg_lo:[1,0,0] neg_hi:[1,0,0]
	v_pk_fma_f32 v[0:1], v[168:169], v[0:1], v[4:5]
	v_mov_b32_e32 v14, v47
	v_pk_fma_f32 v[2:3], v[168:169], v[6:7], v[2:3]
	v_mov_b32_e32 v62, v31
	v_pk_fma_f32 v[6:7], v[170:171], v[0:1], v[14:15] neg_lo:[1,0,0] neg_hi:[1,0,0]
	v_cvt_pk_bf16_f32 v4, v2, v3
	v_pk_fma_f32 v[124:125], v[168:169], v[2:3], v[6:7]
	v_pk_fma_f32 v[2:3], v[170:171], v[2:3], v[62:63]
	v_cvt_pk_bf16_f32 v5, v0, v1
	v_pk_fma_f32 v[126:127], v[168:169], v[0:1], v[2:3]
	v_cvt_pk_bf16_f32 v0, v124, v125
	v_cvt_pk_bf16_f32 v1, v126, v127
	ds_write2_b64 v191, v[4:5], v[0:1] offset0:116 offset1:150
	ds_read_b128 v[0:3], v167 offset:40960
	ds_read_b128 v[16:19], v167 offset:40992
	s_waitcnt lgkmcnt(1)
	v_mfma_f32_32x32x16_bf16 v[0:15], v[0:3], v[80:83], 0
	s_waitcnt lgkmcnt(0)
	v_mfma_f32_32x32x16_bf16 v[0:15], v[16:19], v[84:87], v[0:15]
	ds_read_b128 v[16:19], v167 offset:41024
	ds_read_b128 v[20:23], v167 offset:41056
	s_waitcnt lgkmcnt(1)
	v_mfma_f32_32x32x16_bf16 v[0:15], v[16:19], v[88:91], v[0:15]
	s_waitcnt lgkmcnt(0)
	v_mfma_f32_32x32x16_bf16 v[0:15], v[20:23], v[92:95], v[0:15]
	ds_read_b128 v[16:19], v167 offset:41088
	ds_read_b128 v[20:23], v167 offset:41120
	s_waitcnt lgkmcnt(1)
	v_mfma_f32_32x32x16_bf16 v[0:15], v[16:19], v[96:99], v[0:15]
	s_waitcnt lgkmcnt(0)
	v_mfma_f32_32x32x16_bf16 v[0:15], v[20:23], v[100:103], v[0:15]
	ds_read_b128 v[16:19], v167 offset:41152
	ds_read_b128 v[20:23], v167 offset:41184
	s_waitcnt lgkmcnt(1)
	v_mfma_f32_32x32x16_bf16 v[0:15], v[16:19], v[104:107], v[0:15]
	s_waitcnt lgkmcnt(0)
	v_mfma_f32_32x32x16_bf16 v[0:15], v[20:23], v[108:111], v[0:15]
	s_and_saveexec_b64 s[26:27], s[0:1]
	s_cbranch_execz .LBB0_869
	s_or_b32 s22, s25, 0x40
	s_xor_b32 s56, s25, 0xbf
	s_lshl_b32 s22, s22, 4
	s_lshl_b32 s56, s56, 4
	s_and_b64 s[50:51], s[4:5], exec
	s_cselect_b32 s22, s22, s56
	v_lshl_add_u64 v[16:17], s[22:23], 2, v[174:175]
	s_cbranch_scc0 .Lys12_b
	s_nop 3
	global_store_dword v[16:17], v0, off
	global_store_dword v[16:17], v1, off offset:64
	global_store_dword v[16:17], v2, off offset:128
	global_store_dword v[16:17], v3, off offset:192
	global_store_dword v[16:17], v4, off offset:256
	global_store_dword v[16:17], v5, off offset:320
	global_store_dword v[16:17], v6, off offset:384
	global_store_dword v[16:17], v7, off offset:448
	global_store_dword v[16:17], v8, off offset:512
	global_store_dword v[16:17], v9, off offset:576
	global_store_dword v[16:17], v10, off offset:640
	global_store_dword v[16:17], v11, off offset:704
	global_store_dword v[16:17], v12, off offset:768
	global_store_dword v[16:17], v13, off offset:832
	global_store_dword v[16:17], v14, off offset:896
	global_store_dword v[16:17], v15, off offset:960
	s_branch .Lys12_e

.Lys12_e:
.LBB0_869:
	s_or_b64 exec, exec, s[26:27]
	s_waitcnt vmcnt(2)
	v_mfma_f32_32x32x16_bf16 v[32:47], v[120:123], v[64:67], 0
	v_mfma_f32_32x32x16_bf16 v[0:15], v[120:123], v[72:75], 0
	s_nop 10
	v_mov_b32_e32 v128, v32
	v_mfma_f32_32x32x16_bf16 v[16:31], v[120:123], v[68:71], 0
	v_mov_b32_e32 v129, v0
	v_mov_b32_e32 v0, v33
	v_mfma_f32_32x32x16_bf16 v[48:63], v[120:123], v[76:79], 0
	s_nop 8
	v_mov_b32_e32 v130, v16
	v_fma_f32 v120, -v170, v126, v128
	v_fma_f32 v121, -v171, v127, v129
	v_fma_f32 v120, v168, v124, v120
	v_fma_f32 v121, v169, v125, v121
	v_mov_b32_e32 v131, v48
	v_pk_fma_f32 v[122:123], v[170:171], v[124:125], v[130:131]
	v_mov_b32_e32 v48, v17
	v_pk_fma_f32 v[122:123], v[168:169], v[126:127], v[122:123]
	v_pk_fma_f32 v[16:17], v[170:171], v[120:121], v[48:49]
	v_pk_fma_f32 v[0:1], v[170:171], v[122:123], v[0:1] neg_lo:[1,0,0] neg_hi:[1,0,0]
	v_pk_fma_f32 v[16:17], v[168:169], v[122:123], v[16:17]
	v_pk_fma_f32 v[0:1], v[168:169], v[120:121], v[0:1]
	v_cvt_pk_bf16_f32 v124, v120, v121
	v_cvt_pk_bf16_f32 v125, v122, v123
	v_cvt_pk_bf16_f32 v32, v0, v1
	v_cvt_pk_bf16_f32 v33, v16, v17
	ds_write2_b64 v188, v[124:125], v[32:33] offset1:34
	v_mov_b32_e32 v32, v34
	v_mov_b32_e32 v33, v2
	v_mov_b32_e32 v48, v18
	v_mov_b32_e32 v49, v50
	v_pk_fma_f32 v[32:33], v[170:171], v[16:17], v[32:33] neg_lo:[1,0,0] neg_hi:[1,0,0]
	v_mov_b32_e32 v2, v35
	v_pk_fma_f32 v[32:33], v[168:169], v[0:1], v[32:33]
	v_pk_fma_f32 v[0:1], v[170:171], v[0:1], v[48:49]
	v_mov_b32_e32 v50, v19
	v_pk_fma_f32 v[0:1], v[168:169], v[16:17], v[0:1]
	v_pk_fma_f32 v[18:19], v[170:171], v[32:33], v[50:51]
	v_pk_fma_f32 v[2:3], v[170:171], v[0:1], v[2:3] neg_lo:[1,0,0] neg_hi:[1,0,0]
	v_cvt_pk_bf16_f32 v17, v0, v1
	v_pk_fma_f32 v[2:3], v[168:169], v[32:33], v[2:3]
	v_pk_fma_f32 v[0:1], v[168:169], v[0:1], v[18:19]
	v_cvt_pk_bf16_f32 v16, v32, v33
	v_cvt_pk_bf16_f32 v18, v2, v3
	v_cvt_pk_bf16_f32 v19, v0, v1
	ds_write2_b64 v188, v[16:17], v[18:19] offset0:68 offset1:102
	v_mov_b32_e32 v16, v36
	v_mov_b32_e32 v17, v4
	v_mov_b32_e32 v18, v20
	v_mov_b32_e32 v19, v52
	v_pk_fma_f32 v[16:17], v[170:171], v[0:1], v[16:17] neg_lo:[1,0,0] neg_hi:[1,0,0]
	v_mov_b32_e32 v4, v37
	v_pk_fma_f32 v[16:17], v[168:169], v[2:3], v[16:17]
	v_pk_fma_f32 v[2:3], v[170:171], v[2:3], v[18:19]
	v_mov_b32_e32 v52, v21
	v_pk_fma_f32 v[0:1], v[168:169], v[0:1], v[2:3]
	v_cvt_pk_bf16_f32 v2, v16, v17
	v_pk_fma_f32 v[4:5], v[170:171], v[0:1], v[4:5] neg_lo:[1,0,0] neg_hi:[1,0,0]
	v_cvt_pk_bf16_f32 v3, v0, v1
	v_pk_fma_f32 v[4:5], v[168:169], v[16:17], v[4:5]
	v_pk_fma_f32 v[16:17], v[170:171], v[16:17], v[52:53]
	s_nop 0
	v_pk_fma_f32 v[0:1], v[168:169], v[0:1], v[16:17]
	v_cvt_pk_bf16_f32 v16, v4, v5
	v_cvt_pk_bf16_f32 v17, v0, v1
	ds_write2_b64 v189, v[2:3], v[16:17] offset0:16 offset1:50
	v_mov_b32_e32 v2, v38
	v_mov_b32_e32 v3, v6
	v_mov_b32_e32 v16, v22
	v_mov_b32_e32 v17, v54
	v_pk_fma_f32 v[2:3], v[170:171], v[0:1], v[2:3] neg_lo:[1,0,0] neg_hi:[1,0,0]
	v_mov_b32_e32 v6, v39
	v_pk_fma_f32 v[2:3], v[168:169], v[4:5], v[2:3]
	v_pk_fma_f32 v[4:5], v[170:171], v[4:5], v[16:17]
	v_mov_b32_e32 v54, v23
	v_pk_fma_f32 v[0:1], v[168:169], v[0:1], v[4:5]
	v_cvt_pk_bf16_f32 v4, v2, v3
	v_pk_fma_f32 v[6:7], v[170:171], v[0:1], v[6:7] neg_lo:[1,0,0] neg_hi:[1,0,0]
	v_cvt_pk_bf16_f32 v5, v0, v1
	v_pk_fma_f32 v[6:7], v[168:169], v[2:3], v[6:7]
	v_pk_fma_f32 v[2:3], v[170:171], v[2:3], v[54:55]
	s_nop 0
	v_pk_fma_f32 v[0:1], v[168:169], v[0:1], v[2:3]
	v_cvt_pk_bf16_f32 v2, v6, v7
	v_cvt_pk_bf16_f32 v3, v0, v1
	ds_write2_b64 v189, v[4:5], v[2:3] offset0:84 offset1:118
	v_mov_b32_e32 v4, v24
	v_mov_b32_e32 v5, v56
	v_mov_b32_e32 v2, v40
	v_mov_b32_e32 v3, v8
	v_pk_fma_f32 v[4:5], v[170:171], v[6:7], v[4:5]
	v_pk_fma_f32 v[2:3], v[170:171], v[0:1], v[2:3] neg_lo:[1,0,0] neg_hi:[1,0,0]
	v_pk_fma_f32 v[0:1], v[168:169], v[0:1], v[4:5]
	v_mov_b32_e32 v8, v41
	v_pk_fma_f32 v[2:3], v[168:169], v[6:7], v[2:3]
	v_mov_b32_e32 v56, v25
	v_pk_fma_f32 v[6:7], v[170:171], v[0:1], v[8:9] neg_lo:[1,0,0] neg_hi:[1,0,0]
	v_cvt_pk_bf16_f32 v4, v2, v3
	v_pk_fma_f32 v[6:7], v[168:169], v[2:3], v[6:7]
	v_pk_fma_f32 v[2:3], v[170:171], v[2:3], v[56:57]
	v_cvt_pk_bf16_f32 v5, v0, v1
	v_pk_fma_f32 v[0:1], v[168:169], v[0:1], v[2:3]
	v_cvt_pk_bf16_f32 v2, v6, v7
	v_cvt_pk_bf16_f32 v3, v0, v1
	ds_write2_b64 v190, v[4:5], v[2:3] offset0:32 offset1:66
	v_mov_b32_e32 v4, v26
	v_mov_b32_e32 v5, v58
	v_mov_b32_e32 v2, v42
	v_mov_b32_e32 v3, v10
	v_pk_fma_f32 v[4:5], v[170:171], v[6:7], v[4:5]
	v_pk_fma_f32 v[2:3], v[170:171], v[0:1], v[2:3] neg_lo:[1,0,0] neg_hi:[1,0,0]
	v_pk_fma_f32 v[0:1], v[168:169], v[0:1], v[4:5]
	v_mov_b32_e32 v10, v43
	v_pk_fma_f32 v[2:3], v[168:169], v[6:7], v[2:3]
	v_mov_b32_e32 v58, v27
	v_pk_fma_f32 v[6:7], v[170:171], v[0:1], v[10:11] neg_lo:[1,0,0] neg_hi:[1,0,0]
	v_cvt_pk_bf16_f32 v4, v2, v3
	v_pk_fma_f32 v[6:7], v[168:169], v[2:3], v[6:7]
	v_pk_fma_f32 v[2:3], v[170:171], v[2:3], v[58:59]
	v_cvt_pk_bf16_f32 v5, v0, v1
	v_pk_fma_f32 v[0:1], v[168:169], v[0:1], v[2:3]
	v_cvt_pk_bf16_f32 v2, v6, v7
	v_cvt_pk_bf16_f32 v3, v0, v1
	ds_write2_b64 v190, v[4:5], v[2:3] offset0:100 offset1:134
	v_mov_b32_e32 v4, v28
	v_mov_b32_e32 v5, v60
	v_mov_b32_e32 v2, v44
	v_mov_b32_e32 v3, v12
	v_pk_fma_f32 v[4:5], v[170:171], v[6:7], v[4:5]
	v_pk_fma_f32 v[2:3], v[170:171], v[0:1], v[2:3] neg_lo:[1,0,0] neg_hi:[1,0,0]
	v_pk_fma_f32 v[0:1], v[168:169], v[0:1], v[4:5]
	v_mov_b32_e32 v12, v45
	v_pk_fma_f32 v[2:3], v[168:169], v[6:7], v[2:3]
	v_mov_b32_e32 v60, v29
	v_pk_fma_f32 v[6:7], v[170:171], v[0:1], v[12:13] neg_lo:[1,0,0] neg_hi:[1,0,0]
	v_cvt_pk_bf16_f32 v4, v2, v3
	v_pk_fma_f32 v[6:7], v[168:169], v[2:3], v[6:7]
	v_pk_fma_f32 v[2:3], v[170:171], v[2:3], v[60:61]
	v_cvt_pk_bf16_f32 v5, v0, v1
	v_pk_fma_f32 v[0:1], v[168:169], v[0:1], v[2:3]
	v_cvt_pk_bf16_f32 v2, v6, v7
	v_cvt_pk_bf16_f32 v3, v0, v1
	ds_write2_b64 v191, v[4:5], v[2:3] offset0:48 offset1:82
	v_mov_b32_e32 v4, v30
	v_mov_b32_e32 v5, v62
	v_mov_b32_e32 v2, v46
	v_mov_b32_e32 v3, v14
	v_pk_fma_f32 v[4:5], v[170:171], v[6:7], v[4:5]
	v_pk_fma_f32 v[2:3], v[170:171], v[0:1], v[2:3] neg_lo:[1,0,0] neg_hi:[1,0,0]
	v_pk_fma_f32 v[0:1], v[168:169], v[0:1], v[4:5]
	v_mov_b32_e32 v14, v47
	v_pk_fma_f32 v[2:3], v[168:169], v[6:7], v[2:3]
	v_mov_b32_e32 v62, v31
	v_pk_fma_f32 v[6:7], v[170:171], v[0:1], v[14:15] neg_lo:[1,0,0] neg_hi:[1,0,0]
	v_cvt_pk_bf16_f32 v4, v2, v3
	v_pk_fma_f32 v[120:121], v[168:169], v[2:3], v[6:7]
	v_pk_fma_f32 v[2:3], v[170:171], v[2:3], v[62:63]
	v_cvt_pk_bf16_f32 v5, v0, v1
	v_pk_fma_f32 v[122:123], v[168:169], v[0:1], v[2:3]
	v_cvt_pk_bf16_f32 v0, v120, v121
	v_cvt_pk_bf16_f32 v1, v122, v123
	ds_write2_b64 v191, v[4:5], v[0:1] offset0:116 offset1:150
	ds_read_b128 v[0:3], v167 offset:40960
	ds_read_b128 v[16:19], v167 offset:40992
	s_waitcnt lgkmcnt(1)
	v_mfma_f32_32x32x16_bf16 v[0:15], v[0:3], v[80:83], 0
	s_waitcnt lgkmcnt(0)
	v_mfma_f32_32x32x16_bf16 v[0:15], v[16:19], v[84:87], v[0:15]
	ds_read_b128 v[16:19], v167 offset:41024
	ds_read_b128 v[20:23], v167 offset:41056
	s_waitcnt lgkmcnt(1)
	v_mfma_f32_32x32x16_bf16 v[0:15], v[16:19], v[88:91], v[0:15]
	s_waitcnt lgkmcnt(0)
	v_mfma_f32_32x32x16_bf16 v[0:15], v[20:23], v[92:95], v[0:15]
	ds_read_b128 v[16:19], v167 offset:41088
	ds_read_b128 v[20:23], v167 offset:41120
	s_waitcnt lgkmcnt(1)
	v_mfma_f32_32x32x16_bf16 v[0:15], v[16:19], v[96:99], v[0:15]
	s_waitcnt lgkmcnt(0)
	v_mfma_f32_32x32x16_bf16 v[0:15], v[20:23], v[100:103], v[0:15]
	ds_read_b128 v[16:19], v167 offset:41152
	ds_read_b128 v[20:23], v167 offset:41184
	s_waitcnt lgkmcnt(1)
	v_mfma_f32_32x32x16_bf16 v[0:15], v[16:19], v[104:107], v[0:15]
	s_waitcnt lgkmcnt(0)
	v_mfma_f32_32x32x16_bf16 v[0:15], v[20:23], v[108:111], v[0:15]
	s_and_saveexec_b64 s[26:27], s[0:1]
	s_cbranch_execz .LBB0_871
	s_or_b32 s22, s25, 0x50
	s_xor_b32 s56, s25, 0xaf
	s_lshl_b32 s22, s22, 4
	s_lshl_b32 s56, s56, 4
	s_and_b64 s[50:51], s[4:5], exec
	s_cselect_b32 s22, s22, s56
	v_lshl_add_u64 v[16:17], s[22:23], 2, v[174:175]
	s_cbranch_scc0 .Lys13_b
	s_nop 3
	global_store_dword v[16:17], v0, off
	global_store_dword v[16:17], v1, off offset:64
	global_store_dword v[16:17], v2, off offset:128
	global_store_dword v[16:17], v3, off offset:192
	global_store_dword v[16:17], v4, off offset:256
	global_store_dword v[16:17], v5, off offset:320
	global_store_dword v[16:17], v6, off offset:384
	global_store_dword v[16:17], v7, off offset:448
	global_store_dword v[16:17], v8, off offset:512
	global_store_dword v[16:17], v9, off offset:576
	global_store_dword v[16:17], v10, off offset:640
	global_store_dword v[16:17], v11, off offset:704
	global_store_dword v[16:17], v12, off offset:768
	global_store_dword v[16:17], v13, off offset:832
	global_store_dword v[16:17], v14, off offset:896
	global_store_dword v[16:17], v15, off offset:960
	s_branch .Lys13_e

.Lys13_e:
.LBB0_871:
	s_or_b64 exec, exec, s[26:27]
	s_waitcnt vmcnt(1)
	v_mfma_f32_32x32x16_bf16 v[32:47], v[116:119], v[64:67], 0
	v_mfma_f32_32x32x16_bf16 v[0:15], v[116:119], v[72:75], 0
	s_nop 10
	v_mov_b32_e32 v124, v32
	v_mfma_f32_32x32x16_bf16 v[16:31], v[116:119], v[68:71], 0
	v_mov_b32_e32 v125, v0
	v_mov_b32_e32 v0, v33
	v_mfma_f32_32x32x16_bf16 v[48:63], v[116:119], v[76:79], 0
	s_nop 8
	v_mov_b32_e32 v126, v16
	v_fma_f32 v116, -v170, v122, v124
	v_fma_f32 v117, -v171, v123, v125
	v_fma_f32 v116, v168, v120, v116
	v_fma_f32 v117, v169, v121, v117
	v_mov_b32_e32 v127, v48
	v_pk_fma_f32 v[118:119], v[170:171], v[120:121], v[126:127]
	v_mov_b32_e32 v48, v17
	v_pk_fma_f32 v[118:119], v[168:169], v[122:123], v[118:119]
	v_pk_fma_f32 v[16:17], v[170:171], v[116:117], v[48:49]
	v_pk_fma_f32 v[0:1], v[170:171], v[118:119], v[0:1] neg_lo:[1,0,0] neg_hi:[1,0,0]
	v_pk_fma_f32 v[16:17], v[168:169], v[118:119], v[16:17]
	v_pk_fma_f32 v[0:1], v[168:169], v[116:117], v[0:1]
	v_cvt_pk_bf16_f32 v120, v116, v117
	v_cvt_pk_bf16_f32 v121, v118, v119
	v_cvt_pk_bf16_f32 v32, v0, v1
	v_cvt_pk_bf16_f32 v33, v16, v17
	ds_write2_b64 v188, v[120:121], v[32:33] offset1:34
	v_mov_b32_e32 v32, v34
	v_mov_b32_e32 v33, v2
	v_mov_b32_e32 v48, v18
	v_mov_b32_e32 v49, v50
	v_pk_fma_f32 v[32:33], v[170:171], v[16:17], v[32:33] neg_lo:[1,0,0] neg_hi:[1,0,0]
	v_mov_b32_e32 v2, v35
	v_pk_fma_f32 v[32:33], v[168:169], v[0:1], v[32:33]
	v_pk_fma_f32 v[0:1], v[170:171], v[0:1], v[48:49]
	v_mov_b32_e32 v50, v19
	v_pk_fma_f32 v[0:1], v[168:169], v[16:17], v[0:1]
	v_pk_fma_f32 v[18:19], v[170:171], v[32:33], v[50:51]
	v_pk_fma_f32 v[2:3], v[170:171], v[0:1], v[2:3] neg_lo:[1,0,0] neg_hi:[1,0,0]
	v_cvt_pk_bf16_f32 v17, v0, v1
	v_pk_fma_f32 v[2:3], v[168:169], v[32:33], v[2:3]
	v_pk_fma_f32 v[0:1], v[168:169], v[0:1], v[18:19]
	v_cvt_pk_bf16_f32 v16, v32, v33
	v_cvt_pk_bf16_f32 v18, v2, v3
	v_cvt_pk_bf16_f32 v19, v0, v1
	ds_write2_b64 v188, v[16:17], v[18:19] offset0:68 offset1:102
	v_mov_b32_e32 v16, v36
	v_mov_b32_e32 v17, v4
	v_mov_b32_e32 v18, v20
	v_mov_b32_e32 v19, v52
	v_pk_fma_f32 v[16:17], v[170:171], v[0:1], v[16:17] neg_lo:[1,0,0] neg_hi:[1,0,0]
	v_mov_b32_e32 v4, v37
	v_pk_fma_f32 v[16:17], v[168:169], v[2:3], v[16:17]
	v_pk_fma_f32 v[2:3], v[170:171], v[2:3], v[18:19]
	v_mov_b32_e32 v52, v21
	v_pk_fma_f32 v[0:1], v[168:169], v[0:1], v[2:3]
	v_cvt_pk_bf16_f32 v2, v16, v17
	v_pk_fma_f32 v[4:5], v[170:171], v[0:1], v[4:5] neg_lo:[1,0,0] neg_hi:[1,0,0]
	v_cvt_pk_bf16_f32 v3, v0, v1
	v_pk_fma_f32 v[4:5], v[168:169], v[16:17], v[4:5]
	v_pk_fma_f32 v[16:17], v[170:171], v[16:17], v[52:53]
	s_nop 0
	v_pk_fma_f32 v[0:1], v[168:169], v[0:1], v[16:17]
	v_cvt_pk_bf16_f32 v16, v4, v5
	v_cvt_pk_bf16_f32 v17, v0, v1
	ds_write2_b64 v189, v[2:3], v[16:17] offset0:16 offset1:50
	v_mov_b32_e32 v2, v38
	v_mov_b32_e32 v3, v6
	v_mov_b32_e32 v16, v22
	v_mov_b32_e32 v17, v54
	v_pk_fma_f32 v[2:3], v[170:171], v[0:1], v[2:3] neg_lo:[1,0,0] neg_hi:[1,0,0]
	v_mov_b32_e32 v6, v39
	v_pk_fma_f32 v[2:3], v[168:169], v[4:5], v[2:3]
	v_pk_fma_f32 v[4:5], v[170:171], v[4:5], v[16:17]
	v_mov_b32_e32 v54, v23
	v_pk_fma_f32 v[0:1], v[168:169], v[0:1], v[4:5]
	v_cvt_pk_bf16_f32 v4, v2, v3
	v_pk_fma_f32 v[6:7], v[170:171], v[0:1], v[6:7] neg_lo:[1,0,0] neg_hi:[1,0,0]
	v_cvt_pk_bf16_f32 v5, v0, v1
	v_pk_fma_f32 v[6:7], v[168:169], v[2:3], v[6:7]
	v_pk_fma_f32 v[2:3], v[170:171], v[2:3], v[54:55]
	s_nop 0
	v_pk_fma_f32 v[0:1], v[168:169], v[0:1], v[2:3]
	v_cvt_pk_bf16_f32 v2, v6, v7
	v_cvt_pk_bf16_f32 v3, v0, v1
	ds_write2_b64 v189, v[4:5], v[2:3] offset0:84 offset1:118
	v_mov_b32_e32 v4, v24
	v_mov_b32_e32 v5, v56
	v_mov_b32_e32 v2, v40
	v_mov_b32_e32 v3, v8
	v_pk_fma_f32 v[4:5], v[170:171], v[6:7], v[4:5]
	v_pk_fma_f32 v[2:3], v[170:171], v[0:1], v[2:3] neg_lo:[1,0,0] neg_hi:[1,0,0]
	v_pk_fma_f32 v[0:1], v[168:169], v[0:1], v[4:5]
	v_mov_b32_e32 v8, v41
	v_pk_fma_f32 v[2:3], v[168:169], v[6:7], v[2:3]
	v_mov_b32_e32 v56, v25
	v_pk_fma_f32 v[6:7], v[170:171], v[0:1], v[8:9] neg_lo:[1,0,0] neg_hi:[1,0,0]
	v_cvt_pk_bf16_f32 v4, v2, v3
	v_pk_fma_f32 v[6:7], v[168:169], v[2:3], v[6:7]
	v_pk_fma_f32 v[2:3], v[170:171], v[2:3], v[56:57]
	v_cvt_pk_bf16_f32 v5, v0, v1
	v_pk_fma_f32 v[0:1], v[168:169], v[0:1], v[2:3]
	v_cvt_pk_bf16_f32 v2, v6, v7
	v_cvt_pk_bf16_f32 v3, v0, v1
	ds_write2_b64 v190, v[4:5], v[2:3] offset0:32 offset1:66
	v_mov_b32_e32 v4, v26
	v_mov_b32_e32 v5, v58
	v_mov_b32_e32 v2, v42
	v_mov_b32_e32 v3, v10
	v_pk_fma_f32 v[4:5], v[170:171], v[6:7], v[4:5]
	v_pk_fma_f32 v[2:3], v[170:171], v[0:1], v[2:3] neg_lo:[1,0,0] neg_hi:[1,0,0]
	v_pk_fma_f32 v[0:1], v[168:169], v[0:1], v[4:5]
	v_mov_b32_e32 v10, v43
	v_pk_fma_f32 v[2:3], v[168:169], v[6:7], v[2:3]
	v_mov_b32_e32 v58, v27
	v_pk_fma_f32 v[6:7], v[170:171], v[0:1], v[10:11] neg_lo:[1,0,0] neg_hi:[1,0,0]
	v_cvt_pk_bf16_f32 v4, v2, v3
	v_pk_fma_f32 v[6:7], v[168:169], v[2:3], v[6:7]
	v_pk_fma_f32 v[2:3], v[170:171], v[2:3], v[58:59]
	v_cvt_pk_bf16_f32 v5, v0, v1
	v_pk_fma_f32 v[0:1], v[168:169], v[0:1], v[2:3]
	v_cvt_pk_bf16_f32 v2, v6, v7
	v_cvt_pk_bf16_f32 v3, v0, v1
	ds_write2_b64 v190, v[4:5], v[2:3] offset0:100 offset1:134
	v_mov_b32_e32 v4, v28
	v_mov_b32_e32 v5, v60
	v_mov_b32_e32 v2, v44
	v_mov_b32_e32 v3, v12
	v_pk_fma_f32 v[4:5], v[170:171], v[6:7], v[4:5]
	v_pk_fma_f32 v[2:3], v[170:171], v[0:1], v[2:3] neg_lo:[1,0,0] neg_hi:[1,0,0]
	v_pk_fma_f32 v[0:1], v[168:169], v[0:1], v[4:5]
	v_mov_b32_e32 v12, v45
	v_pk_fma_f32 v[2:3], v[168:169], v[6:7], v[2:3]
	v_mov_b32_e32 v60, v29
	v_pk_fma_f32 v[6:7], v[170:171], v[0:1], v[12:13] neg_lo:[1,0,0] neg_hi:[1,0,0]
	v_cvt_pk_bf16_f32 v4, v2, v3
	v_pk_fma_f32 v[6:7], v[168:169], v[2:3], v[6:7]
	v_pk_fma_f32 v[2:3], v[170:171], v[2:3], v[60:61]
	v_cvt_pk_bf16_f32 v5, v0, v1
	v_pk_fma_f32 v[0:1], v[168:169], v[0:1], v[2:3]
	v_cvt_pk_bf16_f32 v2, v6, v7
	v_cvt_pk_bf16_f32 v3, v0, v1
	ds_write2_b64 v191, v[4:5], v[2:3] offset0:48 offset1:82
	v_mov_b32_e32 v4, v30
	v_mov_b32_e32 v5, v62
	v_mov_b32_e32 v2, v46
	v_mov_b32_e32 v3, v14
	v_pk_fma_f32 v[4:5], v[170:171], v[6:7], v[4:5]
	v_pk_fma_f32 v[2:3], v[170:171], v[0:1], v[2:3] neg_lo:[1,0,0] neg_hi:[1,0,0]
	v_pk_fma_f32 v[0:1], v[168:169], v[0:1], v[4:5]
	v_mov_b32_e32 v14, v47
	v_pk_fma_f32 v[2:3], v[168:169], v[6:7], v[2:3]
	v_mov_b32_e32 v62, v31
	v_pk_fma_f32 v[6:7], v[170:171], v[0:1], v[14:15] neg_lo:[1,0,0] neg_hi:[1,0,0]
	v_cvt_pk_bf16_f32 v4, v2, v3
	v_pk_fma_f32 v[116:117], v[168:169], v[2:3], v[6:7]
	v_pk_fma_f32 v[2:3], v[170:171], v[2:3], v[62:63]
	v_cvt_pk_bf16_f32 v5, v0, v1
	v_pk_fma_f32 v[118:119], v[168:169], v[0:1], v[2:3]
	v_cvt_pk_bf16_f32 v0, v116, v117
	v_cvt_pk_bf16_f32 v1, v118, v119
	ds_write2_b64 v191, v[4:5], v[0:1] offset0:116 offset1:150
	ds_read_b128 v[0:3], v167 offset:40960
	ds_read_b128 v[16:19], v167 offset:40992
	s_waitcnt lgkmcnt(1)
	v_mfma_f32_32x32x16_bf16 v[0:15], v[0:3], v[80:83], 0
	s_waitcnt lgkmcnt(0)
	v_mfma_f32_32x32x16_bf16 v[0:15], v[16:19], v[84:87], v[0:15]
	ds_read_b128 v[16:19], v167 offset:41024
	ds_read_b128 v[20:23], v167 offset:41056
	s_waitcnt lgkmcnt(1)
	v_mfma_f32_32x32x16_bf16 v[0:15], v[16:19], v[88:91], v[0:15]
	s_waitcnt lgkmcnt(0)
	v_mfma_f32_32x32x16_bf16 v[0:15], v[20:23], v[92:95], v[0:15]
	ds_read_b128 v[16:19], v167 offset:41088
	ds_read_b128 v[20:23], v167 offset:41120
	s_waitcnt lgkmcnt(1)
	v_mfma_f32_32x32x16_bf16 v[0:15], v[16:19], v[96:99], v[0:15]
	s_waitcnt lgkmcnt(0)
	v_mfma_f32_32x32x16_bf16 v[0:15], v[20:23], v[100:103], v[0:15]
	ds_read_b128 v[16:19], v167 offset:41152
	ds_read_b128 v[20:23], v167 offset:41184
	s_waitcnt lgkmcnt(1)
	v_mfma_f32_32x32x16_bf16 v[0:15], v[16:19], v[104:107], v[0:15]
	s_waitcnt lgkmcnt(0)
	v_mfma_f32_32x32x16_bf16 v[0:15], v[20:23], v[108:111], v[0:15]
	s_and_saveexec_b64 s[26:27], s[0:1]
	s_cbranch_execz .LBB0_873
	s_or_b32 s22, s25, 0x60
	s_xor_b32 s56, s25, 0x9f
	s_lshl_b32 s22, s22, 4
	s_lshl_b32 s56, s56, 4
	s_and_b64 s[50:51], s[4:5], exec
	s_cselect_b32 s22, s22, s56
	v_lshl_add_u64 v[16:17], s[22:23], 2, v[174:175]
	s_cbranch_scc0 .Lys14_b
	s_nop 3
	global_store_dword v[16:17], v0, off
	global_store_dword v[16:17], v1, off offset:64
	global_store_dword v[16:17], v2, off offset:128
	global_store_dword v[16:17], v3, off offset:192
	global_store_dword v[16:17], v4, off offset:256
	global_store_dword v[16:17], v5, off offset:320
	global_store_dword v[16:17], v6, off offset:384
	global_store_dword v[16:17], v7, off offset:448
	global_store_dword v[16:17], v8, off offset:512
	global_store_dword v[16:17], v9, off offset:576
	global_store_dword v[16:17], v10, off offset:640
	global_store_dword v[16:17], v11, off offset:704
	global_store_dword v[16:17], v12, off offset:768
	global_store_dword v[16:17], v13, off offset:832
	global_store_dword v[16:17], v14, off offset:896
	global_store_dword v[16:17], v15, off offset:960
	s_branch .Lys14_e

.Lys14_e:
.LBB0_873:
	s_or_b64 exec, exec, s[26:27]
	s_waitcnt vmcnt(0)
	v_mfma_f32_32x32x16_bf16 v[32:47], v[112:115], v[64:67], 0
	v_mfma_f32_32x32x16_bf16 v[0:15], v[112:115], v[72:75], 0
	s_nop 10
	v_mov_b32_e32 v120, v32
	v_mfma_f32_32x32x16_bf16 v[16:31], v[112:115], v[68:71], 0
	v_mov_b32_e32 v121, v0
	v_mov_b32_e32 v0, v33
	v_mfma_f32_32x32x16_bf16 v[48:63], v[112:115], v[76:79], 0
	s_nop 8
	v_mov_b32_e32 v122, v16
	v_fma_f32 v112, -v170, v118, v120
	v_fma_f32 v113, -v171, v119, v121
	v_fma_f32 v112, v168, v116, v112
	v_fma_f32 v113, v169, v117, v113
	v_mov_b32_e32 v123, v48
	v_pk_fma_f32 v[114:115], v[170:171], v[116:117], v[122:123]
	v_mov_b32_e32 v48, v17
	v_pk_fma_f32 v[114:115], v[168:169], v[118:119], v[114:115]
	v_pk_fma_f32 v[16:17], v[170:171], v[112:113], v[48:49]
	v_pk_fma_f32 v[0:1], v[170:171], v[114:115], v[0:1] neg_lo:[1,0,0] neg_hi:[1,0,0]
	v_pk_fma_f32 v[16:17], v[168:169], v[114:115], v[16:17]
	v_pk_fma_f32 v[0:1], v[168:169], v[112:113], v[0:1]
	v_cvt_pk_bf16_f32 v116, v112, v113
	v_cvt_pk_bf16_f32 v117, v114, v115
	v_cvt_pk_bf16_f32 v32, v0, v1
	v_cvt_pk_bf16_f32 v33, v16, v17
	ds_write2_b64 v188, v[116:117], v[32:33] offset1:34
	v_mov_b32_e32 v32, v34
	v_mov_b32_e32 v33, v2
	v_mov_b32_e32 v48, v18
	v_mov_b32_e32 v49, v50
	v_pk_fma_f32 v[32:33], v[170:171], v[16:17], v[32:33] neg_lo:[1,0,0] neg_hi:[1,0,0]
	v_mov_b32_e32 v2, v35
	v_pk_fma_f32 v[32:33], v[168:169], v[0:1], v[32:33]
	v_pk_fma_f32 v[0:1], v[170:171], v[0:1], v[48:49]
	v_mov_b32_e32 v50, v19
	v_pk_fma_f32 v[0:1], v[168:169], v[16:17], v[0:1]
	v_pk_fma_f32 v[18:19], v[170:171], v[32:33], v[50:51]
	v_pk_fma_f32 v[2:3], v[170:171], v[0:1], v[2:3] neg_lo:[1,0,0] neg_hi:[1,0,0]
	v_cvt_pk_bf16_f32 v17, v0, v1
	v_pk_fma_f32 v[2:3], v[168:169], v[32:33], v[2:3]
	v_pk_fma_f32 v[0:1], v[168:169], v[0:1], v[18:19]
	v_cvt_pk_bf16_f32 v16, v32, v33
	v_cvt_pk_bf16_f32 v18, v2, v3
	v_cvt_pk_bf16_f32 v19, v0, v1
	ds_write2_b64 v188, v[16:17], v[18:19] offset0:68 offset1:102
	v_mov_b32_e32 v16, v36
	v_mov_b32_e32 v17, v4
	v_mov_b32_e32 v18, v20
	v_mov_b32_e32 v19, v52
	v_pk_fma_f32 v[16:17], v[170:171], v[0:1], v[16:17] neg_lo:[1,0,0] neg_hi:[1,0,0]
	v_mov_b32_e32 v4, v37
	v_pk_fma_f32 v[16:17], v[168:169], v[2:3], v[16:17]
	v_pk_fma_f32 v[2:3], v[170:171], v[2:3], v[18:19]
	v_mov_b32_e32 v52, v21
	v_pk_fma_f32 v[0:1], v[168:169], v[0:1], v[2:3]
	v_cvt_pk_bf16_f32 v2, v16, v17
	v_pk_fma_f32 v[4:5], v[170:171], v[0:1], v[4:5] neg_lo:[1,0,0] neg_hi:[1,0,0]
	v_cvt_pk_bf16_f32 v3, v0, v1
	v_pk_fma_f32 v[4:5], v[168:169], v[16:17], v[4:5]
	v_pk_fma_f32 v[16:17], v[170:171], v[16:17], v[52:53]
	s_nop 0
	v_pk_fma_f32 v[0:1], v[168:169], v[0:1], v[16:17]
	v_cvt_pk_bf16_f32 v16, v4, v5
	v_cvt_pk_bf16_f32 v17, v0, v1
	ds_write2_b64 v189, v[2:3], v[16:17] offset0:16 offset1:50
	v_mov_b32_e32 v2, v38
	v_mov_b32_e32 v3, v6
	v_mov_b32_e32 v16, v22
	v_mov_b32_e32 v17, v54
	v_pk_fma_f32 v[2:3], v[170:171], v[0:1], v[2:3] neg_lo:[1,0,0] neg_hi:[1,0,0]
	v_mov_b32_e32 v6, v39
	v_pk_fma_f32 v[2:3], v[168:169], v[4:5], v[2:3]
	v_pk_fma_f32 v[4:5], v[170:171], v[4:5], v[16:17]
	v_mov_b32_e32 v54, v23
	v_pk_fma_f32 v[0:1], v[168:169], v[0:1], v[4:5]
	v_cvt_pk_bf16_f32 v4, v2, v3
	v_pk_fma_f32 v[6:7], v[170:171], v[0:1], v[6:7] neg_lo:[1,0,0] neg_hi:[1,0,0]
	v_cvt_pk_bf16_f32 v5, v0, v1
	v_pk_fma_f32 v[6:7], v[168:169], v[2:3], v[6:7]
	v_pk_fma_f32 v[2:3], v[170:171], v[2:3], v[54:55]
	s_nop 0
	v_pk_fma_f32 v[0:1], v[168:169], v[0:1], v[2:3]
	v_cvt_pk_bf16_f32 v2, v6, v7
	v_cvt_pk_bf16_f32 v3, v0, v1
	ds_write2_b64 v189, v[4:5], v[2:3] offset0:84 offset1:118
	v_mov_b32_e32 v4, v24
	v_mov_b32_e32 v5, v56
	v_mov_b32_e32 v2, v40
	v_mov_b32_e32 v3, v8
	v_pk_fma_f32 v[4:5], v[170:171], v[6:7], v[4:5]
	v_pk_fma_f32 v[2:3], v[170:171], v[0:1], v[2:3] neg_lo:[1,0,0] neg_hi:[1,0,0]
	v_pk_fma_f32 v[0:1], v[168:169], v[0:1], v[4:5]
	v_mov_b32_e32 v8, v41
	v_pk_fma_f32 v[2:3], v[168:169], v[6:7], v[2:3]
	v_mov_b32_e32 v56, v25
	v_pk_fma_f32 v[6:7], v[170:171], v[0:1], v[8:9] neg_lo:[1,0,0] neg_hi:[1,0,0]
	v_cvt_pk_bf16_f32 v4, v2, v3
	v_pk_fma_f32 v[6:7], v[168:169], v[2:3], v[6:7]
	v_pk_fma_f32 v[2:3], v[170:171], v[2:3], v[56:57]
	v_cvt_pk_bf16_f32 v5, v0, v1
	v_pk_fma_f32 v[0:1], v[168:169], v[0:1], v[2:3]
	v_cvt_pk_bf16_f32 v2, v6, v7
	v_cvt_pk_bf16_f32 v3, v0, v1
	ds_write2_b64 v190, v[4:5], v[2:3] offset0:32 offset1:66
	v_mov_b32_e32 v4, v26
	v_mov_b32_e32 v5, v58
	v_mov_b32_e32 v2, v42
	v_mov_b32_e32 v3, v10
	v_pk_fma_f32 v[4:5], v[170:171], v[6:7], v[4:5]
	v_pk_fma_f32 v[2:3], v[170:171], v[0:1], v[2:3] neg_lo:[1,0,0] neg_hi:[1,0,0]
	v_pk_fma_f32 v[0:1], v[168:169], v[0:1], v[4:5]
	v_mov_b32_e32 v10, v43
	v_pk_fma_f32 v[2:3], v[168:169], v[6:7], v[2:3]
	v_mov_b32_e32 v58, v27
	v_pk_fma_f32 v[6:7], v[170:171], v[0:1], v[10:11] neg_lo:[1,0,0] neg_hi:[1,0,0]
	v_cvt_pk_bf16_f32 v4, v2, v3
	v_pk_fma_f32 v[6:7], v[168:169], v[2:3], v[6:7]
	v_pk_fma_f32 v[2:3], v[170:171], v[2:3], v[58:59]
	v_cvt_pk_bf16_f32 v5, v0, v1
	v_pk_fma_f32 v[0:1], v[168:169], v[0:1], v[2:3]
	v_cvt_pk_bf16_f32 v2, v6, v7
	v_cvt_pk_bf16_f32 v3, v0, v1
	ds_write2_b64 v190, v[4:5], v[2:3] offset0:100 offset1:134
	v_mov_b32_e32 v4, v28
	v_mov_b32_e32 v5, v60
	v_mov_b32_e32 v2, v44
	v_mov_b32_e32 v3, v12
	v_pk_fma_f32 v[4:5], v[170:171], v[6:7], v[4:5]
	v_pk_fma_f32 v[2:3], v[170:171], v[0:1], v[2:3] neg_lo:[1,0,0] neg_hi:[1,0,0]
	v_pk_fma_f32 v[0:1], v[168:169], v[0:1], v[4:5]
	v_mov_b32_e32 v12, v45
	v_pk_fma_f32 v[2:3], v[168:169], v[6:7], v[2:3]
	v_mov_b32_e32 v60, v29
	v_pk_fma_f32 v[6:7], v[170:171], v[0:1], v[12:13] neg_lo:[1,0,0] neg_hi:[1,0,0]
	v_cvt_pk_bf16_f32 v4, v2, v3
	v_pk_fma_f32 v[6:7], v[168:169], v[2:3], v[6:7]
	v_pk_fma_f32 v[2:3], v[170:171], v[2:3], v[60:61]
	v_cvt_pk_bf16_f32 v5, v0, v1
	v_pk_fma_f32 v[0:1], v[168:169], v[0:1], v[2:3]
	v_cvt_pk_bf16_f32 v2, v6, v7
	v_cvt_pk_bf16_f32 v3, v0, v1
	ds_write2_b64 v191, v[4:5], v[2:3] offset0:48 offset1:82
	v_mov_b32_e32 v4, v30
	v_mov_b32_e32 v5, v62
	v_mov_b32_e32 v2, v46
	v_mov_b32_e32 v3, v14
	v_pk_fma_f32 v[4:5], v[170:171], v[6:7], v[4:5]
	v_pk_fma_f32 v[2:3], v[170:171], v[0:1], v[2:3] neg_lo:[1,0,0] neg_hi:[1,0,0]
	v_pk_fma_f32 v[0:1], v[168:169], v[0:1], v[4:5]
	v_mov_b32_e32 v14, v47
	v_pk_fma_f32 v[2:3], v[168:169], v[6:7], v[2:3]
	v_mov_b32_e32 v62, v31
	v_pk_fma_f32 v[6:7], v[170:171], v[0:1], v[14:15] neg_lo:[1,0,0] neg_hi:[1,0,0]
	v_cvt_pk_bf16_f32 v4, v2, v3
	v_pk_fma_f32 v[114:115], v[168:169], v[2:3], v[6:7]
	v_pk_fma_f32 v[2:3], v[170:171], v[2:3], v[62:63]
	v_cvt_pk_bf16_f32 v5, v0, v1
	v_pk_fma_f32 v[112:113], v[168:169], v[0:1], v[2:3]
	v_cvt_pk_bf16_f32 v0, v114, v115
	v_cvt_pk_bf16_f32 v1, v112, v113
	ds_write2_b64 v191, v[4:5], v[0:1] offset0:116 offset1:150
	ds_read_b128 v[0:3], v167 offset:40960
	ds_read_b128 v[16:19], v167 offset:40992
	s_waitcnt lgkmcnt(1)
	v_mfma_f32_32x32x16_bf16 v[0:15], v[0:3], v[80:83], 0
	s_waitcnt lgkmcnt(0)
	v_mfma_f32_32x32x16_bf16 v[0:15], v[16:19], v[84:87], v[0:15]
	ds_read_b128 v[16:19], v167 offset:41024
	ds_read_b128 v[20:23], v167 offset:41056
	s_waitcnt lgkmcnt(1)
	v_mfma_f32_32x32x16_bf16 v[0:15], v[16:19], v[88:91], v[0:15]
	s_waitcnt lgkmcnt(0)
	v_mfma_f32_32x32x16_bf16 v[0:15], v[20:23], v[92:95], v[0:15]
	ds_read_b128 v[16:19], v167 offset:41088
	ds_read_b128 v[20:23], v167 offset:41120
	s_waitcnt lgkmcnt(1)
	v_mfma_f32_32x32x16_bf16 v[0:15], v[16:19], v[96:99], v[0:15]
	s_waitcnt lgkmcnt(0)
	v_mfma_f32_32x32x16_bf16 v[0:15], v[20:23], v[100:103], v[0:15]
	ds_read_b128 v[16:19], v167 offset:41152
	ds_read_b128 v[20:23], v167 offset:41184
	s_waitcnt lgkmcnt(1)
	v_mfma_f32_32x32x16_bf16 v[0:15], v[16:19], v[104:107], v[0:15]
	s_waitcnt lgkmcnt(0)
	v_mfma_f32_32x32x16_bf16 v[0:15], v[20:23], v[108:111], v[0:15]
	s_and_saveexec_b64 s[26:27], s[0:1]
	s_cbranch_execz .LBB0_858
	s_or_b32 s22, s25, 0x70
	s_xor_b32 s56, s25, 0x8f
	s_lshl_b32 s22, s22, 4
	s_lshl_b32 s56, s56, 4
	s_and_b64 s[50:51], s[4:5], exec
	s_cselect_b32 s22, s22, s56
	v_lshl_add_u64 v[16:17], s[22:23], 2, v[174:175]
	s_cbranch_scc0 .Lys15_b
	s_nop 3
	global_store_dword v[16:17], v0, off
	global_store_dword v[16:17], v1, off offset:64
	global_store_dword v[16:17], v2, off offset:128
	global_store_dword v[16:17], v3, off offset:192
	global_store_dword v[16:17], v4, off offset:256
	global_store_dword v[16:17], v5, off offset:320
	global_store_dword v[16:17], v6, off offset:384
	global_store_dword v[16:17], v7, off offset:448
	global_store_dword v[16:17], v8, off offset:512
	global_store_dword v[16:17], v9, off offset:576
	global_store_dword v[16:17], v10, off offset:640
	global_store_dword v[16:17], v11, off offset:704
	global_store_dword v[16:17], v12, off offset:768
	global_store_dword v[16:17], v13, off offset:832
	global_store_dword v[16:17], v14, off offset:896
	global_store_dword v[16:17], v15, off offset:960
	s_branch .LBB0_858
